# q GEMM: transposed accumulators + packed 8-byte stores + batched rope loads; q/kv row-norm pre-pass with transposed permlane/DPP reduction
# speedup vs baseline: 1.0162x; 1.0162x over previous
.LBB0_804:
	s_cmpk_gt_i32 s20, 0x21f
	s_mov_b64 s[0:1], -1
	s_cbranch_scc0 .LBB0_906
	s_add_i32 s16, s20, 0xfde0
	s_and_b32 s8, s16, 0xffff
	s_mul_i32 s0, s8, 0xaaab
	v_mov_b32_e32 v128, v167
	s_lshr_b32 s9, s0, 18
	s_lshl_b32 s21, s9, 8
	v_ashrrev_i32_e32 v129, 1, v128
	v_and_b32_e32 v1, 0xffffffe0, v129
	v_add_u32_e32 v62, s21, v1
	v_and_b32_e32 v1, 64, v192
	v_add_u32_e32 v1, 64, v1
	v_xor_b32_e32 v2, 32, v192
	v_cmp_lt_i32_e32 vcc, v2, v1
	v_and_b32_e32 v0, 63, v128
	v_lshlrev_b32_e32 v164, 4, v0
	v_cndmask_b32_e32 v2, v192, v2, vcc
	v_lshlrev_b32_e32 v63, 2, v2
	v_xor_b32_e32 v2, 16, v192
	v_cmp_lt_i32_e32 vcc, v2, v1
	v_readlane_b32 s1, v254, 47
	v_lshl_add_u64 v[60:61], s[22:23], 0, v[164:165]
	v_cndmask_b32_e32 v2, v192, v2, vcc
	v_lshlrev_b32_e32 v64, 2, v2
	v_xor_b32_e32 v2, 8, v192
	v_cmp_lt_i32_e32 vcc, v2, v1
	s_mov_b32 s0, 0
	v_cmp_eq_u32_e64 s[10:11], 0, v0
	v_cndmask_b32_e32 v2, v192, v2, vcc
	v_lshlrev_b32_e32 v65, 2, v2
	v_xor_b32_e32 v2, 4, v192
	v_cmp_lt_i32_e32 vcc, v2, v1
	v_lshl_add_u32 v69, v129, 2, s1
	s_mov_b64 s[2:3], -1
	v_cndmask_b32_e32 v2, v192, v2, vcc
	v_lshlrev_b32_e32 v66, 2, v2
	v_xor_b32_e32 v2, 2, v192
	v_cmp_lt_i32_e32 vcc, v2, v1
	s_nop 1
	v_cndmask_b32_e32 v2, v192, v2, vcc
	v_lshlrev_b32_e32 v67, 2, v2
	v_xor_b32_e32 v2, 1, v192
	v_cmp_lt_i32_e32 vcc, v2, v1
	s_nop 1
	v_cndmask_b32_e32 v1, v192, v2, vcc
	v_lshlrev_b32_e32 v68, 2, v1
	v_readfirstlane_b32 s0, v167
	v_and_b32_e32 v116, 63, v167
	v_and_b32_e32 v118, 15, v167
	s_lshr_b32 s0, s0, 6
	s_lshl_b32 s1, s0, 5
	s_add_u32 s2, s21, s1
	s_mul_i32 s2, s2, 0x1700
	s_add_u32 s24, s22, s2
	s_addc_u32 s25, s23, 0
	v_lshlrev_b32_e32 v116, 4, v116
	v_and_b32_e32 v117, 48, v167
	s_lshl_b32 s1, s0, 7
	v_add_u32_e32 v117, s1, v117
	v_add_u32_e32 v117, 0x20000, v117
	global_load_dwordx4 v[16:19], v116, s[24:25]
	s_add_u32 s24, s24, 0x1700
	s_addc_u32 s25, s25, 0
	global_load_dwordx4 v[20:23], v116, s[24:25]
	s_add_u32 s24, s24, 0x1700
	s_addc_u32 s25, s25, 0
	global_load_dwordx4 v[24:27], v116, s[24:25]
	s_add_u32 s24, s24, 0x1700
	s_addc_u32 s25, s25, 0
	global_load_dwordx4 v[28:31], v116, s[24:25]
	s_add_u32 s24, s24, 0x1700
	s_addc_u32 s25, s25, 0
	global_load_dwordx4 v[32:35], v116, s[24:25]
	s_add_u32 s24, s24, 0x1700
	s_addc_u32 s25, s25, 0
	global_load_dwordx4 v[36:39], v116, s[24:25]
	s_add_u32 s24, s24, 0x1700
	s_addc_u32 s25, s25, 0
	global_load_dwordx4 v[40:43], v116, s[24:25]
	s_add_u32 s24, s24, 0x1700
	s_addc_u32 s25, s25, 0
	global_load_dwordx4 v[44:47], v116, s[24:25]
	s_add_u32 s24, s24, 0x1700
	s_addc_u32 s25, s25, 0
	global_load_dwordx4 v[48:51], v116, s[24:25]
	s_add_u32 s24, s24, 0x1700
	s_addc_u32 s25, s25, 0
	global_load_dwordx4 v[52:55], v116, s[24:25]
	s_add_u32 s24, s24, 0x1700
	s_addc_u32 s25, s25, 0
	global_load_dwordx4 v[56:59], v116, s[24:25]
	s_add_u32 s24, s24, 0x1700
	s_addc_u32 s25, s25, 0
	global_load_dwordx4 v[60:63], v116, s[24:25]
	s_add_u32 s24, s24, 0x1700
	s_addc_u32 s25, s25, 0
	global_load_dwordx4 v[64:67], v116, s[24:25]
	s_add_u32 s24, s24, 0x1700
	s_addc_u32 s25, s25, 0
	global_load_dwordx4 v[68:71], v116, s[24:25]
	s_add_u32 s24, s24, 0x1700
	s_addc_u32 s25, s25, 0
	global_load_dwordx4 v[72:75], v116, s[24:25]
	s_add_u32 s24, s24, 0x1700
	s_addc_u32 s25, s25, 0
	global_load_dwordx4 v[76:79], v116, s[24:25]
	s_add_u32 s24, s24, 0x1700
	s_addc_u32 s25, s25, 0
	s_waitcnt vmcnt(15)
	v_lshlrev_b32_e32 v112, 16, v16
	v_and_b32_e32 v16, 0xffff0000, v16
	v_mul_f32_e32 v16, v16, v16
	v_fmac_f32_e32 v16, v112, v112
	v_lshlrev_b32_e32 v112, 16, v17
	v_and_b32_e32 v17, 0xffff0000, v17
	v_mul_f32_e32 v17, v17, v17
	v_fmac_f32_e32 v17, v112, v112
	v_add_f32_e32 v16, v16, v17
	v_lshlrev_b32_e32 v112, 16, v18
	v_and_b32_e32 v18, 0xffff0000, v18
	v_mul_f32_e32 v18, v18, v18
	v_fmac_f32_e32 v18, v112, v112
	v_add_f32_e32 v16, v16, v18
	v_lshlrev_b32_e32 v112, 16, v19
	v_and_b32_e32 v19, 0xffff0000, v19
	v_mul_f32_e32 v19, v19, v19
	v_fmac_f32_e32 v19, v112, v112
	v_add_f32_e32 v16, v16, v19
	s_waitcnt vmcnt(14)
	v_lshlrev_b32_e32 v112, 16, v20
	v_and_b32_e32 v20, 0xffff0000, v20
	v_mul_f32_e32 v20, v20, v20
	v_fmac_f32_e32 v20, v112, v112
	v_lshlrev_b32_e32 v112, 16, v21
	v_and_b32_e32 v21, 0xffff0000, v21
	v_mul_f32_e32 v21, v21, v21
	v_fmac_f32_e32 v21, v112, v112
	v_add_f32_e32 v20, v20, v21
	v_lshlrev_b32_e32 v112, 16, v22
	v_and_b32_e32 v22, 0xffff0000, v22
	v_mul_f32_e32 v22, v22, v22
	v_fmac_f32_e32 v22, v112, v112
	v_add_f32_e32 v20, v20, v22
	v_lshlrev_b32_e32 v112, 16, v23
	v_and_b32_e32 v23, 0xffff0000, v23
	v_mul_f32_e32 v23, v23, v23
	v_fmac_f32_e32 v23, v112, v112
	v_add_f32_e32 v20, v20, v23
	s_waitcnt vmcnt(13)
	v_lshlrev_b32_e32 v112, 16, v24
	v_and_b32_e32 v24, 0xffff0000, v24
	v_mul_f32_e32 v24, v24, v24
	v_fmac_f32_e32 v24, v112, v112
	v_lshlrev_b32_e32 v112, 16, v25
	v_and_b32_e32 v25, 0xffff0000, v25
	v_mul_f32_e32 v25, v25, v25
	v_fmac_f32_e32 v25, v112, v112
	v_add_f32_e32 v24, v24, v25
	v_lshlrev_b32_e32 v112, 16, v26
	v_and_b32_e32 v26, 0xffff0000, v26
	v_mul_f32_e32 v26, v26, v26
	v_fmac_f32_e32 v26, v112, v112
	v_add_f32_e32 v24, v24, v26
	v_lshlrev_b32_e32 v112, 16, v27
	v_and_b32_e32 v27, 0xffff0000, v27
	v_mul_f32_e32 v27, v27, v27
	v_fmac_f32_e32 v27, v112, v112
	v_add_f32_e32 v24, v24, v27
	s_waitcnt vmcnt(12)
	v_lshlrev_b32_e32 v112, 16, v28
	v_and_b32_e32 v28, 0xffff0000, v28
	v_mul_f32_e32 v28, v28, v28
	v_fmac_f32_e32 v28, v112, v112
	v_lshlrev_b32_e32 v112, 16, v29
	v_and_b32_e32 v29, 0xffff0000, v29
	v_mul_f32_e32 v29, v29, v29
	v_fmac_f32_e32 v29, v112, v112
	v_add_f32_e32 v28, v28, v29
	v_lshlrev_b32_e32 v112, 16, v30
	v_and_b32_e32 v30, 0xffff0000, v30
	v_mul_f32_e32 v30, v30, v30
	v_fmac_f32_e32 v30, v112, v112
	v_add_f32_e32 v28, v28, v30
	v_lshlrev_b32_e32 v112, 16, v31
	v_and_b32_e32 v31, 0xffff0000, v31
	v_mul_f32_e32 v31, v31, v31
	v_fmac_f32_e32 v31, v112, v112
	v_add_f32_e32 v28, v28, v31
	s_waitcnt vmcnt(11)
	v_lshlrev_b32_e32 v112, 16, v32
	v_and_b32_e32 v32, 0xffff0000, v32
	v_mul_f32_e32 v32, v32, v32
	v_fmac_f32_e32 v32, v112, v112
	v_lshlrev_b32_e32 v112, 16, v33
	v_and_b32_e32 v33, 0xffff0000, v33
	v_mul_f32_e32 v33, v33, v33
	v_fmac_f32_e32 v33, v112, v112
	v_add_f32_e32 v32, v32, v33
	v_lshlrev_b32_e32 v112, 16, v34
	v_and_b32_e32 v34, 0xffff0000, v34
	v_mul_f32_e32 v34, v34, v34
	v_fmac_f32_e32 v34, v112, v112
	v_add_f32_e32 v32, v32, v34
	v_lshlrev_b32_e32 v112, 16, v35
	v_and_b32_e32 v35, 0xffff0000, v35
	v_mul_f32_e32 v35, v35, v35
	v_fmac_f32_e32 v35, v112, v112
	v_add_f32_e32 v32, v32, v35
	s_waitcnt vmcnt(10)
	v_lshlrev_b32_e32 v112, 16, v36
	v_and_b32_e32 v36, 0xffff0000, v36
	v_mul_f32_e32 v36, v36, v36
	v_fmac_f32_e32 v36, v112, v112
	v_lshlrev_b32_e32 v112, 16, v37
	v_and_b32_e32 v37, 0xffff0000, v37
	v_mul_f32_e32 v37, v37, v37
	v_fmac_f32_e32 v37, v112, v112
	v_add_f32_e32 v36, v36, v37
	v_lshlrev_b32_e32 v112, 16, v38
	v_and_b32_e32 v38, 0xffff0000, v38
	v_mul_f32_e32 v38, v38, v38
	v_fmac_f32_e32 v38, v112, v112
	v_add_f32_e32 v36, v36, v38
	v_lshlrev_b32_e32 v112, 16, v39
	v_and_b32_e32 v39, 0xffff0000, v39
	v_mul_f32_e32 v39, v39, v39
	v_fmac_f32_e32 v39, v112, v112
	v_add_f32_e32 v36, v36, v39
	s_waitcnt vmcnt(9)
	v_lshlrev_b32_e32 v112, 16, v40
	v_and_b32_e32 v40, 0xffff0000, v40
	v_mul_f32_e32 v40, v40, v40
	v_fmac_f32_e32 v40, v112, v112
	v_lshlrev_b32_e32 v112, 16, v41
	v_and_b32_e32 v41, 0xffff0000, v41
	v_mul_f32_e32 v41, v41, v41
	v_fmac_f32_e32 v41, v112, v112
	v_add_f32_e32 v40, v40, v41
	v_lshlrev_b32_e32 v112, 16, v42
	v_and_b32_e32 v42, 0xffff0000, v42
	v_mul_f32_e32 v42, v42, v42
	v_fmac_f32_e32 v42, v112, v112
	v_add_f32_e32 v40, v40, v42
	v_lshlrev_b32_e32 v112, 16, v43
	v_and_b32_e32 v43, 0xffff0000, v43
	v_mul_f32_e32 v43, v43, v43
	v_fmac_f32_e32 v43, v112, v112
	v_add_f32_e32 v40, v40, v43
	s_waitcnt vmcnt(8)
	v_lshlrev_b32_e32 v112, 16, v44
	v_and_b32_e32 v44, 0xffff0000, v44
	v_mul_f32_e32 v44, v44, v44
	v_fmac_f32_e32 v44, v112, v112
	v_lshlrev_b32_e32 v112, 16, v45
	v_and_b32_e32 v45, 0xffff0000, v45
	v_mul_f32_e32 v45, v45, v45
	v_fmac_f32_e32 v45, v112, v112
	v_add_f32_e32 v44, v44, v45
	v_lshlrev_b32_e32 v112, 16, v46
	v_and_b32_e32 v46, 0xffff0000, v46
	v_mul_f32_e32 v46, v46, v46
	v_fmac_f32_e32 v46, v112, v112
	v_add_f32_e32 v44, v44, v46
	v_lshlrev_b32_e32 v112, 16, v47
	v_and_b32_e32 v47, 0xffff0000, v47
	v_mul_f32_e32 v47, v47, v47
	v_fmac_f32_e32 v47, v112, v112
	v_add_f32_e32 v44, v44, v47
	s_waitcnt vmcnt(7)
	v_lshlrev_b32_e32 v112, 16, v48
	v_and_b32_e32 v48, 0xffff0000, v48
	v_mul_f32_e32 v48, v48, v48
	v_fmac_f32_e32 v48, v112, v112
	v_lshlrev_b32_e32 v112, 16, v49
	v_and_b32_e32 v49, 0xffff0000, v49
	v_mul_f32_e32 v49, v49, v49
	v_fmac_f32_e32 v49, v112, v112
	v_add_f32_e32 v48, v48, v49
	v_lshlrev_b32_e32 v112, 16, v50
	v_and_b32_e32 v50, 0xffff0000, v50
	v_mul_f32_e32 v50, v50, v50
	v_fmac_f32_e32 v50, v112, v112
	v_add_f32_e32 v48, v48, v50
	v_lshlrev_b32_e32 v112, 16, v51
	v_and_b32_e32 v51, 0xffff0000, v51
	v_mul_f32_e32 v51, v51, v51
	v_fmac_f32_e32 v51, v112, v112
	v_add_f32_e32 v48, v48, v51
	s_waitcnt vmcnt(6)
	v_lshlrev_b32_e32 v112, 16, v52
	v_and_b32_e32 v52, 0xffff0000, v52
	v_mul_f32_e32 v52, v52, v52
	v_fmac_f32_e32 v52, v112, v112
	v_lshlrev_b32_e32 v112, 16, v53
	v_and_b32_e32 v53, 0xffff0000, v53
	v_mul_f32_e32 v53, v53, v53
	v_fmac_f32_e32 v53, v112, v112
	v_add_f32_e32 v52, v52, v53
	v_lshlrev_b32_e32 v112, 16, v54
	v_and_b32_e32 v54, 0xffff0000, v54
	v_mul_f32_e32 v54, v54, v54
	v_fmac_f32_e32 v54, v112, v112
	v_add_f32_e32 v52, v52, v54
	v_lshlrev_b32_e32 v112, 16, v55
	v_and_b32_e32 v55, 0xffff0000, v55
	v_mul_f32_e32 v55, v55, v55
	v_fmac_f32_e32 v55, v112, v112
	v_add_f32_e32 v52, v52, v55
	s_waitcnt vmcnt(5)
	v_lshlrev_b32_e32 v112, 16, v56
	v_and_b32_e32 v56, 0xffff0000, v56
	v_mul_f32_e32 v56, v56, v56
	v_fmac_f32_e32 v56, v112, v112
	v_lshlrev_b32_e32 v112, 16, v57
	v_and_b32_e32 v57, 0xffff0000, v57
	v_mul_f32_e32 v57, v57, v57
	v_fmac_f32_e32 v57, v112, v112
	v_add_f32_e32 v56, v56, v57
	v_lshlrev_b32_e32 v112, 16, v58
	v_and_b32_e32 v58, 0xffff0000, v58
	v_mul_f32_e32 v58, v58, v58
	v_fmac_f32_e32 v58, v112, v112
	v_add_f32_e32 v56, v56, v58
	v_lshlrev_b32_e32 v112, 16, v59
	v_and_b32_e32 v59, 0xffff0000, v59
	v_mul_f32_e32 v59, v59, v59
	v_fmac_f32_e32 v59, v112, v112
	v_add_f32_e32 v56, v56, v59
	s_waitcnt vmcnt(4)
	v_lshlrev_b32_e32 v112, 16, v60
	v_and_b32_e32 v60, 0xffff0000, v60
	v_mul_f32_e32 v60, v60, v60
	v_fmac_f32_e32 v60, v112, v112
	v_lshlrev_b32_e32 v112, 16, v61
	v_and_b32_e32 v61, 0xffff0000, v61
	v_mul_f32_e32 v61, v61, v61
	v_fmac_f32_e32 v61, v112, v112
	v_add_f32_e32 v60, v60, v61
	v_lshlrev_b32_e32 v112, 16, v62
	v_and_b32_e32 v62, 0xffff0000, v62
	v_mul_f32_e32 v62, v62, v62
	v_fmac_f32_e32 v62, v112, v112
	v_add_f32_e32 v60, v60, v62
	v_lshlrev_b32_e32 v112, 16, v63
	v_and_b32_e32 v63, 0xffff0000, v63
	v_mul_f32_e32 v63, v63, v63
	v_fmac_f32_e32 v63, v112, v112
	v_add_f32_e32 v60, v60, v63
	s_waitcnt vmcnt(3)
	v_lshlrev_b32_e32 v112, 16, v64
	v_and_b32_e32 v64, 0xffff0000, v64
	v_mul_f32_e32 v64, v64, v64
	v_fmac_f32_e32 v64, v112, v112
	v_lshlrev_b32_e32 v112, 16, v65
	v_and_b32_e32 v65, 0xffff0000, v65
	v_mul_f32_e32 v65, v65, v65
	v_fmac_f32_e32 v65, v112, v112
	v_add_f32_e32 v64, v64, v65
	v_lshlrev_b32_e32 v112, 16, v66
	v_and_b32_e32 v66, 0xffff0000, v66
	v_mul_f32_e32 v66, v66, v66
	v_fmac_f32_e32 v66, v112, v112
	v_add_f32_e32 v64, v64, v66
	v_lshlrev_b32_e32 v112, 16, v67
	v_and_b32_e32 v67, 0xffff0000, v67
	v_mul_f32_e32 v67, v67, v67
	v_fmac_f32_e32 v67, v112, v112
	v_add_f32_e32 v64, v64, v67
	s_waitcnt vmcnt(2)
	v_lshlrev_b32_e32 v112, 16, v68
	v_and_b32_e32 v68, 0xffff0000, v68
	v_mul_f32_e32 v68, v68, v68
	v_fmac_f32_e32 v68, v112, v112
	v_lshlrev_b32_e32 v112, 16, v69
	v_and_b32_e32 v69, 0xffff0000, v69
	v_mul_f32_e32 v69, v69, v69
	v_fmac_f32_e32 v69, v112, v112
	v_add_f32_e32 v68, v68, v69
	v_lshlrev_b32_e32 v112, 16, v70
	v_and_b32_e32 v70, 0xffff0000, v70
	v_mul_f32_e32 v70, v70, v70
	v_fmac_f32_e32 v70, v112, v112
	v_add_f32_e32 v68, v68, v70
	v_lshlrev_b32_e32 v112, 16, v71
	v_and_b32_e32 v71, 0xffff0000, v71
	v_mul_f32_e32 v71, v71, v71
	v_fmac_f32_e32 v71, v112, v112
	v_add_f32_e32 v68, v68, v71
	s_waitcnt vmcnt(1)
	v_lshlrev_b32_e32 v112, 16, v72
	v_and_b32_e32 v72, 0xffff0000, v72
	v_mul_f32_e32 v72, v72, v72
	v_fmac_f32_e32 v72, v112, v112
	v_lshlrev_b32_e32 v112, 16, v73
	v_and_b32_e32 v73, 0xffff0000, v73
	v_mul_f32_e32 v73, v73, v73
	v_fmac_f32_e32 v73, v112, v112
	v_add_f32_e32 v72, v72, v73
	v_lshlrev_b32_e32 v112, 16, v74
	v_and_b32_e32 v74, 0xffff0000, v74
	v_mul_f32_e32 v74, v74, v74
	v_fmac_f32_e32 v74, v112, v112
	v_add_f32_e32 v72, v72, v74
	v_lshlrev_b32_e32 v112, 16, v75
	v_and_b32_e32 v75, 0xffff0000, v75
	v_mul_f32_e32 v75, v75, v75
	v_fmac_f32_e32 v75, v112, v112
	v_add_f32_e32 v72, v72, v75
	s_waitcnt vmcnt(0)
	v_lshlrev_b32_e32 v112, 16, v76
	v_and_b32_e32 v76, 0xffff0000, v76
	v_mul_f32_e32 v76, v76, v76
	v_fmac_f32_e32 v76, v112, v112
	v_lshlrev_b32_e32 v112, 16, v77
	v_and_b32_e32 v77, 0xffff0000, v77
	v_mul_f32_e32 v77, v77, v77
	v_fmac_f32_e32 v77, v112, v112
	v_add_f32_e32 v76, v76, v77
	v_lshlrev_b32_e32 v112, 16, v78
	v_and_b32_e32 v78, 0xffff0000, v78
	v_mul_f32_e32 v78, v78, v78
	v_fmac_f32_e32 v78, v112, v112
	v_add_f32_e32 v76, v76, v78
	v_lshlrev_b32_e32 v112, 16, v79
	v_and_b32_e32 v79, 0xffff0000, v79
	v_mul_f32_e32 v79, v79, v79
	v_fmac_f32_e32 v79, v112, v112
	v_add_f32_e32 v76, v76, v79
	s_nop 1
	v_permlane32_swap_b32_e32 v16, v48
	v_permlane32_swap_b32_e32 v20, v52
	v_permlane32_swap_b32_e32 v24, v56
	v_permlane32_swap_b32_e32 v28, v60
	v_permlane32_swap_b32_e32 v32, v64
	v_permlane32_swap_b32_e32 v36, v68
	v_permlane32_swap_b32_e32 v40, v72
	v_permlane32_swap_b32_e32 v44, v76
	s_nop 0
	v_add_f32_e32 v16, v16, v48
	v_add_f32_e32 v20, v20, v52
	v_add_f32_e32 v24, v24, v56
	v_add_f32_e32 v28, v28, v60
	v_add_f32_e32 v32, v32, v64
	v_add_f32_e32 v36, v36, v68
	v_add_f32_e32 v40, v40, v72
	v_add_f32_e32 v44, v44, v76
	s_nop 1
	v_permlane16_swap_b32_e32 v16, v32
	v_permlane16_swap_b32_e32 v20, v36
	v_permlane16_swap_b32_e32 v24, v40
	v_permlane16_swap_b32_e32 v28, v44
	s_nop 0
	v_add_f32_e32 v16, v16, v32
	v_add_f32_e32 v20, v20, v36
	v_add_f32_e32 v24, v24, v40
	v_add_f32_e32 v28, v28, v44
	s_nop 1
	v_add_f32_dpp v16, v16, v16 row_ror:8 row_mask:0xf bank_mask:0xf
	v_add_f32_dpp v20, v20, v20 row_ror:8 row_mask:0xf bank_mask:0xf
	v_add_f32_dpp v24, v24, v24 row_ror:8 row_mask:0xf bank_mask:0xf
	v_add_f32_dpp v28, v28, v28 row_ror:8 row_mask:0xf bank_mask:0xf
	s_nop 1
	v_add_f32_dpp v16, v16, v16 row_ror:4 row_mask:0xf bank_mask:0xf
	v_add_f32_dpp v20, v20, v20 row_ror:4 row_mask:0xf bank_mask:0xf
	v_add_f32_dpp v24, v24, v24 row_ror:4 row_mask:0xf bank_mask:0xf
	v_add_f32_dpp v28, v28, v28 row_ror:4 row_mask:0xf bank_mask:0xf
	s_nop 1
	v_add_f32_dpp v16, v16, v16 row_ror:2 row_mask:0xf bank_mask:0xf
	v_add_f32_dpp v20, v20, v20 row_ror:2 row_mask:0xf bank_mask:0xf
	v_add_f32_dpp v24, v24, v24 row_ror:2 row_mask:0xf bank_mask:0xf
	v_add_f32_dpp v28, v28, v28 row_ror:2 row_mask:0xf bank_mask:0xf
	s_nop 1
	v_add_f32_dpp v16, v16, v16 row_ror:1 row_mask:0xf bank_mask:0xf
	v_add_f32_dpp v20, v20, v20 row_ror:1 row_mask:0xf bank_mask:0xf
	v_add_f32_dpp v24, v24, v24 row_ror:1 row_mask:0xf bank_mask:0xf
	v_add_f32_dpp v28, v28, v28 row_ror:1 row_mask:0xf bank_mask:0xf
	v_fmamk_f32 v16, v16, 0x3b000000, v166
	v_fmamk_f32 v20, v20, 0x3b000000, v166
	v_fmamk_f32 v24, v24, 0x3b000000, v166
	v_fmamk_f32 v28, v28, 0x3b000000, v166
	v_mul_f32_e32 v112, 0x4b800000, v16
	v_cmp_gt_f32_e32 vcc, s58, v16
	s_nop 1
	v_cndmask_b32_e32 v16, v16, v112, vcc
	v_rsq_f32_e32 v16, v16
	s_nop 0
	v_mul_f32_e32 v112, 0x45800000, v16
	v_cndmask_b32_e32 v16, v16, v112, vcc
	v_mul_f32_e32 v16, 0x3dd53b94, v16
	v_mul_f32_e32 v112, 0x4b800000, v20
	v_cmp_gt_f32_e32 vcc, s58, v20
	s_nop 1
	v_cndmask_b32_e32 v20, v20, v112, vcc
	v_rsq_f32_e32 v20, v20
	s_nop 0
	v_mul_f32_e32 v112, 0x45800000, v20
	v_cndmask_b32_e32 v20, v20, v112, vcc
	v_mul_f32_e32 v20, 0x3dd53b94, v20
	v_mul_f32_e32 v112, 0x4b800000, v24
	v_cmp_gt_f32_e32 vcc, s58, v24
	s_nop 1
	v_cndmask_b32_e32 v24, v24, v112, vcc
	v_rsq_f32_e32 v24, v24
	s_nop 0
	v_mul_f32_e32 v112, 0x45800000, v24
	v_cndmask_b32_e32 v24, v24, v112, vcc
	v_mul_f32_e32 v24, 0x3dd53b94, v24
	v_mul_f32_e32 v112, 0x4b800000, v28
	v_cmp_gt_f32_e32 vcc, s58, v28
	s_nop 1
	v_cndmask_b32_e32 v28, v28, v112, vcc
	v_rsq_f32_e32 v28, v28
	s_nop 0
	v_mul_f32_e32 v112, 0x45800000, v28
	v_cndmask_b32_e32 v28, v28, v112, vcc
	v_mul_f32_e32 v28, 0x3dd53b94, v28
	v_mov_b32_e32 v112, v16
	v_mov_b32_e32 v113, v20
	v_mov_b32_e32 v114, v24
	v_mov_b32_e32 v115, v28
	v_cmp_eq_u32_e32 vcc, 0, v118
	s_and_saveexec_b64 s[0:1], vcc
	ds_write_b128 v117, v[112:115]
	s_or_b64 exec, exec, s[0:1]
	global_load_dwordx4 v[16:19], v116, s[24:25]
	s_add_u32 s24, s24, 0x1700
	s_addc_u32 s25, s25, 0
	global_load_dwordx4 v[20:23], v116, s[24:25]
	s_add_u32 s24, s24, 0x1700
	s_addc_u32 s25, s25, 0
	global_load_dwordx4 v[24:27], v116, s[24:25]
	s_add_u32 s24, s24, 0x1700
	s_addc_u32 s25, s25, 0
	global_load_dwordx4 v[28:31], v116, s[24:25]
	s_add_u32 s24, s24, 0x1700
	s_addc_u32 s25, s25, 0
	global_load_dwordx4 v[32:35], v116, s[24:25]
	s_add_u32 s24, s24, 0x1700
	s_addc_u32 s25, s25, 0
	global_load_dwordx4 v[36:39], v116, s[24:25]
	s_add_u32 s24, s24, 0x1700
	s_addc_u32 s25, s25, 0
	global_load_dwordx4 v[40:43], v116, s[24:25]
	s_add_u32 s24, s24, 0x1700
	s_addc_u32 s25, s25, 0
	global_load_dwordx4 v[44:47], v116, s[24:25]
	s_add_u32 s24, s24, 0x1700
	s_addc_u32 s25, s25, 0
	global_load_dwordx4 v[48:51], v116, s[24:25]
	s_add_u32 s24, s24, 0x1700
	s_addc_u32 s25, s25, 0
	global_load_dwordx4 v[52:55], v116, s[24:25]
	s_add_u32 s24, s24, 0x1700
	s_addc_u32 s25, s25, 0
	global_load_dwordx4 v[56:59], v116, s[24:25]
	s_add_u32 s24, s24, 0x1700
	s_addc_u32 s25, s25, 0
	global_load_dwordx4 v[60:63], v116, s[24:25]
	s_add_u32 s24, s24, 0x1700
	s_addc_u32 s25, s25, 0
	global_load_dwordx4 v[64:67], v116, s[24:25]
	s_add_u32 s24, s24, 0x1700
	s_addc_u32 s25, s25, 0
	global_load_dwordx4 v[68:71], v116, s[24:25]
	s_add_u32 s24, s24, 0x1700
	s_addc_u32 s25, s25, 0
	global_load_dwordx4 v[72:75], v116, s[24:25]
	s_add_u32 s24, s24, 0x1700
	s_addc_u32 s25, s25, 0
	global_load_dwordx4 v[76:79], v116, s[24:25]
	s_add_u32 s24, s24, 0x1700
	s_addc_u32 s25, s25, 0
	s_waitcnt vmcnt(15)
	v_lshlrev_b32_e32 v112, 16, v16
	v_and_b32_e32 v16, 0xffff0000, v16
	v_mul_f32_e32 v16, v16, v16
	v_fmac_f32_e32 v16, v112, v112
	v_lshlrev_b32_e32 v112, 16, v17
	v_and_b32_e32 v17, 0xffff0000, v17
	v_mul_f32_e32 v17, v17, v17
	v_fmac_f32_e32 v17, v112, v112
	v_add_f32_e32 v16, v16, v17
	v_lshlrev_b32_e32 v112, 16, v18
	v_and_b32_e32 v18, 0xffff0000, v18
	v_mul_f32_e32 v18, v18, v18
	v_fmac_f32_e32 v18, v112, v112
	v_add_f32_e32 v16, v16, v18
	v_lshlrev_b32_e32 v112, 16, v19
	v_and_b32_e32 v19, 0xffff0000, v19
	v_mul_f32_e32 v19, v19, v19
	v_fmac_f32_e32 v19, v112, v112
	v_add_f32_e32 v16, v16, v19
	s_waitcnt vmcnt(14)
	v_lshlrev_b32_e32 v112, 16, v20
	v_and_b32_e32 v20, 0xffff0000, v20
	v_mul_f32_e32 v20, v20, v20
	v_fmac_f32_e32 v20, v112, v112
	v_lshlrev_b32_e32 v112, 16, v21
	v_and_b32_e32 v21, 0xffff0000, v21
	v_mul_f32_e32 v21, v21, v21
	v_fmac_f32_e32 v21, v112, v112
	v_add_f32_e32 v20, v20, v21
	v_lshlrev_b32_e32 v112, 16, v22
	v_and_b32_e32 v22, 0xffff0000, v22
	v_mul_f32_e32 v22, v22, v22
	v_fmac_f32_e32 v22, v112, v112
	v_add_f32_e32 v20, v20, v22
	v_lshlrev_b32_e32 v112, 16, v23
	v_and_b32_e32 v23, 0xffff0000, v23
	v_mul_f32_e32 v23, v23, v23
	v_fmac_f32_e32 v23, v112, v112
	v_add_f32_e32 v20, v20, v23
	s_waitcnt vmcnt(13)
	v_lshlrev_b32_e32 v112, 16, v24
	v_and_b32_e32 v24, 0xffff0000, v24
	v_mul_f32_e32 v24, v24, v24
	v_fmac_f32_e32 v24, v112, v112
	v_lshlrev_b32_e32 v112, 16, v25
	v_and_b32_e32 v25, 0xffff0000, v25
	v_mul_f32_e32 v25, v25, v25
	v_fmac_f32_e32 v25, v112, v112
	v_add_f32_e32 v24, v24, v25
	v_lshlrev_b32_e32 v112, 16, v26
	v_and_b32_e32 v26, 0xffff0000, v26
	v_mul_f32_e32 v26, v26, v26
	v_fmac_f32_e32 v26, v112, v112
	v_add_f32_e32 v24, v24, v26
	v_lshlrev_b32_e32 v112, 16, v27
	v_and_b32_e32 v27, 0xffff0000, v27
	v_mul_f32_e32 v27, v27, v27
	v_fmac_f32_e32 v27, v112, v112
	v_add_f32_e32 v24, v24, v27
	s_waitcnt vmcnt(12)
	v_lshlrev_b32_e32 v112, 16, v28
	v_and_b32_e32 v28, 0xffff0000, v28
	v_mul_f32_e32 v28, v28, v28
	v_fmac_f32_e32 v28, v112, v112
	v_lshlrev_b32_e32 v112, 16, v29
	v_and_b32_e32 v29, 0xffff0000, v29
	v_mul_f32_e32 v29, v29, v29
	v_fmac_f32_e32 v29, v112, v112
	v_add_f32_e32 v28, v28, v29
	v_lshlrev_b32_e32 v112, 16, v30
	v_and_b32_e32 v30, 0xffff0000, v30
	v_mul_f32_e32 v30, v30, v30
	v_fmac_f32_e32 v30, v112, v112
	v_add_f32_e32 v28, v28, v30
	v_lshlrev_b32_e32 v112, 16, v31
	v_and_b32_e32 v31, 0xffff0000, v31
	v_mul_f32_e32 v31, v31, v31
	v_fmac_f32_e32 v31, v112, v112
	v_add_f32_e32 v28, v28, v31
	s_waitcnt vmcnt(11)
	v_lshlrev_b32_e32 v112, 16, v32
	v_and_b32_e32 v32, 0xffff0000, v32
	v_mul_f32_e32 v32, v32, v32
	v_fmac_f32_e32 v32, v112, v112
	v_lshlrev_b32_e32 v112, 16, v33
	v_and_b32_e32 v33, 0xffff0000, v33
	v_mul_f32_e32 v33, v33, v33
	v_fmac_f32_e32 v33, v112, v112
	v_add_f32_e32 v32, v32, v33
	v_lshlrev_b32_e32 v112, 16, v34
	v_and_b32_e32 v34, 0xffff0000, v34
	v_mul_f32_e32 v34, v34, v34
	v_fmac_f32_e32 v34, v112, v112
	v_add_f32_e32 v32, v32, v34
	v_lshlrev_b32_e32 v112, 16, v35
	v_and_b32_e32 v35, 0xffff0000, v35
	v_mul_f32_e32 v35, v35, v35
	v_fmac_f32_e32 v35, v112, v112
	v_add_f32_e32 v32, v32, v35
	s_waitcnt vmcnt(10)
	v_lshlrev_b32_e32 v112, 16, v36
	v_and_b32_e32 v36, 0xffff0000, v36
	v_mul_f32_e32 v36, v36, v36
	v_fmac_f32_e32 v36, v112, v112
	v_lshlrev_b32_e32 v112, 16, v37
	v_and_b32_e32 v37, 0xffff0000, v37
	v_mul_f32_e32 v37, v37, v37
	v_fmac_f32_e32 v37, v112, v112
	v_add_f32_e32 v36, v36, v37
	v_lshlrev_b32_e32 v112, 16, v38
	v_and_b32_e32 v38, 0xffff0000, v38
	v_mul_f32_e32 v38, v38, v38
	v_fmac_f32_e32 v38, v112, v112
	v_add_f32_e32 v36, v36, v38
	v_lshlrev_b32_e32 v112, 16, v39
	v_and_b32_e32 v39, 0xffff0000, v39
	v_mul_f32_e32 v39, v39, v39
	v_fmac_f32_e32 v39, v112, v112
	v_add_f32_e32 v36, v36, v39
	s_waitcnt vmcnt(9)
	v_lshlrev_b32_e32 v112, 16, v40
	v_and_b32_e32 v40, 0xffff0000, v40
	v_mul_f32_e32 v40, v40, v40
	v_fmac_f32_e32 v40, v112, v112
	v_lshlrev_b32_e32 v112, 16, v41
	v_and_b32_e32 v41, 0xffff0000, v41
	v_mul_f32_e32 v41, v41, v41
	v_fmac_f32_e32 v41, v112, v112
	v_add_f32_e32 v40, v40, v41
	v_lshlrev_b32_e32 v112, 16, v42
	v_and_b32_e32 v42, 0xffff0000, v42
	v_mul_f32_e32 v42, v42, v42
	v_fmac_f32_e32 v42, v112, v112
	v_add_f32_e32 v40, v40, v42
	v_lshlrev_b32_e32 v112, 16, v43
	v_and_b32_e32 v43, 0xffff0000, v43
	v_mul_f32_e32 v43, v43, v43
	v_fmac_f32_e32 v43, v112, v112
	v_add_f32_e32 v40, v40, v43
	s_waitcnt vmcnt(8)
	v_lshlrev_b32_e32 v112, 16, v44
	v_and_b32_e32 v44, 0xffff0000, v44
	v_mul_f32_e32 v44, v44, v44
	v_fmac_f32_e32 v44, v112, v112
	v_lshlrev_b32_e32 v112, 16, v45
	v_and_b32_e32 v45, 0xffff0000, v45
	v_mul_f32_e32 v45, v45, v45
	v_fmac_f32_e32 v45, v112, v112
	v_add_f32_e32 v44, v44, v45
	v_lshlrev_b32_e32 v112, 16, v46
	v_and_b32_e32 v46, 0xffff0000, v46
	v_mul_f32_e32 v46, v46, v46
	v_fmac_f32_e32 v46, v112, v112
	v_add_f32_e32 v44, v44, v46
	v_lshlrev_b32_e32 v112, 16, v47
	v_and_b32_e32 v47, 0xffff0000, v47
	v_mul_f32_e32 v47, v47, v47
	v_fmac_f32_e32 v47, v112, v112
	v_add_f32_e32 v44, v44, v47
	s_waitcnt vmcnt(7)
	v_lshlrev_b32_e32 v112, 16, v48
	v_and_b32_e32 v48, 0xffff0000, v48
	v_mul_f32_e32 v48, v48, v48
	v_fmac_f32_e32 v48, v112, v112
	v_lshlrev_b32_e32 v112, 16, v49
	v_and_b32_e32 v49, 0xffff0000, v49
	v_mul_f32_e32 v49, v49, v49
	v_fmac_f32_e32 v49, v112, v112
	v_add_f32_e32 v48, v48, v49
	v_lshlrev_b32_e32 v112, 16, v50
	v_and_b32_e32 v50, 0xffff0000, v50
	v_mul_f32_e32 v50, v50, v50
	v_fmac_f32_e32 v50, v112, v112
	v_add_f32_e32 v48, v48, v50
	v_lshlrev_b32_e32 v112, 16, v51
	v_and_b32_e32 v51, 0xffff0000, v51
	v_mul_f32_e32 v51, v51, v51
	v_fmac_f32_e32 v51, v112, v112
	v_add_f32_e32 v48, v48, v51
	s_waitcnt vmcnt(6)
	v_lshlrev_b32_e32 v112, 16, v52
	v_and_b32_e32 v52, 0xffff0000, v52
	v_mul_f32_e32 v52, v52, v52
	v_fmac_f32_e32 v52, v112, v112
	v_lshlrev_b32_e32 v112, 16, v53
	v_and_b32_e32 v53, 0xffff0000, v53
	v_mul_f32_e32 v53, v53, v53
	v_fmac_f32_e32 v53, v112, v112
	v_add_f32_e32 v52, v52, v53
	v_lshlrev_b32_e32 v112, 16, v54
	v_and_b32_e32 v54, 0xffff0000, v54
	v_mul_f32_e32 v54, v54, v54
	v_fmac_f32_e32 v54, v112, v112
	v_add_f32_e32 v52, v52, v54
	v_lshlrev_b32_e32 v112, 16, v55
	v_and_b32_e32 v55, 0xffff0000, v55
	v_mul_f32_e32 v55, v55, v55
	v_fmac_f32_e32 v55, v112, v112
	v_add_f32_e32 v52, v52, v55
	s_waitcnt vmcnt(5)
	v_lshlrev_b32_e32 v112, 16, v56
	v_and_b32_e32 v56, 0xffff0000, v56
	v_mul_f32_e32 v56, v56, v56
	v_fmac_f32_e32 v56, v112, v112
	v_lshlrev_b32_e32 v112, 16, v57
	v_and_b32_e32 v57, 0xffff0000, v57
	v_mul_f32_e32 v57, v57, v57
	v_fmac_f32_e32 v57, v112, v112
	v_add_f32_e32 v56, v56, v57
	v_lshlrev_b32_e32 v112, 16, v58
	v_and_b32_e32 v58, 0xffff0000, v58
	v_mul_f32_e32 v58, v58, v58
	v_fmac_f32_e32 v58, v112, v112
	v_add_f32_e32 v56, v56, v58
	v_lshlrev_b32_e32 v112, 16, v59
	v_and_b32_e32 v59, 0xffff0000, v59
	v_mul_f32_e32 v59, v59, v59
	v_fmac_f32_e32 v59, v112, v112
	v_add_f32_e32 v56, v56, v59
	s_waitcnt vmcnt(4)
	v_lshlrev_b32_e32 v112, 16, v60
	v_and_b32_e32 v60, 0xffff0000, v60
	v_mul_f32_e32 v60, v60, v60
	v_fmac_f32_e32 v60, v112, v112
	v_lshlrev_b32_e32 v112, 16, v61
	v_and_b32_e32 v61, 0xffff0000, v61
	v_mul_f32_e32 v61, v61, v61
	v_fmac_f32_e32 v61, v112, v112
	v_add_f32_e32 v60, v60, v61
	v_lshlrev_b32_e32 v112, 16, v62
	v_and_b32_e32 v62, 0xffff0000, v62
	v_mul_f32_e32 v62, v62, v62
	v_fmac_f32_e32 v62, v112, v112
	v_add_f32_e32 v60, v60, v62
	v_lshlrev_b32_e32 v112, 16, v63
	v_and_b32_e32 v63, 0xffff0000, v63
	v_mul_f32_e32 v63, v63, v63
	v_fmac_f32_e32 v63, v112, v112
	v_add_f32_e32 v60, v60, v63
	s_waitcnt vmcnt(3)
	v_lshlrev_b32_e32 v112, 16, v64
	v_and_b32_e32 v64, 0xffff0000, v64
	v_mul_f32_e32 v64, v64, v64
	v_fmac_f32_e32 v64, v112, v112
	v_lshlrev_b32_e32 v112, 16, v65
	v_and_b32_e32 v65, 0xffff0000, v65
	v_mul_f32_e32 v65, v65, v65
	v_fmac_f32_e32 v65, v112, v112
	v_add_f32_e32 v64, v64, v65
	v_lshlrev_b32_e32 v112, 16, v66
	v_and_b32_e32 v66, 0xffff0000, v66
	v_mul_f32_e32 v66, v66, v66
	v_fmac_f32_e32 v66, v112, v112
	v_add_f32_e32 v64, v64, v66
	v_lshlrev_b32_e32 v112, 16, v67
	v_and_b32_e32 v67, 0xffff0000, v67
	v_mul_f32_e32 v67, v67, v67
	v_fmac_f32_e32 v67, v112, v112
	v_add_f32_e32 v64, v64, v67
	s_waitcnt vmcnt(2)
	v_lshlrev_b32_e32 v112, 16, v68
	v_and_b32_e32 v68, 0xffff0000, v68
	v_mul_f32_e32 v68, v68, v68
	v_fmac_f32_e32 v68, v112, v112
	v_lshlrev_b32_e32 v112, 16, v69
	v_and_b32_e32 v69, 0xffff0000, v69
	v_mul_f32_e32 v69, v69, v69
	v_fmac_f32_e32 v69, v112, v112
	v_add_f32_e32 v68, v68, v69
	v_lshlrev_b32_e32 v112, 16, v70
	v_and_b32_e32 v70, 0xffff0000, v70
	v_mul_f32_e32 v70, v70, v70
	v_fmac_f32_e32 v70, v112, v112
	v_add_f32_e32 v68, v68, v70
	v_lshlrev_b32_e32 v112, 16, v71
	v_and_b32_e32 v71, 0xffff0000, v71
	v_mul_f32_e32 v71, v71, v71
	v_fmac_f32_e32 v71, v112, v112
	v_add_f32_e32 v68, v68, v71
	s_waitcnt vmcnt(1)
	v_lshlrev_b32_e32 v112, 16, v72
	v_and_b32_e32 v72, 0xffff0000, v72
	v_mul_f32_e32 v72, v72, v72
	v_fmac_f32_e32 v72, v112, v112
	v_lshlrev_b32_e32 v112, 16, v73
	v_and_b32_e32 v73, 0xffff0000, v73
	v_mul_f32_e32 v73, v73, v73
	v_fmac_f32_e32 v73, v112, v112
	v_add_f32_e32 v72, v72, v73
	v_lshlrev_b32_e32 v112, 16, v74
	v_and_b32_e32 v74, 0xffff0000, v74
	v_mul_f32_e32 v74, v74, v74
	v_fmac_f32_e32 v74, v112, v112
	v_add_f32_e32 v72, v72, v74
	v_lshlrev_b32_e32 v112, 16, v75
	v_and_b32_e32 v75, 0xffff0000, v75
	v_mul_f32_e32 v75, v75, v75
	v_fmac_f32_e32 v75, v112, v112
	v_add_f32_e32 v72, v72, v75
	s_waitcnt vmcnt(0)
	v_lshlrev_b32_e32 v112, 16, v76
	v_and_b32_e32 v76, 0xffff0000, v76
	v_mul_f32_e32 v76, v76, v76
	v_fmac_f32_e32 v76, v112, v112
	v_lshlrev_b32_e32 v112, 16, v77
	v_and_b32_e32 v77, 0xffff0000, v77
	v_mul_f32_e32 v77, v77, v77
	v_fmac_f32_e32 v77, v112, v112
	v_add_f32_e32 v76, v76, v77
	v_lshlrev_b32_e32 v112, 16, v78
	v_and_b32_e32 v78, 0xffff0000, v78
	v_mul_f32_e32 v78, v78, v78
	v_fmac_f32_e32 v78, v112, v112
	v_add_f32_e32 v76, v76, v78
	v_lshlrev_b32_e32 v112, 16, v79
	v_and_b32_e32 v79, 0xffff0000, v79
	v_mul_f32_e32 v79, v79, v79
	v_fmac_f32_e32 v79, v112, v112
	v_add_f32_e32 v76, v76, v79
	s_nop 1
	v_permlane32_swap_b32_e32 v16, v48
	v_permlane32_swap_b32_e32 v20, v52
	v_permlane32_swap_b32_e32 v24, v56
	v_permlane32_swap_b32_e32 v28, v60
	v_permlane32_swap_b32_e32 v32, v64
	v_permlane32_swap_b32_e32 v36, v68
	v_permlane32_swap_b32_e32 v40, v72
	v_permlane32_swap_b32_e32 v44, v76
	s_nop 0
	v_add_f32_e32 v16, v16, v48
	v_add_f32_e32 v20, v20, v52
	v_add_f32_e32 v24, v24, v56
	v_add_f32_e32 v28, v28, v60
	v_add_f32_e32 v32, v32, v64
	v_add_f32_e32 v36, v36, v68
	v_add_f32_e32 v40, v40, v72
	v_add_f32_e32 v44, v44, v76
	s_nop 1
	v_permlane16_swap_b32_e32 v16, v32
	v_permlane16_swap_b32_e32 v20, v36
	v_permlane16_swap_b32_e32 v24, v40
	v_permlane16_swap_b32_e32 v28, v44
	s_nop 0
	v_add_f32_e32 v16, v16, v32
	v_add_f32_e32 v20, v20, v36
	v_add_f32_e32 v24, v24, v40
	v_add_f32_e32 v28, v28, v44
	s_nop 1
	v_add_f32_dpp v16, v16, v16 row_ror:8 row_mask:0xf bank_mask:0xf
	v_add_f32_dpp v20, v20, v20 row_ror:8 row_mask:0xf bank_mask:0xf
	v_add_f32_dpp v24, v24, v24 row_ror:8 row_mask:0xf bank_mask:0xf
	v_add_f32_dpp v28, v28, v28 row_ror:8 row_mask:0xf bank_mask:0xf
	s_nop 1
	v_add_f32_dpp v16, v16, v16 row_ror:4 row_mask:0xf bank_mask:0xf
	v_add_f32_dpp v20, v20, v20 row_ror:4 row_mask:0xf bank_mask:0xf
	v_add_f32_dpp v24, v24, v24 row_ror:4 row_mask:0xf bank_mask:0xf
	v_add_f32_dpp v28, v28, v28 row_ror:4 row_mask:0xf bank_mask:0xf
	s_nop 1
	v_add_f32_dpp v16, v16, v16 row_ror:2 row_mask:0xf bank_mask:0xf
	v_add_f32_dpp v20, v20, v20 row_ror:2 row_mask:0xf bank_mask:0xf
	v_add_f32_dpp v24, v24, v24 row_ror:2 row_mask:0xf bank_mask:0xf
	v_add_f32_dpp v28, v28, v28 row_ror:2 row_mask:0xf bank_mask:0xf
	s_nop 1
	v_add_f32_dpp v16, v16, v16 row_ror:1 row_mask:0xf bank_mask:0xf
	v_add_f32_dpp v20, v20, v20 row_ror:1 row_mask:0xf bank_mask:0xf
	v_add_f32_dpp v24, v24, v24 row_ror:1 row_mask:0xf bank_mask:0xf
	v_add_f32_dpp v28, v28, v28 row_ror:1 row_mask:0xf bank_mask:0xf
	v_fmamk_f32 v16, v16, 0x3b000000, v166
	v_fmamk_f32 v20, v20, 0x3b000000, v166
	v_fmamk_f32 v24, v24, 0x3b000000, v166
	v_fmamk_f32 v28, v28, 0x3b000000, v166
	v_mul_f32_e32 v112, 0x4b800000, v16
	v_cmp_gt_f32_e32 vcc, s58, v16
	s_nop 1
	v_cndmask_b32_e32 v16, v16, v112, vcc
	v_rsq_f32_e32 v16, v16
	s_nop 0
	v_mul_f32_e32 v112, 0x45800000, v16
	v_cndmask_b32_e32 v16, v16, v112, vcc
	v_mul_f32_e32 v16, 0x3dd53b94, v16
	v_mul_f32_e32 v112, 0x4b800000, v20
	v_cmp_gt_f32_e32 vcc, s58, v20
	s_nop 1
	v_cndmask_b32_e32 v20, v20, v112, vcc
	v_rsq_f32_e32 v20, v20
	s_nop 0
	v_mul_f32_e32 v112, 0x45800000, v20
	v_cndmask_b32_e32 v20, v20, v112, vcc
	v_mul_f32_e32 v20, 0x3dd53b94, v20
	v_mul_f32_e32 v112, 0x4b800000, v24
	v_cmp_gt_f32_e32 vcc, s58, v24
	s_nop 1
	v_cndmask_b32_e32 v24, v24, v112, vcc
	v_rsq_f32_e32 v24, v24
	s_nop 0
	v_mul_f32_e32 v112, 0x45800000, v24
	v_cndmask_b32_e32 v24, v24, v112, vcc
	v_mul_f32_e32 v24, 0x3dd53b94, v24
	v_mul_f32_e32 v112, 0x4b800000, v28
	v_cmp_gt_f32_e32 vcc, s58, v28
	s_nop 1
	v_cndmask_b32_e32 v28, v28, v112, vcc
	v_rsq_f32_e32 v28, v28
	s_nop 0
	v_mul_f32_e32 v112, 0x45800000, v28
	v_cndmask_b32_e32 v28, v28, v112, vcc
	v_mul_f32_e32 v28, 0x3dd53b94, v28
	v_mov_b32_e32 v112, v16
	v_mov_b32_e32 v113, v20
	v_mov_b32_e32 v114, v24
	v_mov_b32_e32 v115, v28
	v_cmp_eq_u32_e32 vcc, 0, v118
	s_and_saveexec_b64 s[0:1], vcc
	ds_write_b128 v117, v[112:115] offset:64
	s_or_b64 exec, exec, s[0:1]
.LBB0_839:
	s_mul_i32 s0, s9, 6
	v_mov_b32_e32 v22, v167
	s_sub_i32 s1, s16, s0
	s_waitcnt lgkmcnt(0)
	s_barrier
	s_mul_i32 s16, s9, 0xb8000
	s_and_b32 s0, s1, 0xffff
	v_lshlrev_b32_e32 v1, 4, v22
	v_and_b32_e32 v0, 32, v22
	s_lshl_b64 s[2:3], s[16:17], 1
	v_bitop3_b32 v0, v1, v0, 48 bitop3:0x6c
	s_add_u32 s24, s22, s2
	v_lshrrev_b32_e32 v2, 1, v22
	v_lshrrev_b32_e32 v0, 1, v0
	s_addc_u32 s25, s23, s3
	s_lshl_b32 s1, s1, 18
	v_and_b32_e32 v16, 0xfffffc00, v1
	v_lshrrev_b32_e32 v3, 2, v22
	v_and_or_b32 v5, v2, 32, v0
	v_ashrrev_i32_e32 v0, 3, v22
	v_add_u32_e32 v4, 0x2000, v1
	v_add_u32_e32 v7, 0x4000, v1
	v_add_u32_e32 v1, 0x6000, v1
	s_add_u32 s26, s12, s1
	v_bfi_b32 v2, 15, v3, v0
	s_movk_i32 s1, 0xb80
	v_ashrrev_i32_e32 v4, 7, v4
	v_ashrrev_i32_e32 v7, 7, v7
	v_ashrrev_i32_e32 v1, 7, v1
	v_mul_lo_u32 v0, v2, s1
	v_bfi_b32 v6, -16, v4, v3
	v_bfi_b32 v7, -16, v7, v3
	v_bfi_b32 v1, -16, v1, v3
	v_or_b32_e32 v0, v0, v5
	v_mul_lo_u32 v4, v6, s1
	v_mul_lo_u32 v8, v7, s1
	v_mul_lo_u32 v3, v1, s1
	v_add_u32_e32 v17, 0, v16
	v_lshl_or_b32 v2, v2, 9, v5
	v_or_b32_e32 v4, v4, v5
	v_lshl_or_b32 v6, v6, 9, v5
	v_or_b32_e32 v8, v8, v5
	v_lshl_or_b32 v10, v7, 9, v5
	v_or_b32_e32 v12, v3, v5
	v_lshl_or_b32 v14, v1, 9, v5
	v_add_u32_e32 v5, 0x8000, v17
	v_ashrrev_i32_e32 v1, 31, v0
	v_readfirstlane_b32 s2, v17
	s_addc_u32 s27, s13, 0
	v_lshl_add_u64 v[0:1], v[0:1], 1, s[24:25]
	s_mov_b32 m0, s2
	v_ashrrev_i32_e32 v3, 31, v2
	v_readfirstlane_b32 s1, v5
	v_add_u32_e32 v32, 0x2000, v17
	global_load_lds_dwordx4 v[0:1], off
	v_lshl_add_u64 v[2:3], v[2:3], 1, s[26:27]
	s_mov_b32 m0, s1
	v_ashrrev_i32_e32 v5, 31, v4
	v_readfirstlane_b32 s3, v32
	v_add_u32_e32 v33, 0xa000, v17
	global_load_lds_dwordx4 v[2:3], off
	v_lshl_add_u64 v[4:5], v[4:5], 1, s[24:25]
	s_mov_b32 m0, s3
	v_ashrrev_i32_e32 v7, 31, v6
	v_readfirstlane_b32 s9, v33
	v_add_u32_e32 v34, 0x4000, v17
	global_load_lds_dwordx4 v[4:5], off
	v_lshl_add_u64 v[6:7], v[6:7], 1, s[26:27]
	s_mov_b32 m0, s9
	v_ashrrev_i32_e32 v9, 31, v8
	v_readfirstlane_b32 s10, v34
	v_add_u32_e32 v35, 0xc000, v17
	global_load_lds_dwordx4 v[6:7], off
	v_lshl_add_u64 v[8:9], v[8:9], 1, s[24:25]
	s_mov_b32 m0, s10
	v_ashrrev_i32_e32 v11, 31, v10
	v_readfirstlane_b32 s11, v35
	v_add_u32_e32 v36, 0x6000, v17
	v_add_u32_e32 v37, 0xe000, v17
	v_and_b32_e32 v17, 15, v22
	v_lshlrev_b32_e32 v19, 2, v22
	global_load_lds_dwordx4 v[8:9], off
	v_lshl_add_u64 v[10:11], v[10:11], 1, s[26:27]
	s_mov_b32 m0, s11
	v_ashrrev_i32_e32 v13, 31, v12
	v_readfirstlane_b32 s16, v36
	v_and_b32_e32 v18, 48, v22
	v_lshlrev_b32_e32 v17, 6, v17
	v_and_b32_e32 v19, 32, v19
	global_load_lds_dwordx4 v[10:11], off
	v_lshl_add_u64 v[12:13], v[12:13], 1, s[24:25]
	s_mov_b32 m0, s16
	v_ashrrev_i32_e32 v15, 31, v14
	v_readfirstlane_b32 s24, v37
	v_bitop3_b32 v25, v17, v19, v18 bitop3:0x36
	v_lshlrev_b32_e32 v17, 6, v22
	v_add_u32_e32 v39, s90, v16
	v_readlane_b32 s41, v254, 11
	global_load_lds_dwordx4 v[12:13], off
	v_lshl_add_u64 v[14:15], v[14:15], 1, s[26:27]
	s_mov_b32 m0, s24
	v_and_b32_e32 v30, 0xffffc000, v17
	v_and_b32_e32 v17, 0x3c0, v17
	v_add_u32_e32 v38, s41, v16
	v_readfirstlane_b32 s34, v39
	global_load_lds_dwordx4 v[14:15], off
	v_bitop3_b32 v127, v17, v19, v18 bitop3:0x36
	v_lshl_add_u64 v[16:17], v[0:1], 0, s[96:97]
	s_mov_b32 m0, s34
	v_readfirstlane_b32 s25, v38
	v_add_u32_e32 v40, 0x2000, v39
	s_waitcnt vmcnt(0)
	s_waitcnt vmcnt(0) lgkmcnt(0)
	s_barrier
	global_load_lds_dwordx4 v[16:17], off
	v_lshl_add_u64 v[16:17], v[2:3], 0, s[96:97]
	s_mov_b32 m0, s25
	v_readfirstlane_b32 s26, v40
	v_add_u32_e32 v41, 0x2000, v38
	global_load_lds_dwordx4 v[16:17], off
	v_lshl_add_u64 v[16:17], v[4:5], 0, s[96:97]
	s_mov_b32 m0, s26
	v_readfirstlane_b32 s27, v41
	v_add_u32_e32 v42, 0x4000, v39
	global_load_lds_dwordx4 v[16:17], off
	v_lshl_add_u64 v[16:17], v[6:7], 0, s[96:97]
	s_mov_b32 m0, s27
	v_readfirstlane_b32 s35, v42
	v_add_u32_e32 v43, 0x4000, v38
	global_load_lds_dwordx4 v[16:17], off
	v_lshl_add_u64 v[16:17], v[8:9], 0, s[96:97]
	s_mov_b32 m0, s35
	v_readfirstlane_b32 s36, v43
	v_add_u32_e32 v44, 0x6000, v39
	global_load_lds_dwordx4 v[16:17], off
	v_lshl_add_u64 v[16:17], v[10:11], 0, s[96:97]
	s_mov_b32 m0, s36
	v_readfirstlane_b32 s37, v44
	v_add_u32_e32 v45, 0x6000, v38
	global_load_lds_dwordx4 v[16:17], off
	v_lshl_add_u64 v[16:17], v[12:13], 0, s[96:97]
	s_mov_b32 m0, s37
	v_readfirstlane_b32 s40, v45
	global_load_lds_dwordx4 v[16:17], off
	v_lshl_add_u64 v[16:17], v[14:15], 0, s[96:97]
	s_mov_b32 m0, s40
	v_or_b32_e32 v126, 0x800, v30
	global_load_lds_dwordx4 v[16:17], off
	v_add_u32_e32 v16, 0, v25
	v_add_u32_e32 v24, v16, v30
	ds_read_b128 v[18:21], v24
	v_lshlrev_b32_e32 v17, 7, v22
	v_and_b32_e32 v162, 0x6000, v17
	v_add_u32_e32 v17, 0, v127
	v_add_u32_e32 v23, v16, v162
	v_add_u32_e32 v16, v17, v126
	ds_read_b128 v[26:29], v23 offset:32768
	ds_read_b128 v[46:49], v16
	ds_read_b128 v[50:53], v23 offset:34816
	ds_read_b128 v[62:65], v23 offset:36864
	ds_read_b128 v[66:69], v23 offset:38912
	v_or_b32_e32 v163, 0x1000, v30
	v_or_b32_e32 v164, 0x1800, v30
	v_or_b32_e32 v180, 0x2000, v30
	v_or_b32_e32 v182, 0x2800, v30
	v_or_b32_e32 v183, 0x3000, v30
	v_or_b32_e32 v193, 0x3800, v30
	s_waitcnt lgkmcnt(0)
	v_mfma_f32_16x16x32_bf16 v[54:57], v[26:29], v[18:21], 0
	v_add_u32_e32 v22, v17, v163
	ds_read_b128 v[90:93], v22
	v_mfma_f32_16x16x32_bf16 v[58:61], v[50:53], v[18:21], 0
	v_mfma_f32_16x16x32_bf16 v[70:73], v[62:65], v[18:21], 0
	v_mfma_f32_16x16x32_bf16 v[74:77], v[66:69], v[18:21], 0
	v_add_u32_e32 v19, v17, v164
	v_add_u32_e32 v21, v17, v180
	v_add_u32_e32 v18, v17, v182
	v_add_u32_e32 v20, v17, v183
	v_add_u32_e32 v17, v17, v193
	ds_read_b128 v[94:97], v19
	ds_read_b128 v[158:161], v20
	ds_read_b128 v[122:125], v21
	ds_read_b128 v[130:133], v18
	ds_read_b128 v[168:171], v17
	v_mfma_f32_16x16x32_bf16 v[78:81], v[26:29], v[46:49], 0
	v_mfma_f32_16x16x32_bf16 v[82:85], v[50:53], v[46:49], 0
	v_mfma_f32_16x16x32_bf16 v[86:89], v[62:65], v[46:49], 0
	v_mfma_f32_16x16x32_bf16 v[46:49], v[66:69], v[46:49], 0
	s_waitcnt lgkmcnt(0)
	v_mfma_f32_16x16x32_bf16 v[98:101], v[26:29], v[90:93], 0
	v_mfma_f32_16x16x32_bf16 v[102:105], v[50:53], v[90:93], 0
	v_mfma_f32_16x16x32_bf16 v[106:109], v[62:65], v[90:93], 0
	v_mfma_f32_16x16x32_bf16 v[90:93], v[66:69], v[90:93], 0
	v_mfma_f32_16x16x32_bf16 v[110:113], v[26:29], v[94:97], 0
	v_mfma_f32_16x16x32_bf16 v[114:117], v[50:53], v[94:97], 0
	v_mfma_f32_16x16x32_bf16 v[118:121], v[62:65], v[94:97], 0
	v_mfma_f32_16x16x32_bf16 v[94:97], v[66:69], v[94:97], 0
	v_mfma_f32_16x16x32_bf16 v[134:137], v[26:29], v[122:125], 0
	v_mfma_f32_16x16x32_bf16 v[138:141], v[50:53], v[122:125], 0
	v_mfma_f32_16x16x32_bf16 v[142:145], v[62:65], v[122:125], 0
	v_mfma_f32_16x16x32_bf16 v[122:125], v[66:69], v[122:125], 0
	v_mfma_f32_16x16x32_bf16 v[146:149], v[26:29], v[130:133], 0
	v_mfma_f32_16x16x32_bf16 v[150:153], v[50:53], v[130:133], 0
	v_mfma_f32_16x16x32_bf16 v[154:157], v[62:65], v[130:133], 0
	v_mfma_f32_16x16x32_bf16 v[130:133], v[66:69], v[130:133], 0
	v_mfma_f32_16x16x32_bf16 v[172:175], v[26:29], v[158:161], 0
	v_mfma_f32_16x16x32_bf16 v[176:179], v[50:53], v[158:161], 0
	v_mfma_f32_16x16x32_bf16 v[194:197], v[62:65], v[158:161], 0
	v_mfma_f32_16x16x32_bf16 v[158:161], v[66:69], v[158:161], 0
	v_mfma_f32_16x16x32_bf16 v[26:29], v[26:29], v[168:171], 0
	v_mfma_f32_16x16x32_bf16 v[50:53], v[50:53], v[168:171], 0
	v_mfma_f32_16x16x32_bf16 v[62:65], v[62:65], v[168:171], 0
	v_mfma_f32_16x16x32_bf16 v[66:69], v[66:69], v[168:171], 0
	ds_read_b128 v[168:171], v24 offset:1024
	ds_read_b128 v[198:201], v23 offset:33792
	ds_read_b128 v[202:205], v23 offset:35840
	ds_read_b128 v[206:209], v23 offset:37888
	ds_read_b128 v[210:213], v23 offset:39936
	s_waitcnt lgkmcnt(0)
	v_mfma_f32_16x16x32_bf16 v[54:57], v[198:201], v[168:171], v[54:57]
	v_mfma_f32_16x16x32_bf16 v[58:61], v[202:205], v[168:171], v[58:61]
	v_mfma_f32_16x16x32_bf16 v[70:73], v[206:209], v[168:171], v[70:73]
	v_mfma_f32_16x16x32_bf16 v[74:77], v[210:213], v[168:171], v[74:77]
	ds_read_b128 v[168:171], v16 offset:1024
	s_waitcnt lgkmcnt(0)
	v_mfma_f32_16x16x32_bf16 v[78:81], v[198:201], v[168:171], v[78:81]
	v_mfma_f32_16x16x32_bf16 v[82:85], v[202:205], v[168:171], v[82:85]
	v_mfma_f32_16x16x32_bf16 v[86:89], v[206:209], v[168:171], v[86:89]
	v_mfma_f32_16x16x32_bf16 v[46:49], v[210:213], v[168:171], v[46:49]
	ds_read_b128 v[168:171], v22 offset:1024
	s_waitcnt lgkmcnt(0)
	v_mfma_f32_16x16x32_bf16 v[98:101], v[198:201], v[168:171], v[98:101]
	v_mfma_f32_16x16x32_bf16 v[102:105], v[202:205], v[168:171], v[102:105]
	v_mfma_f32_16x16x32_bf16 v[106:109], v[206:209], v[168:171], v[106:109]
	v_mfma_f32_16x16x32_bf16 v[90:93], v[210:213], v[168:171], v[90:93]
	ds_read_b128 v[168:171], v19 offset:1024
	s_waitcnt lgkmcnt(0)
	v_mfma_f32_16x16x32_bf16 v[110:113], v[198:201], v[168:171], v[110:113]
	v_mfma_f32_16x16x32_bf16 v[114:117], v[202:205], v[168:171], v[114:117]
	v_mfma_f32_16x16x32_bf16 v[118:121], v[206:209], v[168:171], v[118:121]
	v_mfma_f32_16x16x32_bf16 v[94:97], v[210:213], v[168:171], v[94:97]
	ds_read_b128 v[168:171], v21 offset:1024
	s_waitcnt lgkmcnt(0)
	v_mfma_f32_16x16x32_bf16 v[134:137], v[198:201], v[168:171], v[134:137]
	v_mfma_f32_16x16x32_bf16 v[138:141], v[202:205], v[168:171], v[138:141]
	v_mfma_f32_16x16x32_bf16 v[142:145], v[206:209], v[168:171], v[142:145]
	v_mfma_f32_16x16x32_bf16 v[122:125], v[210:213], v[168:171], v[122:125]
	ds_read_b128 v[168:171], v18 offset:1024
	s_waitcnt lgkmcnt(0)
	v_mfma_f32_16x16x32_bf16 v[146:149], v[198:201], v[168:171], v[146:149]
	v_mfma_f32_16x16x32_bf16 v[150:153], v[202:205], v[168:171], v[150:153]
	v_mfma_f32_16x16x32_bf16 v[154:157], v[206:209], v[168:171], v[154:157]
	v_mfma_f32_16x16x32_bf16 v[168:171], v[210:213], v[168:171], v[130:133]
	s_nop 2
	ds_read_b128 v[130:133], v20 offset:1024
	s_waitcnt lgkmcnt(0)
	v_mfma_f32_16x16x32_bf16 v[172:175], v[198:201], v[130:133], v[172:175]
	v_mfma_f32_16x16x32_bf16 v[176:179], v[202:205], v[130:133], v[176:179]
	v_mfma_f32_16x16x32_bf16 v[194:197], v[206:209], v[130:133], v[194:197]
	v_mfma_f32_16x16x32_bf16 v[158:161], v[210:213], v[130:133], v[158:161]
	ds_read_b128 v[130:133], v17 offset:1024
	s_waitcnt lgkmcnt(0)
	v_mfma_f32_16x16x32_bf16 v[50:53], v[202:205], v[130:133], v[50:53]
	v_mfma_f32_16x16x32_bf16 v[62:65], v[206:209], v[130:133], v[62:65]
	v_mfma_f32_16x16x32_bf16 v[66:69], v[210:213], v[130:133], v[66:69]
	v_mfma_f32_16x16x32_bf16 v[198:201], v[198:201], v[130:133], v[26:29]
	s_mov_b32 m0, s2
	s_nop 1
	v_lshl_add_u64 v[26:27], v[0:1], 0, s[62:63]
	s_waitcnt vmcnt(0)
	s_waitcnt vmcnt(0)
	s_barrier
	global_load_lds_dwordx4 v[26:27], off
	v_lshl_add_u64 v[26:27], v[2:3], 0, s[62:63]
	s_mov_b32 m0, s1
	v_add_u32_e32 v127, s90, v127
	global_load_lds_dwordx4 v[26:27], off
	v_lshl_add_u64 v[26:27], v[4:5], 0, s[62:63]
	s_mov_b32 m0, s3
	s_nop 0
	global_load_lds_dwordx4 v[26:27], off
	v_lshl_add_u64 v[26:27], v[6:7], 0, s[62:63]
	s_mov_b32 m0, s9
	s_nop 0
	global_load_lds_dwordx4 v[26:27], off
	v_lshl_add_u64 v[26:27], v[8:9], 0, s[62:63]
	s_mov_b32 m0, s10
	s_nop 0
	global_load_lds_dwordx4 v[26:27], off
	v_lshl_add_u64 v[26:27], v[10:11], 0, s[62:63]
	s_mov_b32 m0, s11
	s_nop 0
	global_load_lds_dwordx4 v[26:27], off
	v_lshl_add_u64 v[26:27], v[12:13], 0, s[62:63]
	s_mov_b32 m0, s16
	s_nop 0
	global_load_lds_dwordx4 v[26:27], off
	v_lshl_add_u64 v[26:27], v[14:15], 0, s[62:63]
	s_mov_b32 m0, s24
	s_nop 0
	global_load_lds_dwordx4 v[26:27], off
	v_add3_u32 v26, s90, v25, v30
	ds_read_b128 v[28:31], v26
	v_add_u32_e32 v27, v127, v126
	ds_read_b128 v[130:133], v27
	v_add3_u32 v25, s41, v25, v162
	ds_read_b128 v[202:205], v25
	ds_read_b128 v[206:209], v25 offset:2048
	ds_read_b128 v[210:213], v25 offset:4096
	ds_read_b128 v[214:217], v25 offset:6144
	s_waitcnt lgkmcnt(0)
	v_mfma_f32_16x16x32_bf16 v[54:57], v[202:205], v[28:31], v[54:57]
	v_mfma_f32_16x16x32_bf16 v[58:61], v[206:209], v[28:31], v[58:61]
	v_mfma_f32_16x16x32_bf16 v[70:73], v[210:213], v[28:31], v[70:73]
	v_mfma_f32_16x16x32_bf16 v[74:77], v[214:217], v[28:31], v[74:77]
	v_add_u32_e32 v28, v127, v163
	v_add_u32_e32 v29, v127, v164
	v_add_u32_e32 v31, v127, v182
	v_mfma_f32_16x16x32_bf16 v[78:81], v[202:205], v[130:133], v[78:81]
	ds_read_b128 v[218:221], v31
	v_add_u32_e32 v30, v127, v180
	v_mfma_f32_16x16x32_bf16 v[82:85], v[206:209], v[130:133], v[82:85]
	v_mfma_f32_16x16x32_bf16 v[86:89], v[210:213], v[130:133], v[86:89]
	v_mfma_f32_16x16x32_bf16 v[46:49], v[214:217], v[130:133], v[46:49]
	ds_read_b128 v[130:133], v28
	s_waitcnt lgkmcnt(0)
	v_mfma_f32_16x16x32_bf16 v[98:101], v[202:205], v[130:133], v[98:101]
	v_mfma_f32_16x16x32_bf16 v[102:105], v[206:209], v[130:133], v[102:105]
	v_mfma_f32_16x16x32_bf16 v[106:109], v[210:213], v[130:133], v[106:109]
	v_mfma_f32_16x16x32_bf16 v[90:93], v[214:217], v[130:133], v[90:93]
	ds_read_b128 v[130:133], v29
	s_waitcnt lgkmcnt(0)
	v_mfma_f32_16x16x32_bf16 v[110:113], v[202:205], v[130:133], v[110:113]
	v_mfma_f32_16x16x32_bf16 v[114:117], v[206:209], v[130:133], v[114:117]
	v_mfma_f32_16x16x32_bf16 v[118:121], v[210:213], v[130:133], v[118:121]
	v_mfma_f32_16x16x32_bf16 v[94:97], v[214:217], v[130:133], v[94:97]
	ds_read_b128 v[130:133], v30
	s_waitcnt lgkmcnt(0)
	v_mfma_f32_16x16x32_bf16 v[134:137], v[202:205], v[130:133], v[134:137]
	v_mfma_f32_16x16x32_bf16 v[138:141], v[206:209], v[130:133], v[138:141]
	v_mfma_f32_16x16x32_bf16 v[142:145], v[210:213], v[130:133], v[142:145]
	v_mfma_f32_16x16x32_bf16 v[122:125], v[214:217], v[130:133], v[122:125]
	v_add_u32_e32 v130, v127, v183
	v_add_u32_e32 v131, v127, v193
	v_mfma_f32_16x16x32_bf16 v[146:149], v[202:205], v[218:221], v[146:149]
	v_mfma_f32_16x16x32_bf16 v[150:153], v[206:209], v[218:221], v[150:153]
	v_mfma_f32_16x16x32_bf16 v[154:157], v[210:213], v[218:221], v[154:157]
	v_mfma_f32_16x16x32_bf16 v[168:171], v[214:217], v[218:221], v[168:171]
	ds_read_b128 v[218:221], v130
	s_waitcnt lgkmcnt(0)
	v_mfma_f32_16x16x32_bf16 v[172:175], v[202:205], v[218:221], v[172:175]
	v_mfma_f32_16x16x32_bf16 v[176:179], v[206:209], v[218:221], v[176:179]
	v_mfma_f32_16x16x32_bf16 v[194:197], v[210:213], v[218:221], v[194:197]
	v_mfma_f32_16x16x32_bf16 v[158:161], v[214:217], v[218:221], v[158:161]
	ds_read_b128 v[218:221], v131
	s_waitcnt lgkmcnt(0)
	v_mfma_f32_16x16x32_bf16 v[50:53], v[206:209], v[218:221], v[50:53]
	v_mfma_f32_16x16x32_bf16 v[62:65], v[210:213], v[218:221], v[62:65]
	v_mfma_f32_16x16x32_bf16 v[66:69], v[214:217], v[218:221], v[66:69]
	v_mfma_f32_16x16x32_bf16 v[198:201], v[202:205], v[218:221], v[198:201]
	ds_read_b128 v[202:205], v26 offset:1024
	ds_read_b128 v[206:209], v25 offset:1024
	ds_read_b128 v[210:213], v25 offset:3072
	ds_read_b128 v[214:217], v25 offset:5120
	ds_read_b128 v[218:221], v25 offset:7168
	s_waitcnt lgkmcnt(0)
	v_mfma_f32_16x16x32_bf16 v[54:57], v[206:209], v[202:205], v[54:57]
	v_mfma_f32_16x16x32_bf16 v[58:61], v[210:213], v[202:205], v[58:61]
	v_mfma_f32_16x16x32_bf16 v[70:73], v[214:217], v[202:205], v[70:73]
	v_mfma_f32_16x16x32_bf16 v[74:77], v[218:221], v[202:205], v[74:77]
	ds_read_b128 v[202:205], v27 offset:1024
	s_waitcnt lgkmcnt(0)
	v_mfma_f32_16x16x32_bf16 v[78:81], v[206:209], v[202:205], v[78:81]
	v_mfma_f32_16x16x32_bf16 v[82:85], v[210:213], v[202:205], v[82:85]
	v_mfma_f32_16x16x32_bf16 v[86:89], v[214:217], v[202:205], v[86:89]
	v_mfma_f32_16x16x32_bf16 v[46:49], v[218:221], v[202:205], v[46:49]
	ds_read_b128 v[202:205], v28 offset:1024
	s_waitcnt lgkmcnt(0)
	v_mfma_f32_16x16x32_bf16 v[98:101], v[206:209], v[202:205], v[98:101]
	v_mfma_f32_16x16x32_bf16 v[102:105], v[210:213], v[202:205], v[102:105]
	v_mfma_f32_16x16x32_bf16 v[106:109], v[214:217], v[202:205], v[106:109]
	v_mfma_f32_16x16x32_bf16 v[90:93], v[218:221], v[202:205], v[90:93]
	ds_read_b128 v[202:205], v29 offset:1024
	s_waitcnt lgkmcnt(0)
	v_mfma_f32_16x16x32_bf16 v[110:113], v[206:209], v[202:205], v[110:113]
	v_mfma_f32_16x16x32_bf16 v[114:117], v[210:213], v[202:205], v[114:117]
	v_mfma_f32_16x16x32_bf16 v[118:121], v[214:217], v[202:205], v[118:121]
	v_mfma_f32_16x16x32_bf16 v[94:97], v[218:221], v[202:205], v[94:97]
	ds_read_b128 v[202:205], v30 offset:1024
	s_waitcnt lgkmcnt(0)
	v_mfma_f32_16x16x32_bf16 v[132:135], v[206:209], v[202:205], v[134:137]
	v_mfma_f32_16x16x32_bf16 v[136:139], v[210:213], v[202:205], v[138:141]
	v_mfma_f32_16x16x32_bf16 v[140:143], v[214:217], v[202:205], v[142:145]
	v_mfma_f32_16x16x32_bf16 v[122:125], v[218:221], v[202:205], v[122:125]
	ds_read_b128 v[202:205], v31 offset:1024
	s_waitcnt lgkmcnt(0)
	v_mfma_f32_16x16x32_bf16 v[144:147], v[206:209], v[202:205], v[146:149]
	v_mfma_f32_16x16x32_bf16 v[148:151], v[210:213], v[202:205], v[150:153]
	v_mfma_f32_16x16x32_bf16 v[152:155], v[214:217], v[202:205], v[154:157]
	v_mfma_f32_16x16x32_bf16 v[168:171], v[218:221], v[202:205], v[168:171]
	ds_read_b128 v[202:205], v130 offset:1024
	s_waitcnt lgkmcnt(0)
	v_mfma_f32_16x16x32_bf16 v[156:159], v[218:221], v[202:205], v[158:161]
	s_nop 2
	ds_read_b128 v[160:163], v131 offset:1024
	s_waitcnt lgkmcnt(0)
	v_mfma_f32_16x16x32_bf16 v[50:53], v[210:213], v[160:163], v[50:53]
	v_mfma_f32_16x16x32_bf16 v[62:65], v[214:217], v[160:163], v[62:65]
	v_mfma_f32_16x16x32_bf16 v[66:69], v[218:221], v[160:163], v[66:69]
	v_mfma_f32_16x16x32_bf16 v[172:175], v[206:209], v[202:205], v[172:175]
	v_mfma_f32_16x16x32_bf16 v[176:179], v[210:213], v[202:205], v[176:179]
	v_mfma_f32_16x16x32_bf16 v[194:197], v[214:217], v[202:205], v[194:197]
	v_mfma_f32_16x16x32_bf16 v[198:201], v[206:209], v[160:163], v[198:201]
	s_mov_b32 m0, s34
	v_lshl_add_u64 v[126:127], v[0:1], 0, s[6:7]
	s_waitcnt vmcnt(0)
	s_waitcnt vmcnt(0)
	s_barrier
	global_load_lds_dwordx4 v[126:127], off
	v_lshl_add_u64 v[126:127], v[2:3], 0, s[6:7]
	s_mov_b32 m0, s25
	s_nop 0
	global_load_lds_dwordx4 v[126:127], off
	v_lshl_add_u64 v[126:127], v[4:5], 0, s[6:7]
	s_mov_b32 m0, s26
	s_nop 0
	global_load_lds_dwordx4 v[126:127], off
	v_lshl_add_u64 v[126:127], v[6:7], 0, s[6:7]
	s_mov_b32 m0, s27
	s_nop 0
	global_load_lds_dwordx4 v[126:127], off
	v_lshl_add_u64 v[126:127], v[8:9], 0, s[6:7]
	s_mov_b32 m0, s35
	s_nop 0
	global_load_lds_dwordx4 v[126:127], off
	v_lshl_add_u64 v[126:127], v[10:11], 0, s[6:7]
	s_mov_b32 m0, s36
	s_nop 0
	global_load_lds_dwordx4 v[126:127], off
	v_lshl_add_u64 v[126:127], v[12:13], 0, s[6:7]
	s_mov_b32 m0, s37
	s_nop 0
	global_load_lds_dwordx4 v[126:127], off
	v_lshl_add_u64 v[126:127], v[14:15], 0, s[6:7]
	s_mov_b32 m0, s40
	s_nop 0
	global_load_lds_dwordx4 v[126:127], off
	ds_read_b128 v[160:163], v24
	ds_read_b128 v[202:205], v23 offset:32768
	ds_read_b128 v[206:209], v23 offset:34816
	ds_read_b128 v[210:213], v23 offset:36864
	ds_read_b128 v[214:217], v23 offset:38912
	s_waitcnt lgkmcnt(0)
	v_mfma_f32_16x16x32_bf16 v[54:57], v[202:205], v[160:163], v[54:57]
	v_mfma_f32_16x16x32_bf16 v[58:61], v[206:209], v[160:163], v[58:61]
	v_mfma_f32_16x16x32_bf16 v[70:73], v[210:213], v[160:163], v[70:73]
	v_mfma_f32_16x16x32_bf16 v[74:77], v[214:217], v[160:163], v[74:77]
	ds_read_b128 v[160:163], v16
	s_waitcnt lgkmcnt(0)
	v_mfma_f32_16x16x32_bf16 v[78:81], v[202:205], v[160:163], v[78:81]
	v_mfma_f32_16x16x32_bf16 v[82:85], v[206:209], v[160:163], v[82:85]
	v_mfma_f32_16x16x32_bf16 v[86:89], v[210:213], v[160:163], v[86:89]
	v_mfma_f32_16x16x32_bf16 v[46:49], v[214:217], v[160:163], v[46:49]
	ds_read_b128 v[160:163], v22
	s_waitcnt lgkmcnt(0)
	v_mfma_f32_16x16x32_bf16 v[98:101], v[202:205], v[160:163], v[98:101]
	v_mfma_f32_16x16x32_bf16 v[102:105], v[206:209], v[160:163], v[102:105]
	v_mfma_f32_16x16x32_bf16 v[106:109], v[210:213], v[160:163], v[106:109]
	v_mfma_f32_16x16x32_bf16 v[90:93], v[214:217], v[160:163], v[90:93]
	ds_read_b128 v[160:163], v19
	s_waitcnt lgkmcnt(0)
	v_mfma_f32_16x16x32_bf16 v[110:113], v[202:205], v[160:163], v[110:113]
	v_mfma_f32_16x16x32_bf16 v[114:117], v[206:209], v[160:163], v[114:117]
	v_mfma_f32_16x16x32_bf16 v[118:121], v[210:213], v[160:163], v[118:121]
	v_mfma_f32_16x16x32_bf16 v[94:97], v[214:217], v[160:163], v[94:97]
	ds_read_b128 v[160:163], v21
	s_waitcnt lgkmcnt(0)
	v_mfma_f32_16x16x32_bf16 v[132:135], v[202:205], v[160:163], v[132:135]
	v_mfma_f32_16x16x32_bf16 v[136:139], v[206:209], v[160:163], v[136:139]
	v_mfma_f32_16x16x32_bf16 v[140:143], v[210:213], v[160:163], v[140:143]
	v_mfma_f32_16x16x32_bf16 v[122:125], v[214:217], v[160:163], v[122:125]
	ds_read_b128 v[160:163], v18
	s_waitcnt lgkmcnt(0)
	v_mfma_f32_16x16x32_bf16 v[144:147], v[202:205], v[160:163], v[144:147]
	v_mfma_f32_16x16x32_bf16 v[148:151], v[206:209], v[160:163], v[148:151]
	v_mfma_f32_16x16x32_bf16 v[152:155], v[210:213], v[160:163], v[152:155]
	v_mfma_f32_16x16x32_bf16 v[160:163], v[214:217], v[160:163], v[168:171]
	s_nop 2
	ds_read_b128 v[168:171], v20
	s_waitcnt lgkmcnt(0)
	v_mfma_f32_16x16x32_bf16 v[172:175], v[202:205], v[168:171], v[172:175]
	v_mfma_f32_16x16x32_bf16 v[176:179], v[206:209], v[168:171], v[176:179]
	v_mfma_f32_16x16x32_bf16 v[194:197], v[210:213], v[168:171], v[194:197]
	v_mfma_f32_16x16x32_bf16 v[156:159], v[214:217], v[168:171], v[156:159]
	ds_read_b128 v[168:171], v17
	s_waitcnt lgkmcnt(0)
	v_mfma_f32_16x16x32_bf16 v[50:53], v[206:209], v[168:171], v[50:53]
	v_mfma_f32_16x16x32_bf16 v[62:65], v[210:213], v[168:171], v[62:65]
	v_mfma_f32_16x16x32_bf16 v[66:69], v[214:217], v[168:171], v[66:69]
	v_mfma_f32_16x16x32_bf16 v[198:201], v[202:205], v[168:171], v[198:201]
	ds_read_b128 v[168:171], v24 offset:1024
	ds_read_b128 v[202:205], v23 offset:33792
	ds_read_b128 v[206:209], v23 offset:35840
	ds_read_b128 v[210:213], v23 offset:37888
	ds_read_b128 v[214:217], v23 offset:39936
	s_waitcnt lgkmcnt(0)
	v_mfma_f32_16x16x32_bf16 v[54:57], v[202:205], v[168:171], v[54:57]
	v_mfma_f32_16x16x32_bf16 v[58:61], v[206:209], v[168:171], v[58:61]
	v_mfma_f32_16x16x32_bf16 v[70:73], v[210:213], v[168:171], v[70:73]
	v_mfma_f32_16x16x32_bf16 v[74:77], v[214:217], v[168:171], v[74:77]
	ds_read_b128 v[168:171], v16 offset:1024
	s_waitcnt lgkmcnt(0)
	v_mfma_f32_16x16x32_bf16 v[78:81], v[202:205], v[168:171], v[78:81]
	v_mfma_f32_16x16x32_bf16 v[82:85], v[206:209], v[168:171], v[82:85]
	v_mfma_f32_16x16x32_bf16 v[86:89], v[210:213], v[168:171], v[86:89]
	v_mfma_f32_16x16x32_bf16 v[46:49], v[214:217], v[168:171], v[46:49]
	ds_read_b128 v[168:171], v22 offset:1024
	s_waitcnt lgkmcnt(0)
	v_mfma_f32_16x16x32_bf16 v[98:101], v[202:205], v[168:171], v[98:101]
	v_mfma_f32_16x16x32_bf16 v[102:105], v[206:209], v[168:171], v[102:105]
	v_mfma_f32_16x16x32_bf16 v[106:109], v[210:213], v[168:171], v[106:109]
	v_mfma_f32_16x16x32_bf16 v[90:93], v[214:217], v[168:171], v[90:93]
	ds_read_b128 v[168:171], v19 offset:1024
	s_waitcnt lgkmcnt(0)
	v_mfma_f32_16x16x32_bf16 v[110:113], v[202:205], v[168:171], v[110:113]
	v_mfma_f32_16x16x32_bf16 v[114:117], v[206:209], v[168:171], v[114:117]
	v_mfma_f32_16x16x32_bf16 v[118:121], v[210:213], v[168:171], v[118:121]
	v_mfma_f32_16x16x32_bf16 v[94:97], v[214:217], v[168:171], v[94:97]
	ds_read_b128 v[168:171], v21 offset:1024
	s_waitcnt lgkmcnt(0)
	v_mfma_f32_16x16x32_bf16 v[132:135], v[202:205], v[168:171], v[132:135]
	v_mfma_f32_16x16x32_bf16 v[136:139], v[206:209], v[168:171], v[136:139]
	v_mfma_f32_16x16x32_bf16 v[140:143], v[210:213], v[168:171], v[140:143]
	v_mfma_f32_16x16x32_bf16 v[122:125], v[214:217], v[168:171], v[122:125]
	ds_read_b128 v[168:171], v18 offset:1024
	s_waitcnt lgkmcnt(0)
	v_mfma_f32_16x16x32_bf16 v[144:147], v[202:205], v[168:171], v[144:147]
	v_mfma_f32_16x16x32_bf16 v[148:151], v[206:209], v[168:171], v[148:151]
	v_mfma_f32_16x16x32_bf16 v[152:155], v[210:213], v[168:171], v[152:155]
	v_mfma_f32_16x16x32_bf16 v[160:163], v[214:217], v[168:171], v[160:163]
	ds_read_b128 v[168:171], v20 offset:1024
	s_waitcnt lgkmcnt(0)
	v_mfma_f32_16x16x32_bf16 v[172:175], v[202:205], v[168:171], v[172:175]
	v_mfma_f32_16x16x32_bf16 v[176:179], v[206:209], v[168:171], v[176:179]
	v_mfma_f32_16x16x32_bf16 v[194:197], v[210:213], v[168:171], v[194:197]
	v_mfma_f32_16x16x32_bf16 v[156:159], v[214:217], v[168:171], v[156:159]
	ds_read_b128 v[168:171], v17 offset:1024
	s_waitcnt lgkmcnt(0)
	v_mfma_f32_16x16x32_bf16 v[50:53], v[206:209], v[168:171], v[50:53]
	v_mfma_f32_16x16x32_bf16 v[62:65], v[210:213], v[168:171], v[62:65]
	v_mfma_f32_16x16x32_bf16 v[66:69], v[214:217], v[168:171], v[66:69]
	v_mfma_f32_16x16x32_bf16 v[198:201], v[202:205], v[168:171], v[198:201]
	s_mov_b64 s[26:27], 0x200
	s_mov_b32 m0, s2
	v_lshl_add_u64 v[126:127], v[0:1], 0, s[26:27]
	s_waitcnt vmcnt(0)
	s_waitcnt vmcnt(0)
	s_barrier
	global_load_lds_dwordx4 v[126:127], off
	v_lshl_add_u64 v[126:127], v[2:3], 0, s[26:27]
	s_mov_b32 m0, s1
	s_nop 0
	global_load_lds_dwordx4 v[126:127], off
	v_lshl_add_u64 v[126:127], v[4:5], 0, s[26:27]
	s_mov_b32 m0, s3
	s_nop 0
	global_load_lds_dwordx4 v[126:127], off
	v_lshl_add_u64 v[126:127], v[6:7], 0, s[26:27]
	s_mov_b32 m0, s9
	s_nop 0
	global_load_lds_dwordx4 v[126:127], off
	v_lshl_add_u64 v[126:127], v[8:9], 0, s[26:27]
	s_mov_b32 m0, s10
	s_nop 0
	global_load_lds_dwordx4 v[126:127], off
	v_lshl_add_u64 v[126:127], v[10:11], 0, s[26:27]
	s_mov_b32 m0, s11
	s_nop 0
	global_load_lds_dwordx4 v[126:127], off
	v_lshl_add_u64 v[126:127], v[12:13], 0, s[26:27]
	s_mov_b32 m0, s16
	s_nop 0
	global_load_lds_dwordx4 v[126:127], off
	v_lshl_add_u64 v[126:127], v[14:15], 0, s[26:27]
	s_mov_b32 m0, s24
	s_nop 0
	global_load_lds_dwordx4 v[126:127], off
	ds_read_b128 v[168:171], v26
	ds_read_b128 v[202:205], v25
	ds_read_b128 v[206:209], v25 offset:2048
	ds_read_b128 v[210:213], v25 offset:4096
	ds_read_b128 v[214:217], v25 offset:6144
	s_waitcnt lgkmcnt(0)
	v_mfma_f32_16x16x32_bf16 v[54:57], v[202:205], v[168:171], v[54:57]
	v_mfma_f32_16x16x32_bf16 v[58:61], v[206:209], v[168:171], v[58:61]
	v_mfma_f32_16x16x32_bf16 v[70:73], v[210:213], v[168:171], v[70:73]
	v_mfma_f32_16x16x32_bf16 v[74:77], v[214:217], v[168:171], v[74:77]
	ds_read_b128 v[168:171], v27
	s_waitcnt lgkmcnt(0)
	v_mfma_f32_16x16x32_bf16 v[78:81], v[202:205], v[168:171], v[78:81]
	v_mfma_f32_16x16x32_bf16 v[82:85], v[206:209], v[168:171], v[82:85]
	v_mfma_f32_16x16x32_bf16 v[86:89], v[210:213], v[168:171], v[86:89]
	v_mfma_f32_16x16x32_bf16 v[46:49], v[214:217], v[168:171], v[46:49]
	ds_read_b128 v[168:171], v28
	s_waitcnt lgkmcnt(0)
	v_mfma_f32_16x16x32_bf16 v[98:101], v[202:205], v[168:171], v[98:101]
	v_mfma_f32_16x16x32_bf16 v[102:105], v[206:209], v[168:171], v[102:105]
	v_mfma_f32_16x16x32_bf16 v[106:109], v[210:213], v[168:171], v[106:109]
	v_mfma_f32_16x16x32_bf16 v[90:93], v[214:217], v[168:171], v[90:93]
	ds_read_b128 v[168:171], v29
	s_waitcnt lgkmcnt(0)
	v_mfma_f32_16x16x32_bf16 v[110:113], v[202:205], v[168:171], v[110:113]
	v_mfma_f32_16x16x32_bf16 v[114:117], v[206:209], v[168:171], v[114:117]
	v_mfma_f32_16x16x32_bf16 v[118:121], v[210:213], v[168:171], v[118:121]
	v_mfma_f32_16x16x32_bf16 v[94:97], v[214:217], v[168:171], v[94:97]
	ds_read_b128 v[168:171], v30
	s_waitcnt lgkmcnt(0)
	v_mfma_f32_16x16x32_bf16 v[132:135], v[202:205], v[168:171], v[132:135]
	v_mfma_f32_16x16x32_bf16 v[136:139], v[206:209], v[168:171], v[136:139]
	v_mfma_f32_16x16x32_bf16 v[140:143], v[210:213], v[168:171], v[140:143]
	v_mfma_f32_16x16x32_bf16 v[122:125], v[214:217], v[168:171], v[122:125]
	ds_read_b128 v[168:171], v31
	s_waitcnt lgkmcnt(0)
	v_mfma_f32_16x16x32_bf16 v[144:147], v[202:205], v[168:171], v[144:147]
	v_mfma_f32_16x16x32_bf16 v[148:151], v[206:209], v[168:171], v[148:151]
	v_mfma_f32_16x16x32_bf16 v[152:155], v[210:213], v[168:171], v[152:155]
	v_mfma_f32_16x16x32_bf16 v[160:163], v[214:217], v[168:171], v[160:163]
	ds_read_b128 v[168:171], v130
	s_waitcnt lgkmcnt(0)
	v_mfma_f32_16x16x32_bf16 v[172:175], v[202:205], v[168:171], v[172:175]
	v_mfma_f32_16x16x32_bf16 v[176:179], v[206:209], v[168:171], v[176:179]
	v_mfma_f32_16x16x32_bf16 v[194:197], v[210:213], v[168:171], v[194:197]
	v_mfma_f32_16x16x32_bf16 v[156:159], v[214:217], v[168:171], v[156:159]
	ds_read_b128 v[168:171], v131
	s_waitcnt lgkmcnt(0)
	v_mfma_f32_16x16x32_bf16 v[50:53], v[206:209], v[168:171], v[50:53]
	v_mfma_f32_16x16x32_bf16 v[62:65], v[210:213], v[168:171], v[62:65]
	v_mfma_f32_16x16x32_bf16 v[66:69], v[214:217], v[168:171], v[66:69]
	v_mfma_f32_16x16x32_bf16 v[198:201], v[202:205], v[168:171], v[198:201]
	ds_read_b128 v[168:171], v26 offset:1024
	ds_read_b128 v[202:205], v25 offset:1024
	ds_read_b128 v[206:209], v25 offset:3072
	ds_read_b128 v[210:213], v25 offset:5120
	ds_read_b128 v[214:217], v25 offset:7168
	s_waitcnt lgkmcnt(0)
	v_mfma_f32_16x16x32_bf16 v[54:57], v[202:205], v[168:171], v[54:57]
	v_mfma_f32_16x16x32_bf16 v[58:61], v[206:209], v[168:171], v[58:61]
	v_mfma_f32_16x16x32_bf16 v[70:73], v[210:213], v[168:171], v[70:73]
	v_mfma_f32_16x16x32_bf16 v[74:77], v[214:217], v[168:171], v[74:77]
	ds_read_b128 v[168:171], v27 offset:1024
	s_waitcnt lgkmcnt(0)
	v_mfma_f32_16x16x32_bf16 v[78:81], v[202:205], v[168:171], v[78:81]
	v_mfma_f32_16x16x32_bf16 v[82:85], v[206:209], v[168:171], v[82:85]
	v_mfma_f32_16x16x32_bf16 v[86:89], v[210:213], v[168:171], v[86:89]
	v_mfma_f32_16x16x32_bf16 v[46:49], v[214:217], v[168:171], v[46:49]
	ds_read_b128 v[168:171], v28 offset:1024
	s_waitcnt lgkmcnt(0)
	v_mfma_f32_16x16x32_bf16 v[98:101], v[202:205], v[168:171], v[98:101]
	v_mfma_f32_16x16x32_bf16 v[102:105], v[206:209], v[168:171], v[102:105]
	v_mfma_f32_16x16x32_bf16 v[106:109], v[210:213], v[168:171], v[106:109]
	v_mfma_f32_16x16x32_bf16 v[90:93], v[214:217], v[168:171], v[90:93]
	ds_read_b128 v[168:171], v29 offset:1024
	s_waitcnt lgkmcnt(0)
	v_mfma_f32_16x16x32_bf16 v[110:113], v[202:205], v[168:171], v[110:113]
	v_mfma_f32_16x16x32_bf16 v[114:117], v[206:209], v[168:171], v[114:117]
	v_mfma_f32_16x16x32_bf16 v[118:121], v[210:213], v[168:171], v[118:121]
	v_mfma_f32_16x16x32_bf16 v[94:97], v[214:217], v[168:171], v[94:97]
	ds_read_b128 v[168:171], v30 offset:1024
	s_waitcnt lgkmcnt(0)
	v_mfma_f32_16x16x32_bf16 v[132:135], v[202:205], v[168:171], v[132:135]
	v_mfma_f32_16x16x32_bf16 v[136:139], v[206:209], v[168:171], v[136:139]
	v_mfma_f32_16x16x32_bf16 v[140:143], v[210:213], v[168:171], v[140:143]
	v_mfma_f32_16x16x32_bf16 v[122:125], v[214:217], v[168:171], v[122:125]
	ds_read_b128 v[168:171], v31 offset:1024
	s_waitcnt lgkmcnt(0)
	v_mfma_f32_16x16x32_bf16 v[144:147], v[202:205], v[168:171], v[144:147]
	v_mfma_f32_16x16x32_bf16 v[148:151], v[206:209], v[168:171], v[148:151]
	v_mfma_f32_16x16x32_bf16 v[152:155], v[210:213], v[168:171], v[152:155]
	v_mfma_f32_16x16x32_bf16 v[160:163], v[214:217], v[168:171], v[160:163]
	ds_read_b128 v[168:171], v130 offset:1024
	s_waitcnt lgkmcnt(0)
	v_mfma_f32_16x16x32_bf16 v[172:175], v[202:205], v[168:171], v[172:175]
	v_mfma_f32_16x16x32_bf16 v[176:179], v[206:209], v[168:171], v[176:179]
	v_mfma_f32_16x16x32_bf16 v[194:197], v[210:213], v[168:171], v[194:197]
	v_mfma_f32_16x16x32_bf16 v[156:159], v[214:217], v[168:171], v[156:159]
	ds_read_b128 v[168:171], v131 offset:1024
	s_waitcnt lgkmcnt(0)
	v_mfma_f32_16x16x32_bf16 v[50:53], v[206:209], v[168:171], v[50:53]
	v_mfma_f32_16x16x32_bf16 v[62:65], v[210:213], v[168:171], v[62:65]
	v_mfma_f32_16x16x32_bf16 v[66:69], v[214:217], v[168:171], v[66:69]
	v_mfma_f32_16x16x32_bf16 v[198:201], v[202:205], v[168:171], v[198:201]
	s_mov_b64 s[26:27], 0x280
	v_readfirstlane_b32 s25, v39
	v_lshl_add_u64 v[126:127], v[0:1], 0, s[26:27]
	s_mov_b32 m0, s25
	v_readfirstlane_b32 s3, v38
	s_waitcnt vmcnt(0)
	s_waitcnt vmcnt(0)
	s_barrier
	global_load_lds_dwordx4 v[126:127], off
	v_lshl_add_u64 v[126:127], v[2:3], 0, s[26:27]
	s_mov_b32 m0, s3
	v_readfirstlane_b32 s9, v40
	global_load_lds_dwordx4 v[126:127], off
	v_lshl_add_u64 v[38:39], v[4:5], 0, s[26:27]
	s_mov_b32 m0, s9
	v_readfirstlane_b32 s10, v41
	global_load_lds_dwordx4 v[38:39], off
	v_lshl_add_u64 v[38:39], v[6:7], 0, s[26:27]
	s_mov_b32 m0, s10
	v_readfirstlane_b32 s11, v42
	global_load_lds_dwordx4 v[38:39], off
	v_lshl_add_u64 v[38:39], v[8:9], 0, s[26:27]
	s_mov_b32 m0, s11
	v_readfirstlane_b32 s16, v43
	global_load_lds_dwordx4 v[38:39], off
	v_lshl_add_u64 v[38:39], v[10:11], 0, s[26:27]
	s_mov_b32 m0, s16
	v_readfirstlane_b32 s24, v44
	global_load_lds_dwordx4 v[38:39], off
	v_lshl_add_u64 v[38:39], v[12:13], 0, s[26:27]
	s_mov_b32 m0, s24
	s_nop 0
	global_load_lds_dwordx4 v[38:39], off
	v_lshl_add_u64 v[38:39], v[14:15], 0, s[26:27]
	v_readfirstlane_b32 s26, v45
	s_mov_b32 m0, s26
	s_nop 0
	global_load_lds_dwordx4 v[38:39], off
	ds_read_b128 v[38:41], v24
	ds_read_b128 v[42:45], v23 offset:32768
	ds_read_b128 v[168:171], v23 offset:34816
	ds_read_b128 v[202:205], v23 offset:36864
	ds_read_b128 v[206:209], v23 offset:38912
	s_waitcnt lgkmcnt(0)
	v_mfma_f32_16x16x32_bf16 v[54:57], v[42:45], v[38:41], v[54:57]
	v_mfma_f32_16x16x32_bf16 v[58:61], v[168:171], v[38:41], v[58:61]
	v_mfma_f32_16x16x32_bf16 v[70:73], v[202:205], v[38:41], v[70:73]
	v_mfma_f32_16x16x32_bf16 v[38:41], v[206:209], v[38:41], v[74:77]
	s_nop 2
	ds_read_b128 v[74:77], v16
	s_waitcnt lgkmcnt(0)
	v_mfma_f32_16x16x32_bf16 v[78:81], v[42:45], v[74:77], v[78:81]
	v_mfma_f32_16x16x32_bf16 v[82:85], v[168:171], v[74:77], v[82:85]
	v_mfma_f32_16x16x32_bf16 v[86:89], v[202:205], v[74:77], v[86:89]
	v_mfma_f32_16x16x32_bf16 v[46:49], v[206:209], v[74:77], v[46:49]
	ds_read_b128 v[74:77], v22
	s_waitcnt lgkmcnt(0)
	v_mfma_f32_16x16x32_bf16 v[98:101], v[42:45], v[74:77], v[98:101]
	v_mfma_f32_16x16x32_bf16 v[102:105], v[168:171], v[74:77], v[102:105]
	v_mfma_f32_16x16x32_bf16 v[106:109], v[202:205], v[74:77], v[106:109]
	v_mfma_f32_16x16x32_bf16 v[74:77], v[206:209], v[74:77], v[90:93]
	s_nop 2
	ds_read_b128 v[90:93], v19
	s_waitcnt lgkmcnt(0)
	v_mfma_f32_16x16x32_bf16 v[110:113], v[42:45], v[90:93], v[110:113]
	v_mfma_f32_16x16x32_bf16 v[114:117], v[168:171], v[90:93], v[114:117]
	v_mfma_f32_16x16x32_bf16 v[118:121], v[202:205], v[90:93], v[118:121]
	v_mfma_f32_16x16x32_bf16 v[90:93], v[206:209], v[90:93], v[94:97]
	s_nop 2
	ds_read_b128 v[94:97], v21
	s_waitcnt lgkmcnt(0)
	v_mfma_f32_16x16x32_bf16 v[132:135], v[42:45], v[94:97], v[132:135]
	v_mfma_f32_16x16x32_bf16 v[136:139], v[168:171], v[94:97], v[136:139]
	v_mfma_f32_16x16x32_bf16 v[140:143], v[202:205], v[94:97], v[140:143]
	v_mfma_f32_16x16x32_bf16 v[94:97], v[206:209], v[94:97], v[122:125]
	s_nop 2
	ds_read_b128 v[122:125], v18
	s_waitcnt lgkmcnt(0)
	v_mfma_f32_16x16x32_bf16 v[144:147], v[42:45], v[122:125], v[144:147]
	v_mfma_f32_16x16x32_bf16 v[148:151], v[168:171], v[122:125], v[148:151]
	v_mfma_f32_16x16x32_bf16 v[152:155], v[202:205], v[122:125], v[152:155]
	v_mfma_f32_16x16x32_bf16 v[122:125], v[206:209], v[122:125], v[160:163]
	s_nop 2
	ds_read_b128 v[160:163], v20
	s_waitcnt lgkmcnt(0)
	v_mfma_f32_16x16x32_bf16 v[172:175], v[42:45], v[160:163], v[172:175]
	v_mfma_f32_16x16x32_bf16 v[176:179], v[168:171], v[160:163], v[176:179]
	v_mfma_f32_16x16x32_bf16 v[194:197], v[202:205], v[160:163], v[194:197]
	v_mfma_f32_16x16x32_bf16 v[156:159], v[206:209], v[160:163], v[156:159]
	ds_read_b128 v[160:163], v17
	s_waitcnt lgkmcnt(0)
	v_mfma_f32_16x16x32_bf16 v[42:45], v[42:45], v[160:163], v[198:201]
	v_mfma_f32_16x16x32_bf16 v[50:53], v[168:171], v[160:163], v[50:53]
	v_mfma_f32_16x16x32_bf16 v[62:65], v[202:205], v[160:163], v[62:65]
	v_mfma_f32_16x16x32_bf16 v[66:69], v[206:209], v[160:163], v[66:69]
	ds_read_b128 v[160:163], v24 offset:1024
	ds_read_b128 v[168:171], v23 offset:33792
	ds_read_b128 v[198:201], v23 offset:35840
	ds_read_b128 v[202:205], v23 offset:37888
	ds_read_b128 v[206:209], v23 offset:39936
	s_waitcnt lgkmcnt(0)
	v_mfma_f32_16x16x32_bf16 v[54:57], v[168:171], v[160:163], v[54:57]
	v_mfma_f32_16x16x32_bf16 v[58:61], v[198:201], v[160:163], v[58:61]
	v_mfma_f32_16x16x32_bf16 v[70:73], v[202:205], v[160:163], v[70:73]
	v_mfma_f32_16x16x32_bf16 v[38:41], v[206:209], v[160:163], v[38:41]
	ds_read_b128 v[160:163], v16 offset:1024
	s_waitcnt lgkmcnt(0)
	v_mfma_f32_16x16x32_bf16 v[78:81], v[168:171], v[160:163], v[78:81]
	v_mfma_f32_16x16x32_bf16 v[82:85], v[198:201], v[160:163], v[82:85]
	v_mfma_f32_16x16x32_bf16 v[86:89], v[202:205], v[160:163], v[86:89]
	v_mfma_f32_16x16x32_bf16 v[46:49], v[206:209], v[160:163], v[46:49]
	ds_read_b128 v[160:163], v22 offset:1024
	s_waitcnt lgkmcnt(0)
	v_mfma_f32_16x16x32_bf16 v[98:101], v[168:171], v[160:163], v[98:101]
	v_mfma_f32_16x16x32_bf16 v[102:105], v[198:201], v[160:163], v[102:105]
	v_mfma_f32_16x16x32_bf16 v[106:109], v[202:205], v[160:163], v[106:109]
	v_mfma_f32_16x16x32_bf16 v[74:77], v[206:209], v[160:163], v[74:77]
	ds_read_b128 v[160:163], v19 offset:1024
	s_waitcnt lgkmcnt(0)
	v_mfma_f32_16x16x32_bf16 v[110:113], v[168:171], v[160:163], v[110:113]
	v_mfma_f32_16x16x32_bf16 v[114:117], v[198:201], v[160:163], v[114:117]
	v_mfma_f32_16x16x32_bf16 v[118:121], v[202:205], v[160:163], v[118:121]
	v_mfma_f32_16x16x32_bf16 v[90:93], v[206:209], v[160:163], v[90:93]
	ds_read_b128 v[160:163], v21 offset:1024
	s_waitcnt lgkmcnt(0)
	v_mfma_f32_16x16x32_bf16 v[132:135], v[168:171], v[160:163], v[132:135]
	v_mfma_f32_16x16x32_bf16 v[136:139], v[198:201], v[160:163], v[136:139]
	v_mfma_f32_16x16x32_bf16 v[140:143], v[202:205], v[160:163], v[140:143]
	v_mfma_f32_16x16x32_bf16 v[94:97], v[206:209], v[160:163], v[94:97]
	ds_read_b128 v[160:163], v18 offset:1024
	s_waitcnt lgkmcnt(0)
	v_mfma_f32_16x16x32_bf16 v[144:147], v[168:171], v[160:163], v[144:147]
	v_mfma_f32_16x16x32_bf16 v[148:151], v[198:201], v[160:163], v[148:151]
	v_mfma_f32_16x16x32_bf16 v[152:155], v[202:205], v[160:163], v[152:155]
	v_mfma_f32_16x16x32_bf16 v[122:125], v[206:209], v[160:163], v[122:125]
	ds_read_b128 v[160:163], v20 offset:1024
	s_waitcnt lgkmcnt(0)
	v_mfma_f32_16x16x32_bf16 v[172:175], v[168:171], v[160:163], v[172:175]
	v_mfma_f32_16x16x32_bf16 v[176:179], v[198:201], v[160:163], v[176:179]
	v_mfma_f32_16x16x32_bf16 v[194:197], v[202:205], v[160:163], v[194:197]
	v_mfma_f32_16x16x32_bf16 v[156:159], v[206:209], v[160:163], v[156:159]
	ds_read_b128 v[160:163], v17 offset:1024
	s_waitcnt lgkmcnt(0)
	v_mfma_f32_16x16x32_bf16 v[42:45], v[168:171], v[160:163], v[42:45]
	v_mfma_f32_16x16x32_bf16 v[50:53], v[198:201], v[160:163], v[50:53]
	v_mfma_f32_16x16x32_bf16 v[62:65], v[202:205], v[160:163], v[62:65]
	v_mfma_f32_16x16x32_bf16 v[66:69], v[206:209], v[160:163], v[66:69]
	s_mov_b64 s[34:35], 0x300
	s_mov_b32 m0, s2
	v_lshl_add_u64 v[126:127], v[0:1], 0, s[34:35]
	s_waitcnt vmcnt(0)
	s_waitcnt vmcnt(0)
	s_barrier
	global_load_lds_dwordx4 v[126:127], off
	v_lshl_add_u64 v[126:127], v[2:3], 0, s[34:35]
	s_mov_b32 m0, s1
	v_readfirstlane_b32 s1, v32
	global_load_lds_dwordx4 v[126:127], off
	v_lshl_add_u64 v[126:127], v[4:5], 0, s[34:35]
	s_mov_b32 m0, s1
	v_readfirstlane_b32 s1, v33
	global_load_lds_dwordx4 v[126:127], off
	v_lshl_add_u64 v[126:127], v[6:7], 0, s[34:35]
	s_mov_b32 m0, s1
	v_readfirstlane_b32 s1, v34
	global_load_lds_dwordx4 v[126:127], off
	v_lshl_add_u64 v[32:33], v[8:9], 0, s[34:35]
	s_mov_b32 m0, s1
	v_readfirstlane_b32 s1, v35
	global_load_lds_dwordx4 v[32:33], off
	v_lshl_add_u64 v[32:33], v[10:11], 0, s[34:35]
	s_mov_b32 m0, s1
	v_readfirstlane_b32 s1, v36
	global_load_lds_dwordx4 v[32:33], off
	v_lshl_add_u64 v[32:33], v[12:13], 0, s[34:35]
	s_mov_b32 m0, s1
	v_readfirstlane_b32 s1, v37
	global_load_lds_dwordx4 v[32:33], off
	v_lshl_add_u64 v[32:33], v[14:15], 0, s[34:35]
	s_mov_b32 m0, s1
	s_nop 0
	global_load_lds_dwordx4 v[32:33], off
	ds_read_b128 v[32:35], v26
	ds_read_b128 v[160:163], v25
	ds_read_b128 v[168:171], v25 offset:2048
	ds_read_b128 v[198:201], v25 offset:4096
	ds_read_b128 v[202:205], v25 offset:6144
	s_waitcnt lgkmcnt(0)
	v_mfma_f32_16x16x32_bf16 v[54:57], v[160:163], v[32:35], v[54:57]
	v_mfma_f32_16x16x32_bf16 v[58:61], v[168:171], v[32:35], v[58:61]
	v_mfma_f32_16x16x32_bf16 v[70:73], v[198:201], v[32:35], v[70:73]
	v_mfma_f32_16x16x32_bf16 v[32:35], v[202:205], v[32:35], v[38:41]
	s_nop 2
	ds_read_b128 v[36:39], v27
	s_waitcnt lgkmcnt(0)
	v_mfma_f32_16x16x32_bf16 v[78:81], v[160:163], v[36:39], v[78:81]
	v_mfma_f32_16x16x32_bf16 v[82:85], v[168:171], v[36:39], v[82:85]
	v_mfma_f32_16x16x32_bf16 v[86:89], v[198:201], v[36:39], v[86:89]
	v_mfma_f32_16x16x32_bf16 v[36:39], v[202:205], v[36:39], v[46:49]
	s_nop 2
	ds_read_b128 v[46:49], v28
	s_waitcnt lgkmcnt(0)
	v_mfma_f32_16x16x32_bf16 v[98:101], v[160:163], v[46:49], v[98:101]
	v_mfma_f32_16x16x32_bf16 v[102:105], v[168:171], v[46:49], v[102:105]
	v_mfma_f32_16x16x32_bf16 v[106:109], v[198:201], v[46:49], v[106:109]
	v_mfma_f32_16x16x32_bf16 v[46:49], v[202:205], v[46:49], v[74:77]
	s_nop 2
	ds_read_b128 v[74:77], v29
	s_waitcnt lgkmcnt(0)
	v_mfma_f32_16x16x32_bf16 v[110:113], v[160:163], v[74:77], v[110:113]
	v_mfma_f32_16x16x32_bf16 v[114:117], v[168:171], v[74:77], v[114:117]
	v_mfma_f32_16x16x32_bf16 v[118:121], v[198:201], v[74:77], v[118:121]
	v_mfma_f32_16x16x32_bf16 v[74:77], v[202:205], v[74:77], v[90:93]
	s_nop 2
	ds_read_b128 v[90:93], v30
	s_waitcnt lgkmcnt(0)
	v_mfma_f32_16x16x32_bf16 v[132:135], v[160:163], v[90:93], v[132:135]
	v_mfma_f32_16x16x32_bf16 v[136:139], v[168:171], v[90:93], v[136:139]
	v_mfma_f32_16x16x32_bf16 v[140:143], v[198:201], v[90:93], v[140:143]
	v_mfma_f32_16x16x32_bf16 v[90:93], v[202:205], v[90:93], v[94:97]
	s_nop 2
	ds_read_b128 v[94:97], v31
	s_waitcnt lgkmcnt(0)
	v_mfma_f32_16x16x32_bf16 v[144:147], v[160:163], v[94:97], v[144:147]
	v_mfma_f32_16x16x32_bf16 v[148:151], v[168:171], v[94:97], v[148:151]
	v_mfma_f32_16x16x32_bf16 v[152:155], v[198:201], v[94:97], v[152:155]
	v_mfma_f32_16x16x32_bf16 v[94:97], v[202:205], v[94:97], v[122:125]
	s_nop 2
	ds_read_b128 v[122:125], v130
	s_waitcnt lgkmcnt(0)
	v_mfma_f32_16x16x32_bf16 v[172:175], v[160:163], v[122:125], v[172:175]
	v_mfma_f32_16x16x32_bf16 v[176:179], v[168:171], v[122:125], v[176:179]
	v_mfma_f32_16x16x32_bf16 v[194:197], v[198:201], v[122:125], v[194:197]
	v_mfma_f32_16x16x32_bf16 v[122:125], v[202:205], v[122:125], v[156:159]
	s_nop 2
	ds_read_b128 v[156:159], v131
	s_waitcnt lgkmcnt(0)
	v_mfma_f32_16x16x32_bf16 v[40:43], v[160:163], v[156:159], v[42:45]
	v_mfma_f32_16x16x32_bf16 v[50:53], v[168:171], v[156:159], v[50:53]
	v_mfma_f32_16x16x32_bf16 v[62:65], v[198:201], v[156:159], v[62:65]
	v_mfma_f32_16x16x32_bf16 v[66:69], v[202:205], v[156:159], v[66:69]
	ds_read_b128 v[156:159], v26 offset:1024
	ds_read_b128 v[160:163], v25 offset:1024
	ds_read_b128 v[168:171], v25 offset:3072
	ds_read_b128 v[198:201], v25 offset:5120
	ds_read_b128 v[202:205], v25 offset:7168
	s_waitcnt lgkmcnt(0)
	v_mfma_f32_16x16x32_bf16 v[54:57], v[160:163], v[156:159], v[54:57]
	v_mfma_f32_16x16x32_bf16 v[58:61], v[168:171], v[156:159], v[58:61]
	v_mfma_f32_16x16x32_bf16 v[70:73], v[198:201], v[156:159], v[70:73]
	v_mfma_f32_16x16x32_bf16 v[32:35], v[202:205], v[156:159], v[32:35]
	ds_read_b128 v[156:159], v27 offset:1024
	s_waitcnt lgkmcnt(0)
	v_mfma_f32_16x16x32_bf16 v[78:81], v[160:163], v[156:159], v[78:81]
	v_mfma_f32_16x16x32_bf16 v[82:85], v[168:171], v[156:159], v[82:85]
	v_mfma_f32_16x16x32_bf16 v[86:89], v[198:201], v[156:159], v[86:89]
	v_mfma_f32_16x16x32_bf16 v[36:39], v[202:205], v[156:159], v[36:39]
	ds_read_b128 v[156:159], v28 offset:1024
	s_waitcnt lgkmcnt(0)
	v_mfma_f32_16x16x32_bf16 v[98:101], v[160:163], v[156:159], v[98:101]
	v_mfma_f32_16x16x32_bf16 v[102:105], v[168:171], v[156:159], v[102:105]
	v_mfma_f32_16x16x32_bf16 v[106:109], v[198:201], v[156:159], v[106:109]
	v_mfma_f32_16x16x32_bf16 v[44:47], v[202:205], v[156:159], v[46:49]
	ds_read_b128 v[156:159], v29 offset:1024
	s_waitcnt lgkmcnt(0)
	v_mfma_f32_16x16x32_bf16 v[110:113], v[160:163], v[156:159], v[110:113]
	v_mfma_f32_16x16x32_bf16 v[114:117], v[168:171], v[156:159], v[114:117]
	v_mfma_f32_16x16x32_bf16 v[118:121], v[198:201], v[156:159], v[118:121]
	v_mfma_f32_16x16x32_bf16 v[74:77], v[202:205], v[156:159], v[74:77]
	ds_read_b128 v[156:159], v30 offset:1024
	s_waitcnt lgkmcnt(0)
	v_mfma_f32_16x16x32_bf16 v[132:135], v[160:163], v[156:159], v[132:135]
	v_mfma_f32_16x16x32_bf16 v[136:139], v[168:171], v[156:159], v[136:139]
	v_mfma_f32_16x16x32_bf16 v[140:143], v[198:201], v[156:159], v[140:143]
	v_mfma_f32_16x16x32_bf16 v[90:93], v[202:205], v[156:159], v[90:93]
	ds_read_b128 v[156:159], v31 offset:1024
	s_waitcnt lgkmcnt(0)
	v_mfma_f32_16x16x32_bf16 v[144:147], v[160:163], v[156:159], v[144:147]
	v_mfma_f32_16x16x32_bf16 v[148:151], v[168:171], v[156:159], v[148:151]
	v_mfma_f32_16x16x32_bf16 v[152:155], v[198:201], v[156:159], v[152:155]
	v_mfma_f32_16x16x32_bf16 v[94:97], v[202:205], v[156:159], v[94:97]
	ds_read_b128 v[156:159], v130 offset:1024
	s_waitcnt lgkmcnt(0)
	v_mfma_f32_16x16x32_bf16 v[172:175], v[160:163], v[156:159], v[172:175]
	v_mfma_f32_16x16x32_bf16 v[176:179], v[168:171], v[156:159], v[176:179]
	v_mfma_f32_16x16x32_bf16 v[194:197], v[198:201], v[156:159], v[194:197]
	v_mfma_f32_16x16x32_bf16 v[122:125], v[202:205], v[156:159], v[122:125]
	ds_read_b128 v[156:159], v131 offset:1024
	s_waitcnt lgkmcnt(0)
	v_mfma_f32_16x16x32_bf16 v[40:43], v[160:163], v[156:159], v[40:43]
	v_mfma_f32_16x16x32_bf16 v[48:51], v[168:171], v[156:159], v[50:53]
	v_mfma_f32_16x16x32_bf16 v[62:65], v[198:201], v[156:159], v[62:65]
	v_mfma_f32_16x16x32_bf16 v[66:69], v[202:205], v[156:159], v[66:69]
	s_mov_b64 s[34:35], 0x380
	s_mov_b32 m0, s25
	v_lshl_add_u64 v[0:1], v[0:1], 0, s[34:35]
	s_waitcnt vmcnt(0)
	s_waitcnt vmcnt(0)
	s_barrier
	global_load_lds_dwordx4 v[0:1], off
	v_lshl_add_u64 v[0:1], v[2:3], 0, s[34:35]
	s_mov_b32 m0, s3
	s_nop 0
	global_load_lds_dwordx4 v[0:1], off
	v_lshl_add_u64 v[0:1], v[4:5], 0, s[34:35]
	s_mov_b32 m0, s9
	s_nop 0
	global_load_lds_dwordx4 v[0:1], off
	v_lshl_add_u64 v[0:1], v[6:7], 0, s[34:35]
	s_mov_b32 m0, s10
	s_nop 0
	global_load_lds_dwordx4 v[0:1], off
	v_lshl_add_u64 v[0:1], v[8:9], 0, s[34:35]
	s_mov_b32 m0, s11
	s_nop 0
	global_load_lds_dwordx4 v[0:1], off
	v_lshl_add_u64 v[0:1], v[10:11], 0, s[34:35]
	s_mov_b32 m0, s16
	s_nop 0
	global_load_lds_dwordx4 v[0:1], off
	v_lshl_add_u64 v[0:1], v[12:13], 0, s[34:35]
	s_mov_b32 m0, s24
	s_nop 0
	global_load_lds_dwordx4 v[0:1], off
	v_lshl_add_u64 v[0:1], v[14:15], 0, s[34:35]
	s_mov_b32 m0, s26
	s_nop 0
	global_load_lds_dwordx4 v[0:1], off
	ds_read_b128 v[0:3], v24
	ds_read_b128 v[4:7], v23 offset:32768
	ds_read_b128 v[12:15], v23 offset:34816
	ds_read_b128 v[156:159], v23 offset:38912
	s_waitcnt lgkmcnt(0)
	v_mfma_f32_16x16x32_bf16 v[8:11], v[4:7], v[0:3], v[54:57]
	v_mfma_f32_16x16x32_bf16 v[52:55], v[12:15], v[0:3], v[58:61]
	s_nop 2
	ds_read_b128 v[56:59], v23 offset:36864
	s_waitcnt lgkmcnt(0)
	v_mfma_f32_16x16x32_bf16 v[70:73], v[56:59], v[0:3], v[70:73]
	v_mfma_f32_16x16x32_bf16 v[0:3], v[156:159], v[0:3], v[32:35]
	s_nop 2
	ds_read_b128 v[32:35], v16
	s_waitcnt lgkmcnt(0)
	v_mfma_f32_16x16x32_bf16 v[78:81], v[4:7], v[32:35], v[78:81]
	v_mfma_f32_16x16x32_bf16 v[82:85], v[12:15], v[32:35], v[82:85]
	v_mfma_f32_16x16x32_bf16 v[86:89], v[56:59], v[32:35], v[86:89]
	v_mfma_f32_16x16x32_bf16 v[32:35], v[156:159], v[32:35], v[36:39]
	s_nop 2
	ds_read_b128 v[36:39], v22
	s_waitcnt lgkmcnt(0)
	v_mfma_f32_16x16x32_bf16 v[98:101], v[4:7], v[36:39], v[98:101]
	v_mfma_f32_16x16x32_bf16 v[102:105], v[12:15], v[36:39], v[102:105]
	v_mfma_f32_16x16x32_bf16 v[106:109], v[56:59], v[36:39], v[106:109]
	v_mfma_f32_16x16x32_bf16 v[36:39], v[156:159], v[36:39], v[44:47]
	s_nop 2
	ds_read_b128 v[44:47], v19
	s_waitcnt lgkmcnt(0)
	v_mfma_f32_16x16x32_bf16 v[110:113], v[4:7], v[44:47], v[110:113]
	v_mfma_f32_16x16x32_bf16 v[114:117], v[12:15], v[44:47], v[114:117]
	v_mfma_f32_16x16x32_bf16 v[118:121], v[56:59], v[44:47], v[118:121]
	v_mfma_f32_16x16x32_bf16 v[44:47], v[156:159], v[44:47], v[74:77]
	s_nop 2
	ds_read_b128 v[74:77], v21
	s_waitcnt lgkmcnt(0)
	v_mfma_f32_16x16x32_bf16 v[132:135], v[4:7], v[74:77], v[132:135]
	v_mfma_f32_16x16x32_bf16 v[136:139], v[12:15], v[74:77], v[136:139]
	v_mfma_f32_16x16x32_bf16 v[140:143], v[56:59], v[74:77], v[140:143]
	v_mfma_f32_16x16x32_bf16 v[74:77], v[156:159], v[74:77], v[90:93]
	s_nop 2
	ds_read_b128 v[90:93], v18
	s_waitcnt lgkmcnt(0)
	v_mfma_f32_16x16x32_bf16 v[144:147], v[4:7], v[90:93], v[144:147]
	v_mfma_f32_16x16x32_bf16 v[148:151], v[12:15], v[90:93], v[148:151]
	v_mfma_f32_16x16x32_bf16 v[152:155], v[56:59], v[90:93], v[152:155]
	v_mfma_f32_16x16x32_bf16 v[90:93], v[156:159], v[90:93], v[94:97]
	s_nop 2
	ds_read_b128 v[94:97], v20
	s_waitcnt lgkmcnt(0)
	v_mfma_f32_16x16x32_bf16 v[160:163], v[4:7], v[94:97], v[172:175]
	v_mfma_f32_16x16x32_bf16 v[168:171], v[12:15], v[94:97], v[176:179]
	v_mfma_f32_16x16x32_bf16 v[172:175], v[56:59], v[94:97], v[194:197]
	v_mfma_f32_16x16x32_bf16 v[94:97], v[156:159], v[94:97], v[122:125]
	s_nop 2
	ds_read_b128 v[122:125], v17
	s_waitcnt lgkmcnt(0)
	v_mfma_f32_16x16x32_bf16 v[4:7], v[4:7], v[122:125], v[40:43]
	v_mfma_f32_16x16x32_bf16 v[12:15], v[12:15], v[122:125], v[48:51]
	v_mfma_f32_16x16x32_bf16 v[40:43], v[56:59], v[122:125], v[62:65]
	v_mfma_f32_16x16x32_bf16 v[48:51], v[156:159], v[122:125], v[66:69]
	ds_read_b128 v[56:59], v24 offset:1024
	s_nop 0
	ds_read_b128 v[60:63], v23 offset:33792
	ds_read_b128 v[64:67], v23 offset:35840
	ds_read_b128 v[122:125], v23 offset:37888
	ds_read_b128 v[156:159], v23 offset:39936
	s_waitcnt lgkmcnt(0)
	v_mfma_f32_16x16x32_bf16 v[8:11], v[60:63], v[56:59], v[8:11]
	v_mfma_f32_16x16x32_bf16 v[52:55], v[64:67], v[56:59], v[52:55]
	v_mfma_f32_16x16x32_bf16 v[68:71], v[122:125], v[56:59], v[70:73]
	v_mfma_f32_16x16x32_bf16 v[0:3], v[156:159], v[56:59], v[0:3]
	ds_read_b128 v[56:59], v16 offset:1024
	s_waitcnt lgkmcnt(0)
	v_mfma_f32_16x16x32_bf16 v[78:81], v[60:63], v[56:59], v[78:81]
	v_mfma_f32_16x16x32_bf16 v[82:85], v[64:67], v[56:59], v[82:85]
	v_mfma_f32_16x16x32_bf16 v[86:89], v[122:125], v[56:59], v[86:89]
	v_mfma_f32_16x16x32_bf16 v[32:35], v[156:159], v[56:59], v[32:35]
	ds_read_b128 v[56:59], v22 offset:1024
	s_waitcnt lgkmcnt(0)
	v_mfma_f32_16x16x32_bf16 v[98:101], v[60:63], v[56:59], v[98:101]
	v_mfma_f32_16x16x32_bf16 v[102:105], v[64:67], v[56:59], v[102:105]
	v_mfma_f32_16x16x32_bf16 v[106:109], v[122:125], v[56:59], v[106:109]
	v_mfma_f32_16x16x32_bf16 v[36:39], v[156:159], v[56:59], v[36:39]
	ds_read_b128 v[56:59], v19 offset:1024
	s_waitcnt lgkmcnt(0)
	v_mfma_f32_16x16x32_bf16 v[110:113], v[60:63], v[56:59], v[110:113]
	v_mfma_f32_16x16x32_bf16 v[114:117], v[64:67], v[56:59], v[114:117]
	v_mfma_f32_16x16x32_bf16 v[118:121], v[122:125], v[56:59], v[118:121]
	v_mfma_f32_16x16x32_bf16 v[44:47], v[156:159], v[56:59], v[44:47]
	ds_read_b128 v[56:59], v21 offset:1024
	s_waitcnt lgkmcnt(0)
	v_mfma_f32_16x16x32_bf16 v[132:135], v[60:63], v[56:59], v[132:135]
	v_mfma_f32_16x16x32_bf16 v[136:139], v[64:67], v[56:59], v[136:139]
	v_mfma_f32_16x16x32_bf16 v[140:143], v[122:125], v[56:59], v[140:143]
	v_mfma_f32_16x16x32_bf16 v[56:59], v[156:159], v[56:59], v[74:77]
	s_nop 2
	ds_read_b128 v[72:75], v18 offset:1024
	ds_read_b128 v[18:21], v20 offset:1024
	s_waitcnt lgkmcnt(0)
	v_mfma_f32_16x16x32_bf16 v[144:147], v[60:63], v[72:75], v[144:147]
	v_mfma_f32_16x16x32_bf16 v[148:151], v[64:67], v[72:75], v[148:151]
	v_mfma_f32_16x16x32_bf16 v[152:155], v[122:125], v[72:75], v[152:155]
	v_mfma_f32_16x16x32_bf16 v[72:75], v[156:159], v[72:75], v[90:93]
	v_mfma_f32_16x16x32_bf16 v[90:93], v[60:63], v[18:21], v[160:163]
	v_mfma_f32_16x16x32_bf16 v[160:163], v[64:67], v[18:21], v[168:171]
	v_mfma_f32_16x16x32_bf16 v[168:171], v[122:125], v[18:21], v[172:175]
	v_mfma_f32_16x16x32_bf16 v[18:21], v[156:159], v[18:21], v[94:97]
	s_nop 2
	ds_read_b128 v[94:97], v17 offset:1024
	s_waitcnt lgkmcnt(0)
	v_mfma_f32_16x16x32_bf16 v[4:7], v[60:63], v[94:97], v[4:7]
	v_mfma_f32_16x16x32_bf16 v[12:15], v[64:67], v[94:97], v[12:15]
	v_mfma_f32_16x16x32_bf16 v[40:43], v[122:125], v[94:97], v[40:43]
	v_mfma_f32_16x16x32_bf16 v[48:51], v[156:159], v[94:97], v[48:51]
	s_waitcnt vmcnt(0)
	s_waitcnt vmcnt(0)
	s_barrier
	ds_read_b128 v[60:63], v26
	ds_read_b128 v[64:67], v25
	ds_read_b128 v[94:97], v25 offset:2048
	ds_read_b128 v[122:125], v25 offset:4096
	ds_read_b128 v[156:159], v25 offset:6144
	s_waitcnt lgkmcnt(3)
	v_mfma_f32_16x16x32_bf16 v[8:11], v[64:67], v[60:63], v[8:11]
	s_waitcnt lgkmcnt(2)
	v_mfma_f32_16x16x32_bf16 v[52:55], v[94:97], v[60:63], v[52:55]
	s_waitcnt lgkmcnt(1)
	v_mfma_f32_16x16x32_bf16 v[68:71], v[122:125], v[60:63], v[68:71]
	s_waitcnt lgkmcnt(0)
	v_mfma_f32_16x16x32_bf16 v[0:3], v[156:159], v[60:63], v[0:3]
	ds_read_b128 v[60:63], v27
	s_waitcnt lgkmcnt(0)
	v_mfma_f32_16x16x32_bf16 v[76:79], v[64:67], v[60:63], v[78:81]
	v_mfma_f32_16x16x32_bf16 v[80:83], v[94:97], v[60:63], v[82:85]
	v_mfma_f32_16x16x32_bf16 v[84:87], v[122:125], v[60:63], v[86:89]
	v_mfma_f32_16x16x32_bf16 v[32:35], v[156:159], v[60:63], v[32:35]
	ds_read_b128 v[60:63], v28
	s_waitcnt lgkmcnt(0)
	v_mfma_f32_16x16x32_bf16 v[172:175], v[64:67], v[60:63], v[98:101]
	v_mfma_f32_16x16x32_bf16 v[176:179], v[94:97], v[60:63], v[102:105]
	v_mfma_f32_16x16x32_bf16 v[194:197], v[122:125], v[60:63], v[106:109]
	v_mfma_f32_16x16x32_bf16 v[36:39], v[156:159], v[60:63], v[36:39]
	ds_read_b128 v[60:63], v29
	s_waitcnt lgkmcnt(0)
	v_mfma_f32_16x16x32_bf16 v[198:201], v[64:67], v[60:63], v[110:113]
	v_mfma_f32_16x16x32_bf16 v[202:205], v[94:97], v[60:63], v[114:117]
	v_mfma_f32_16x16x32_bf16 v[206:209], v[122:125], v[60:63], v[118:121]
	v_mfma_f32_16x16x32_bf16 v[44:47], v[156:159], v[60:63], v[44:47]
	ds_read_b128 v[60:63], v30
	s_waitcnt lgkmcnt(0)
	v_mfma_f32_16x16x32_bf16 v[210:213], v[156:159], v[60:63], v[56:59]
	s_nop 2
	ds_read_b128 v[56:59], v31
	s_waitcnt lgkmcnt(0)
	v_mfma_f32_16x16x32_bf16 v[144:147], v[64:67], v[56:59], v[144:147]
	v_mfma_f32_16x16x32_bf16 v[148:151], v[94:97], v[56:59], v[148:151]
	v_mfma_f32_16x16x32_bf16 v[152:155], v[122:125], v[56:59], v[152:155]
	v_mfma_f32_16x16x32_bf16 v[214:217], v[156:159], v[56:59], v[72:75]
	ds_read_b128 v[56:59], v130
	s_waitcnt lgkmcnt(0)
	v_mfma_f32_16x16x32_bf16 v[20:23], v[156:159], v[56:59], v[18:21]
	s_nop 2
	ds_read_b128 v[16:19], v131
	v_mfma_f32_16x16x32_bf16 v[140:143], v[122:125], v[60:63], v[140:143]
	s_waitcnt lgkmcnt(0)
	v_mfma_f32_16x16x32_bf16 v[4:7], v[64:67], v[16:19], v[4:7]
	v_mfma_f32_16x16x32_bf16 v[132:135], v[64:67], v[60:63], v[132:135]
	v_mfma_f32_16x16x32_bf16 v[136:139], v[94:97], v[60:63], v[136:139]
	v_mfma_f32_16x16x32_bf16 v[218:221], v[64:67], v[56:59], v[90:93]
	v_mfma_f32_16x16x32_bf16 v[160:163], v[94:97], v[56:59], v[160:163]
	v_mfma_f32_16x16x32_bf16 v[168:171], v[122:125], v[56:59], v[168:171]
	v_mfma_f32_16x16x32_bf16 v[222:225], v[94:97], v[16:19], v[12:15]
	v_mfma_f32_16x16x32_bf16 v[226:229], v[122:125], v[16:19], v[40:43]
	v_mfma_f32_16x16x32_bf16 v[156:159], v[156:159], v[16:19], v[48:51]
	s_nop 0
	ds_read_b128 v[12:15], v26 offset:1024
	ds_read_b128 v[230:233], v25 offset:1024
	ds_read_b128 v[238:241], v25 offset:7168
	s_waitcnt lgkmcnt(0)
	v_mfma_f32_16x16x32_bf16 v[120:123], v[238:241], v[12:15], v[0:3]
	s_nop 2
	ds_read_b128 v[0:3], v27 offset:1024
	ds_read_b128 v[234:237], v25 offset:5120
	v_mfma_f32_16x16x32_bf16 v[112:115], v[230:233], v[12:15], v[8:11]
	s_nop 2
	ds_read_b128 v[8:11], v25 offset:3072
	s_waitcnt lgkmcnt(2)
	v_mfma_f32_16x16x32_bf16 v[108:111], v[230:233], v[0:3], v[76:79]
	s_waitcnt lgkmcnt(0)
	v_mfma_f32_16x16x32_bf16 v[96:99], v[8:11], v[0:3], v[80:83]
	v_mfma_f32_16x16x32_bf16 v[104:107], v[234:237], v[0:3], v[84:87]
	v_mfma_f32_16x16x32_bf16 v[100:103], v[238:241], v[0:3], v[32:35]
	ds_read_b128 v[0:3], v28 offset:1024
	s_waitcnt lgkmcnt(0)
	v_mfma_f32_16x16x32_bf16 v[92:95], v[230:233], v[0:3], v[172:175]
	v_mfma_f32_16x16x32_bf16 v[80:83], v[8:11], v[0:3], v[176:179]
	v_mfma_f32_16x16x32_bf16 v[88:91], v[234:237], v[0:3], v[194:197]
	v_mfma_f32_16x16x32_bf16 v[84:87], v[238:241], v[0:3], v[36:39]
	ds_read_b128 v[0:3], v29 offset:1024
	v_mfma_f32_16x16x32_bf16 v[124:127], v[234:237], v[12:15], v[68:71]
	s_waitcnt lgkmcnt(0)
	v_mfma_f32_16x16x32_bf16 v[76:79], v[230:233], v[0:3], v[198:201]
	v_mfma_f32_16x16x32_bf16 v[64:67], v[8:11], v[0:3], v[202:205]
	v_mfma_f32_16x16x32_bf16 v[72:75], v[234:237], v[0:3], v[206:209]
	v_mfma_f32_16x16x32_bf16 v[68:71], v[238:241], v[0:3], v[44:47]
	ds_read_b128 v[0:3], v30 offset:1024
	v_mfma_f32_16x16x32_bf16 v[116:119], v[8:11], v[12:15], v[52:55]
	s_waitcnt lgkmcnt(0)
	v_mfma_f32_16x16x32_bf16 v[60:63], v[230:233], v[0:3], v[132:135]
	v_mfma_f32_16x16x32_bf16 v[48:51], v[8:11], v[0:3], v[136:139]
	v_mfma_f32_16x16x32_bf16 v[56:59], v[234:237], v[0:3], v[140:143]
	v_mfma_f32_16x16x32_bf16 v[52:55], v[238:241], v[0:3], v[210:213]
	ds_read_b128 v[0:3], v31 offset:1024
	s_waitcnt lgkmcnt(0)
	v_mfma_f32_16x16x32_bf16 v[44:47], v[230:233], v[0:3], v[144:147]
	v_mfma_f32_16x16x32_bf16 v[32:35], v[8:11], v[0:3], v[148:151]
	v_mfma_f32_16x16x32_bf16 v[40:43], v[234:237], v[0:3], v[152:155]
	v_mfma_f32_16x16x32_bf16 v[36:39], v[238:241], v[0:3], v[214:217]
	ds_read_b128 v[0:3], v130 offset:1024
	ds_read_b128 v[130:133], v131 offset:1024
	s_waitcnt lgkmcnt(1)
	v_mfma_f32_16x16x32_bf16 v[28:31], v[230:233], v[0:3], v[218:221]
	v_mfma_f32_16x16x32_bf16 v[16:19], v[8:11], v[0:3], v[160:163]
	v_mfma_f32_16x16x32_bf16 v[24:27], v[234:237], v[0:3], v[168:171]
	v_mfma_f32_16x16x32_bf16 v[20:23], v[238:241], v[0:3], v[20:23]
	s_waitcnt lgkmcnt(0)
	v_mfma_f32_16x16x32_bf16 v[12:15], v[230:233], v[130:133], v[4:7]
	v_mfma_f32_16x16x32_bf16 v[0:3], v[8:11], v[130:133], v[222:225]
	v_mfma_f32_16x16x32_bf16 v[8:11], v[234:237], v[130:133], v[226:229]
	v_mfma_f32_16x16x32_bf16 v[4:7], v[238:241], v[130:133], v[156:159]
	s_waitcnt vmcnt(0)
	s_barrier
	s_add_i32 s0, s20, 0xfffffde0
	s_mul_i32 s1, s0, 0xaaab
	s_lshr_b32 s1, s1, 18
	s_mul_i32 s2, s1, 6
	s_sub_i32 s2, s0, s2
	v_readfirstlane_b32 s8, v167
	v_and_b32_e32 v128, 15, v167
	v_bfe_u32 v129, v167, 4, 2
	s_lshr_b32 s8, s8, 6
	s_and_b32 s9, s8, 3
	s_lshr_b32 s8, s8, 2
	s_lshl_b32 s3, s1, 8
	s_lshl_b32 s10, s8, 7
	s_add_u32 s3, s3, s10
	s_lshl_b32 s10, s2, 8
	s_lshl_b32 s11, s9, 6
	s_add_u32 s10, s10, s11
	v_readlane_b32 s24, v255, 28
	v_readlane_b32 s25, v255, 29
	s_mul_i32 s11, s3, 0xc00
	s_lshl_b32 s26, s10, 1
	s_add_u32 s11, s11, s26
	s_add_u32 s24, s24, s11
	s_addc_u32 s25, s25, 0
	v_mul_u32_u24_e32 v131, 0xc00, v128
	v_lshl_add_u32 v131, v129, 3, v131
	s_lshl_b32 s11, s8, 9
	v_lshl_add_u32 v130, v128, 2, s11
	v_add_u32_e32 v130, 0x20000, v130
	ds_read_b32 v134, v130
	ds_read_b32 v135, v130 offset:64
	ds_read_b32 v136, v130 offset:128
	ds_read_b32 v137, v130 offset:192
	ds_read_b32 v138, v130 offset:256
	ds_read_b32 v139, v130 offset:320
	ds_read_b32 v140, v130 offset:384
	ds_read_b32 v141, v130 offset:448
	s_lshl_b32 s11, s2, 2
	s_add_u32 s11, s11, s9
	s_mul_i32 s26, s11, 0xaaab
	s_lshr_b32 s26, s26, 17
	s_mul_i32 s26, s26, 3
	s_sub_u32 s11, s11, s26
	s_cmp_eq_u32 s11, 2
	s_cselect_b32 s11, 1, 0
	s_cmp_lt_u32 s1, 64
	s_cselect_b32 s11, s11, 0
	s_cmp_eq_u32 s11, 0
	s_cbranch_scc1 .Lq_norope
	s_and_b32 s26, s3, 0xfff
	s_lshr_b32 s26, s26, 6
	s_lshl_b32 s26, s26, 7
	v_lshlrev_b32_e32 v132, 5, v129
	v_lshl_add_u32 v133, v128, 7, v132
	v_add_u32_e32 v132, s26, v132
	global_load_dwordx4 v[194:197], v132, s[38:39]
	global_load_dwordx4 v[198:201], v132, s[38:39] offset:16
	global_load_dwordx4 v[210:213], v133, s[38:39]
	global_load_dwordx4 v[214:217], v133, s[38:39] offset:16
	global_load_dwordx4 v[202:205], v132, s[38:39]
	global_load_dwordx4 v[206:209], v132, s[38:39] offset:16
	global_load_dwordx4 v[218:221], v133, s[38:39] offset:2048
	global_load_dwordx4 v[222:225], v133, s[38:39] offset:2064
	s_waitcnt lgkmcnt(0)
	global_load_dwordx4 v[226:229], v132, s[38:39]
	global_load_dwordx4 v[230:233], v132, s[38:39] offset:16
	v_add_u32_e32 v160, 4096, v133
	global_load_dwordx4 v[142:145], v160, s[38:39]
	global_load_dwordx4 v[146:149], v160, s[38:39] offset:16
	global_load_dwordx4 v[234:237], v132, s[38:39]
	global_load_dwordx4 v[238:241], v132, s[38:39] offset:16
	v_add_u32_e32 v160, 6144, v133
	global_load_dwordx4 v[150:153], v160, s[38:39]
	global_load_dwordx4 v[154:157], v160, s[38:39] offset:16
	v_mul_f32_e32 v112, v112, v134
	v_mul_f32_e32 v113, v113, v134
	v_mul_f32_e32 v114, v114, v134
	v_mul_f32_e32 v115, v115, v134
	v_mul_f32_e32 v116, v116, v134
	v_mul_f32_e32 v117, v117, v134
	v_mul_f32_e32 v118, v118, v134
	v_mul_f32_e32 v119, v119, v134
	v_mul_f32_e32 v124, v124, v134
	v_mul_f32_e32 v125, v125, v134
	v_mul_f32_e32 v126, v126, v134
	v_mul_f32_e32 v127, v127, v134
	v_mul_f32_e32 v120, v120, v134
	v_mul_f32_e32 v121, v121, v134
	v_mul_f32_e32 v122, v122, v134
	v_mul_f32_e32 v123, v123, v134
	v_mul_f32_e32 v108, v108, v135
	v_mul_f32_e32 v109, v109, v135
	v_mul_f32_e32 v110, v110, v135
	v_mul_f32_e32 v111, v111, v135
	v_mul_f32_e32 v96, v96, v135
	v_mul_f32_e32 v97, v97, v135
	v_mul_f32_e32 v98, v98, v135
	v_mul_f32_e32 v99, v99, v135
	v_mul_f32_e32 v104, v104, v135
	v_mul_f32_e32 v105, v105, v135
	v_mul_f32_e32 v106, v106, v135
	v_mul_f32_e32 v107, v107, v135
	v_mul_f32_e32 v100, v100, v135
	v_mul_f32_e32 v101, v101, v135
	v_mul_f32_e32 v102, v102, v135
	v_mul_f32_e32 v103, v103, v135
	s_waitcnt vmcnt(8)
	v_mul_f32_e32 v160, v116, v195
	v_mul_f32_e32 v161, v112, v195
	v_fma_f32 v112, v112, v194, -v160
	v_fma_f32 v116, v116, v194, v161
	v_mul_f32_e32 v162, v117, v197
	v_mul_f32_e32 v163, v113, v197
	v_fma_f32 v113, v113, v196, -v162
	v_fma_f32 v117, v117, v196, v163
	v_mul_f32_e32 v160, v118, v199
	v_mul_f32_e32 v161, v114, v199
	v_fma_f32 v114, v114, v198, -v160
	v_fma_f32 v118, v118, v198, v161
	v_mul_f32_e32 v162, v119, v201
	v_mul_f32_e32 v163, v115, v201
	v_fma_f32 v115, v115, v200, -v162
	v_fma_f32 v119, v119, v200, v163
	v_mul_f32_e32 v160, v120, v211
	v_mul_f32_e32 v161, v124, v211
	v_fma_f32 v124, v124, v210, -v160
	v_fma_f32 v120, v120, v210, v161
	v_mul_f32_e32 v162, v121, v213
	v_mul_f32_e32 v163, v125, v213
	v_fma_f32 v125, v125, v212, -v162
	v_fma_f32 v121, v121, v212, v163
	v_mul_f32_e32 v160, v122, v215
	v_mul_f32_e32 v161, v126, v215
	v_fma_f32 v126, v126, v214, -v160
	v_fma_f32 v122, v122, v214, v161
	v_mul_f32_e32 v162, v123, v217
	v_mul_f32_e32 v163, v127, v217
	v_fma_f32 v127, v127, v216, -v162
	v_fma_f32 v123, v123, v216, v163
	v_mul_f32_e32 v160, v96, v203
	v_mul_f32_e32 v161, v108, v203
	v_fma_f32 v108, v108, v202, -v160
	v_fma_f32 v96, v96, v202, v161
	v_mul_f32_e32 v162, v97, v205
	v_mul_f32_e32 v163, v109, v205
	v_fma_f32 v109, v109, v204, -v162
	v_fma_f32 v97, v97, v204, v163
	v_mul_f32_e32 v160, v98, v207
	v_mul_f32_e32 v161, v110, v207
	v_fma_f32 v110, v110, v206, -v160
	v_fma_f32 v98, v98, v206, v161
	v_mul_f32_e32 v162, v99, v209
	v_mul_f32_e32 v163, v111, v209
	v_fma_f32 v111, v111, v208, -v162
	v_fma_f32 v99, v99, v208, v163
	v_mul_f32_e32 v160, v100, v219
	v_mul_f32_e32 v161, v104, v219
	v_fma_f32 v104, v104, v218, -v160
	v_fma_f32 v100, v100, v218, v161
	v_mul_f32_e32 v162, v101, v221
	v_mul_f32_e32 v163, v105, v221
	v_fma_f32 v105, v105, v220, -v162
	v_fma_f32 v101, v101, v220, v163
	v_mul_f32_e32 v160, v102, v223
	v_mul_f32_e32 v161, v106, v223
	v_fma_f32 v106, v106, v222, -v160
	v_fma_f32 v102, v102, v222, v161
	v_mul_f32_e32 v162, v103, v225
	v_mul_f32_e32 v163, v107, v225
	v_fma_f32 v107, v107, v224, -v162
	v_fma_f32 v103, v103, v224, v163
	v_mov_b32_e32 v158, v131
	v_cvt_pk_bf16_f32 v112, v112, v113
	v_cvt_pk_bf16_f32 v113, v114, v115
	v_cvt_pk_bf16_f32 v116, v116, v117
	v_cvt_pk_bf16_f32 v117, v118, v119
	v_cvt_pk_bf16_f32 v124, v124, v125
	v_cvt_pk_bf16_f32 v125, v126, v127
	v_cvt_pk_bf16_f32 v120, v120, v121
	v_cvt_pk_bf16_f32 v121, v122, v123
	global_store_dwordx2 v158, v[112:113], s[24:25]
	global_store_dwordx2 v158, v[116:117], s[24:25] offset:32
	global_store_dwordx2 v158, v[124:125], s[24:25] offset:64
	global_store_dwordx2 v158, v[120:121], s[24:25] offset:96
	v_add_u32_e32 v158, 49152, v131
	v_cvt_pk_bf16_f32 v108, v108, v109
	v_cvt_pk_bf16_f32 v109, v110, v111
	v_cvt_pk_bf16_f32 v96, v96, v97
	v_cvt_pk_bf16_f32 v97, v98, v99
	v_cvt_pk_bf16_f32 v104, v104, v105
	v_cvt_pk_bf16_f32 v105, v106, v107
	v_cvt_pk_bf16_f32 v100, v100, v101
	v_cvt_pk_bf16_f32 v101, v102, v103
	global_store_dwordx2 v158, v[108:109], s[24:25]
	global_store_dwordx2 v158, v[96:97], s[24:25] offset:32
	global_store_dwordx2 v158, v[104:105], s[24:25] offset:64
	global_store_dwordx2 v158, v[100:101], s[24:25] offset:96
	global_load_dwordx4 v[194:197], v132, s[38:39] offset:128
	global_load_dwordx4 v[198:201], v132, s[38:39] offset:144
	global_load_dwordx4 v[210:213], v133, s[38:39]
	global_load_dwordx4 v[214:217], v133, s[38:39] offset:16
	global_load_dwordx4 v[202:205], v132, s[38:39] offset:128
	global_load_dwordx4 v[206:209], v132, s[38:39] offset:144
	global_load_dwordx4 v[218:221], v133, s[38:39] offset:2048
	global_load_dwordx4 v[222:225], v133, s[38:39] offset:2064
	v_mul_f32_e32 v92, v92, v136
	v_mul_f32_e32 v93, v93, v136
	v_mul_f32_e32 v94, v94, v136
	v_mul_f32_e32 v95, v95, v136
	v_mul_f32_e32 v80, v80, v136
	v_mul_f32_e32 v81, v81, v136
	v_mul_f32_e32 v82, v82, v136
	v_mul_f32_e32 v83, v83, v136
	v_mul_f32_e32 v88, v88, v136
	v_mul_f32_e32 v89, v89, v136
	v_mul_f32_e32 v90, v90, v136
	v_mul_f32_e32 v91, v91, v136
	v_mul_f32_e32 v84, v84, v136
	v_mul_f32_e32 v85, v85, v136
	v_mul_f32_e32 v86, v86, v136
	v_mul_f32_e32 v87, v87, v136
	v_mul_f32_e32 v76, v76, v137
	v_mul_f32_e32 v77, v77, v137
	v_mul_f32_e32 v78, v78, v137
	v_mul_f32_e32 v79, v79, v137
	v_mul_f32_e32 v64, v64, v137
	v_mul_f32_e32 v65, v65, v137
	v_mul_f32_e32 v66, v66, v137
	v_mul_f32_e32 v67, v67, v137
	v_mul_f32_e32 v72, v72, v137
	v_mul_f32_e32 v73, v73, v137
	v_mul_f32_e32 v74, v74, v137
	v_mul_f32_e32 v75, v75, v137
	v_mul_f32_e32 v68, v68, v137
	v_mul_f32_e32 v69, v69, v137
	v_mul_f32_e32 v70, v70, v137
	v_mul_f32_e32 v71, v71, v137
	s_waitcnt vmcnt(16)
	v_mul_f32_e32 v160, v80, v227
	v_mul_f32_e32 v161, v92, v227
	v_fma_f32 v92, v92, v226, -v160
	v_fma_f32 v80, v80, v226, v161
	v_mul_f32_e32 v162, v81, v229
	v_mul_f32_e32 v163, v93, v229
	v_fma_f32 v93, v93, v228, -v162
	v_fma_f32 v81, v81, v228, v163
	v_mul_f32_e32 v160, v82, v231
	v_mul_f32_e32 v161, v94, v231
	v_fma_f32 v94, v94, v230, -v160
	v_fma_f32 v82, v82, v230, v161
	v_mul_f32_e32 v162, v83, v233
	v_mul_f32_e32 v163, v95, v233
	v_fma_f32 v95, v95, v232, -v162
	v_fma_f32 v83, v83, v232, v163
	v_mul_f32_e32 v160, v84, v143
	v_mul_f32_e32 v161, v88, v143
	v_fma_f32 v88, v88, v142, -v160
	v_fma_f32 v84, v84, v142, v161
	v_mul_f32_e32 v162, v85, v145
	v_mul_f32_e32 v163, v89, v145
	v_fma_f32 v89, v89, v144, -v162
	v_fma_f32 v85, v85, v144, v163
	v_mul_f32_e32 v160, v86, v147
	v_mul_f32_e32 v161, v90, v147
	v_fma_f32 v90, v90, v146, -v160
	v_fma_f32 v86, v86, v146, v161
	v_mul_f32_e32 v162, v87, v149
	v_mul_f32_e32 v163, v91, v149
	v_fma_f32 v91, v91, v148, -v162
	v_fma_f32 v87, v87, v148, v163
	v_mul_f32_e32 v160, v64, v235
	v_mul_f32_e32 v161, v76, v235
	v_fma_f32 v76, v76, v234, -v160
	v_fma_f32 v64, v64, v234, v161
	v_mul_f32_e32 v162, v65, v237
	v_mul_f32_e32 v163, v77, v237
	v_fma_f32 v77, v77, v236, -v162
	v_fma_f32 v65, v65, v236, v163
	v_mul_f32_e32 v160, v66, v239
	v_mul_f32_e32 v161, v78, v239
	v_fma_f32 v78, v78, v238, -v160
	v_fma_f32 v66, v66, v238, v161
	v_mul_f32_e32 v162, v67, v241
	v_mul_f32_e32 v163, v79, v241
	v_fma_f32 v79, v79, v240, -v162
	v_fma_f32 v67, v67, v240, v163
	v_mul_f32_e32 v160, v68, v151
	v_mul_f32_e32 v161, v72, v151
	v_fma_f32 v72, v72, v150, -v160
	v_fma_f32 v68, v68, v150, v161
	v_mul_f32_e32 v162, v69, v153
	v_mul_f32_e32 v163, v73, v153
	v_fma_f32 v73, v73, v152, -v162
	v_fma_f32 v69, v69, v152, v163
	v_mul_f32_e32 v160, v70, v155
	v_mul_f32_e32 v161, v74, v155
	v_fma_f32 v74, v74, v154, -v160
	v_fma_f32 v70, v70, v154, v161
	v_mul_f32_e32 v162, v71, v157
	v_mul_f32_e32 v163, v75, v157
	v_fma_f32 v75, v75, v156, -v162
	v_fma_f32 v71, v71, v156, v163
	v_add_u32_e32 v158, 98304, v131
	v_cvt_pk_bf16_f32 v92, v92, v93
	v_cvt_pk_bf16_f32 v93, v94, v95
	v_cvt_pk_bf16_f32 v80, v80, v81
	v_cvt_pk_bf16_f32 v81, v82, v83
	v_cvt_pk_bf16_f32 v88, v88, v89
	v_cvt_pk_bf16_f32 v89, v90, v91
	v_cvt_pk_bf16_f32 v84, v84, v85
	v_cvt_pk_bf16_f32 v85, v86, v87
	global_store_dwordx2 v158, v[92:93], s[24:25]
	global_store_dwordx2 v158, v[80:81], s[24:25] offset:32
	global_store_dwordx2 v158, v[88:89], s[24:25] offset:64
	global_store_dwordx2 v158, v[84:85], s[24:25] offset:96
	v_add_u32_e32 v158, 147456, v131
	v_cvt_pk_bf16_f32 v76, v76, v77
	v_cvt_pk_bf16_f32 v77, v78, v79
	v_cvt_pk_bf16_f32 v64, v64, v65
	v_cvt_pk_bf16_f32 v65, v66, v67
	v_cvt_pk_bf16_f32 v72, v72, v73
	v_cvt_pk_bf16_f32 v73, v74, v75
	v_cvt_pk_bf16_f32 v68, v68, v69
	v_cvt_pk_bf16_f32 v69, v70, v71
	global_store_dwordx2 v158, v[76:77], s[24:25]
	global_store_dwordx2 v158, v[64:65], s[24:25] offset:32
	global_store_dwordx2 v158, v[72:73], s[24:25] offset:64
	global_store_dwordx2 v158, v[68:69], s[24:25] offset:96
	global_load_dwordx4 v[226:229], v132, s[38:39] offset:128
	global_load_dwordx4 v[230:233], v132, s[38:39] offset:144
	v_add_u32_e32 v160, 4096, v133
	global_load_dwordx4 v[142:145], v160, s[38:39]
	global_load_dwordx4 v[146:149], v160, s[38:39] offset:16
	global_load_dwordx4 v[234:237], v132, s[38:39] offset:128
	global_load_dwordx4 v[238:241], v132, s[38:39] offset:144
	v_add_u32_e32 v160, 6144, v133
	global_load_dwordx4 v[150:153], v160, s[38:39]
	global_load_dwordx4 v[154:157], v160, s[38:39] offset:16
	v_mul_f32_e32 v60, v60, v138
	v_mul_f32_e32 v61, v61, v138
	v_mul_f32_e32 v62, v62, v138
	v_mul_f32_e32 v63, v63, v138
	v_mul_f32_e32 v48, v48, v138
	v_mul_f32_e32 v49, v49, v138
	v_mul_f32_e32 v50, v50, v138
	v_mul_f32_e32 v51, v51, v138
	v_mul_f32_e32 v56, v56, v138
	v_mul_f32_e32 v57, v57, v138
	v_mul_f32_e32 v58, v58, v138
	v_mul_f32_e32 v59, v59, v138
	v_mul_f32_e32 v52, v52, v138
	v_mul_f32_e32 v53, v53, v138
	v_mul_f32_e32 v54, v54, v138
	v_mul_f32_e32 v55, v55, v138
	v_mul_f32_e32 v44, v44, v139
	v_mul_f32_e32 v45, v45, v139
	v_mul_f32_e32 v46, v46, v139
	v_mul_f32_e32 v47, v47, v139
	v_mul_f32_e32 v32, v32, v139
	v_mul_f32_e32 v33, v33, v139
	v_mul_f32_e32 v34, v34, v139
	v_mul_f32_e32 v35, v35, v139
	v_mul_f32_e32 v40, v40, v139
	v_mul_f32_e32 v41, v41, v139
	v_mul_f32_e32 v42, v42, v139
	v_mul_f32_e32 v43, v43, v139
	v_mul_f32_e32 v36, v36, v139
	v_mul_f32_e32 v37, v37, v139
	v_mul_f32_e32 v38, v38, v139
	v_mul_f32_e32 v39, v39, v139
	s_waitcnt vmcnt(16)
	v_mul_f32_e32 v160, v48, v195
	v_mul_f32_e32 v161, v60, v195
	v_fma_f32 v60, v60, v194, -v160
	v_fma_f32 v48, v48, v194, v161
	v_mul_f32_e32 v162, v49, v197
	v_mul_f32_e32 v163, v61, v197
	v_fma_f32 v61, v61, v196, -v162
	v_fma_f32 v49, v49, v196, v163
	v_mul_f32_e32 v160, v50, v199
	v_mul_f32_e32 v161, v62, v199
	v_fma_f32 v62, v62, v198, -v160
	v_fma_f32 v50, v50, v198, v161
	v_mul_f32_e32 v162, v51, v201
	v_mul_f32_e32 v163, v63, v201
	v_fma_f32 v63, v63, v200, -v162
	v_fma_f32 v51, v51, v200, v163
	v_mul_f32_e32 v160, v52, v211
	v_mul_f32_e32 v161, v56, v211
	v_fma_f32 v56, v56, v210, -v160
	v_fma_f32 v52, v52, v210, v161
	v_mul_f32_e32 v162, v53, v213
	v_mul_f32_e32 v163, v57, v213
	v_fma_f32 v57, v57, v212, -v162
	v_fma_f32 v53, v53, v212, v163
	v_mul_f32_e32 v160, v54, v215
	v_mul_f32_e32 v161, v58, v215
	v_fma_f32 v58, v58, v214, -v160
	v_fma_f32 v54, v54, v214, v161
	v_mul_f32_e32 v162, v55, v217
	v_mul_f32_e32 v163, v59, v217
	v_fma_f32 v59, v59, v216, -v162
	v_fma_f32 v55, v55, v216, v163
	v_mul_f32_e32 v160, v32, v203
	v_mul_f32_e32 v161, v44, v203
	v_fma_f32 v44, v44, v202, -v160
	v_fma_f32 v32, v32, v202, v161
	v_mul_f32_e32 v162, v33, v205
	v_mul_f32_e32 v163, v45, v205
	v_fma_f32 v45, v45, v204, -v162
	v_fma_f32 v33, v33, v204, v163
	v_mul_f32_e32 v160, v34, v207
	v_mul_f32_e32 v161, v46, v207
	v_fma_f32 v46, v46, v206, -v160
	v_fma_f32 v34, v34, v206, v161
	v_mul_f32_e32 v162, v35, v209
	v_mul_f32_e32 v163, v47, v209
	v_fma_f32 v47, v47, v208, -v162
	v_fma_f32 v35, v35, v208, v163
	v_mul_f32_e32 v160, v36, v219
	v_mul_f32_e32 v161, v40, v219
	v_fma_f32 v40, v40, v218, -v160
	v_fma_f32 v36, v36, v218, v161
	v_mul_f32_e32 v162, v37, v221
	v_mul_f32_e32 v163, v41, v221
	v_fma_f32 v41, v41, v220, -v162
	v_fma_f32 v37, v37, v220, v163
	v_mul_f32_e32 v160, v38, v223
	v_mul_f32_e32 v161, v42, v223
	v_fma_f32 v42, v42, v222, -v160
	v_fma_f32 v38, v38, v222, v161
	v_mul_f32_e32 v162, v39, v225
	v_mul_f32_e32 v163, v43, v225
	v_fma_f32 v43, v43, v224, -v162
	v_fma_f32 v39, v39, v224, v163
	v_add_u32_e32 v158, 196608, v131
	v_cvt_pk_bf16_f32 v60, v60, v61
	v_cvt_pk_bf16_f32 v61, v62, v63
	v_cvt_pk_bf16_f32 v48, v48, v49
	v_cvt_pk_bf16_f32 v49, v50, v51
	v_cvt_pk_bf16_f32 v56, v56, v57
	v_cvt_pk_bf16_f32 v57, v58, v59
	v_cvt_pk_bf16_f32 v52, v52, v53
	v_cvt_pk_bf16_f32 v53, v54, v55
	global_store_dwordx2 v158, v[60:61], s[24:25]
	global_store_dwordx2 v158, v[48:49], s[24:25] offset:32
	global_store_dwordx2 v158, v[56:57], s[24:25] offset:64
	global_store_dwordx2 v158, v[52:53], s[24:25] offset:96
	v_add_u32_e32 v158, 245760, v131
	v_cvt_pk_bf16_f32 v44, v44, v45
	v_cvt_pk_bf16_f32 v45, v46, v47
	v_cvt_pk_bf16_f32 v32, v32, v33
	v_cvt_pk_bf16_f32 v33, v34, v35
	v_cvt_pk_bf16_f32 v40, v40, v41
	v_cvt_pk_bf16_f32 v41, v42, v43
	v_cvt_pk_bf16_f32 v36, v36, v37
	v_cvt_pk_bf16_f32 v37, v38, v39
	global_store_dwordx2 v158, v[44:45], s[24:25]
	global_store_dwordx2 v158, v[32:33], s[24:25] offset:32
	global_store_dwordx2 v158, v[40:41], s[24:25] offset:64
	global_store_dwordx2 v158, v[36:37], s[24:25] offset:96
	v_mul_f32_e32 v28, v28, v140
	v_mul_f32_e32 v29, v29, v140
	v_mul_f32_e32 v30, v30, v140
	v_mul_f32_e32 v31, v31, v140
	v_mul_f32_e32 v16, v16, v140
	v_mul_f32_e32 v17, v17, v140
	v_mul_f32_e32 v18, v18, v140
	v_mul_f32_e32 v19, v19, v140
	v_mul_f32_e32 v24, v24, v140
	v_mul_f32_e32 v25, v25, v140
	v_mul_f32_e32 v26, v26, v140
	v_mul_f32_e32 v27, v27, v140
	v_mul_f32_e32 v20, v20, v140
	v_mul_f32_e32 v21, v21, v140
	v_mul_f32_e32 v22, v22, v140
	v_mul_f32_e32 v23, v23, v140
	v_mul_f32_e32 v12, v12, v141
	v_mul_f32_e32 v13, v13, v141
	v_mul_f32_e32 v14, v14, v141
	v_mul_f32_e32 v15, v15, v141
	v_mul_f32_e32 v0, v0, v141
	v_mul_f32_e32 v1, v1, v141
	v_mul_f32_e32 v2, v2, v141
	v_mul_f32_e32 v3, v3, v141
	v_mul_f32_e32 v8, v8, v141
	v_mul_f32_e32 v9, v9, v141
	v_mul_f32_e32 v10, v10, v141
	v_mul_f32_e32 v11, v11, v141
	v_mul_f32_e32 v4, v4, v141
	v_mul_f32_e32 v5, v5, v141
	v_mul_f32_e32 v6, v6, v141
	v_mul_f32_e32 v7, v7, v141
	s_waitcnt vmcnt(8)
	v_mul_f32_e32 v160, v16, v227
	v_mul_f32_e32 v161, v28, v227
	v_fma_f32 v28, v28, v226, -v160
	v_fma_f32 v16, v16, v226, v161
	v_mul_f32_e32 v162, v17, v229
	v_mul_f32_e32 v163, v29, v229
	v_fma_f32 v29, v29, v228, -v162
	v_fma_f32 v17, v17, v228, v163
	v_mul_f32_e32 v160, v18, v231
	v_mul_f32_e32 v161, v30, v231
	v_fma_f32 v30, v30, v230, -v160
	v_fma_f32 v18, v18, v230, v161
	v_mul_f32_e32 v162, v19, v233
	v_mul_f32_e32 v163, v31, v233
	v_fma_f32 v31, v31, v232, -v162
	v_fma_f32 v19, v19, v232, v163
	v_mul_f32_e32 v160, v20, v143
	v_mul_f32_e32 v161, v24, v143
	v_fma_f32 v24, v24, v142, -v160
	v_fma_f32 v20, v20, v142, v161
	v_mul_f32_e32 v162, v21, v145
	v_mul_f32_e32 v163, v25, v145
	v_fma_f32 v25, v25, v144, -v162
	v_fma_f32 v21, v21, v144, v163
	v_mul_f32_e32 v160, v22, v147
	v_mul_f32_e32 v161, v26, v147
	v_fma_f32 v26, v26, v146, -v160
	v_fma_f32 v22, v22, v146, v161
	v_mul_f32_e32 v162, v23, v149
	v_mul_f32_e32 v163, v27, v149
	v_fma_f32 v27, v27, v148, -v162
	v_fma_f32 v23, v23, v148, v163
	v_mul_f32_e32 v160, v0, v235
	v_mul_f32_e32 v161, v12, v235
	v_fma_f32 v12, v12, v234, -v160
	v_fma_f32 v0, v0, v234, v161
	v_mul_f32_e32 v162, v1, v237
	v_mul_f32_e32 v163, v13, v237
	v_fma_f32 v13, v13, v236, -v162
	v_fma_f32 v1, v1, v236, v163
	v_mul_f32_e32 v160, v2, v239
	v_mul_f32_e32 v161, v14, v239
	v_fma_f32 v14, v14, v238, -v160
	v_fma_f32 v2, v2, v238, v161
	v_mul_f32_e32 v162, v3, v241
	v_mul_f32_e32 v163, v15, v241
	v_fma_f32 v15, v15, v240, -v162
	v_fma_f32 v3, v3, v240, v163
	v_mul_f32_e32 v160, v4, v151
	v_mul_f32_e32 v161, v8, v151
	v_fma_f32 v8, v8, v150, -v160
	v_fma_f32 v4, v4, v150, v161
	v_mul_f32_e32 v162, v5, v153
	v_mul_f32_e32 v163, v9, v153
	v_fma_f32 v9, v9, v152, -v162
	v_fma_f32 v5, v5, v152, v163
	v_mul_f32_e32 v160, v6, v155
	v_mul_f32_e32 v161, v10, v155
	v_fma_f32 v10, v10, v154, -v160
	v_fma_f32 v6, v6, v154, v161
	v_mul_f32_e32 v162, v7, v157
	v_mul_f32_e32 v163, v11, v157
	v_fma_f32 v11, v11, v156, -v162
	v_fma_f32 v7, v7, v156, v163
	v_add_u32_e32 v158, 294912, v131
	v_cvt_pk_bf16_f32 v28, v28, v29
	v_cvt_pk_bf16_f32 v29, v30, v31
	v_cvt_pk_bf16_f32 v16, v16, v17
	v_cvt_pk_bf16_f32 v17, v18, v19
	v_cvt_pk_bf16_f32 v24, v24, v25
	v_cvt_pk_bf16_f32 v25, v26, v27
	v_cvt_pk_bf16_f32 v20, v20, v21
	v_cvt_pk_bf16_f32 v21, v22, v23
	global_store_dwordx2 v158, v[28:29], s[24:25]
	global_store_dwordx2 v158, v[16:17], s[24:25] offset:32
	global_store_dwordx2 v158, v[24:25], s[24:25] offset:64
	global_store_dwordx2 v158, v[20:21], s[24:25] offset:96
	v_add_u32_e32 v158, 344064, v131
	v_cvt_pk_bf16_f32 v12, v12, v13
	v_cvt_pk_bf16_f32 v13, v14, v15
	v_cvt_pk_bf16_f32 v0, v0, v1
	v_cvt_pk_bf16_f32 v1, v2, v3
	v_cvt_pk_bf16_f32 v8, v8, v9
	v_cvt_pk_bf16_f32 v9, v10, v11
	v_cvt_pk_bf16_f32 v4, v4, v5
	v_cvt_pk_bf16_f32 v5, v6, v7
	global_store_dwordx2 v158, v[12:13], s[24:25]
	global_store_dwordx2 v158, v[0:1], s[24:25] offset:32
	global_store_dwordx2 v158, v[8:9], s[24:25] offset:64
	global_store_dwordx2 v158, v[4:5], s[24:25] offset:96
	s_branch .Lq_epi_done
.Lq_norope:
	s_waitcnt lgkmcnt(0)
	v_mul_f32_e32 v112, v112, v134
	v_mul_f32_e32 v113, v113, v134
	v_mul_f32_e32 v114, v114, v134
	v_mul_f32_e32 v115, v115, v134
	v_mul_f32_e32 v116, v116, v134
	v_mul_f32_e32 v117, v117, v134
	v_mul_f32_e32 v118, v118, v134
	v_mul_f32_e32 v119, v119, v134
	v_mul_f32_e32 v124, v124, v134
	v_mul_f32_e32 v125, v125, v134
	v_mul_f32_e32 v126, v126, v134
	v_mul_f32_e32 v127, v127, v134
	v_mul_f32_e32 v120, v120, v134
	v_mul_f32_e32 v121, v121, v134
	v_mul_f32_e32 v122, v122, v134
	v_mul_f32_e32 v123, v123, v134
	v_mov_b32_e32 v158, v131
	v_cvt_pk_bf16_f32 v112, v112, v113
	v_cvt_pk_bf16_f32 v113, v114, v115
	v_cvt_pk_bf16_f32 v116, v116, v117
	v_cvt_pk_bf16_f32 v117, v118, v119
	v_cvt_pk_bf16_f32 v124, v124, v125
	v_cvt_pk_bf16_f32 v125, v126, v127
	v_cvt_pk_bf16_f32 v120, v120, v121
	v_cvt_pk_bf16_f32 v121, v122, v123
	global_store_dwordx2 v158, v[112:113], s[24:25]
	global_store_dwordx2 v158, v[116:117], s[24:25] offset:32
	global_store_dwordx2 v158, v[124:125], s[24:25] offset:64
	global_store_dwordx2 v158, v[120:121], s[24:25] offset:96
	v_mul_f32_e32 v108, v108, v135
	v_mul_f32_e32 v109, v109, v135
	v_mul_f32_e32 v110, v110, v135
	v_mul_f32_e32 v111, v111, v135
	v_mul_f32_e32 v96, v96, v135
	v_mul_f32_e32 v97, v97, v135
	v_mul_f32_e32 v98, v98, v135
	v_mul_f32_e32 v99, v99, v135
	v_mul_f32_e32 v104, v104, v135
	v_mul_f32_e32 v105, v105, v135
	v_mul_f32_e32 v106, v106, v135
	v_mul_f32_e32 v107, v107, v135
	v_mul_f32_e32 v100, v100, v135
	v_mul_f32_e32 v101, v101, v135
	v_mul_f32_e32 v102, v102, v135
	v_mul_f32_e32 v103, v103, v135
	v_add_u32_e32 v158, 49152, v131
	v_cvt_pk_bf16_f32 v108, v108, v109
	v_cvt_pk_bf16_f32 v109, v110, v111
	v_cvt_pk_bf16_f32 v96, v96, v97
	v_cvt_pk_bf16_f32 v97, v98, v99
	v_cvt_pk_bf16_f32 v104, v104, v105
	v_cvt_pk_bf16_f32 v105, v106, v107
	v_cvt_pk_bf16_f32 v100, v100, v101
	v_cvt_pk_bf16_f32 v101, v102, v103
	global_store_dwordx2 v158, v[108:109], s[24:25]
	global_store_dwordx2 v158, v[96:97], s[24:25] offset:32
	global_store_dwordx2 v158, v[104:105], s[24:25] offset:64
	global_store_dwordx2 v158, v[100:101], s[24:25] offset:96
	v_mul_f32_e32 v92, v92, v136
	v_mul_f32_e32 v93, v93, v136
	v_mul_f32_e32 v94, v94, v136
	v_mul_f32_e32 v95, v95, v136
	v_mul_f32_e32 v80, v80, v136
	v_mul_f32_e32 v81, v81, v136
	v_mul_f32_e32 v82, v82, v136
	v_mul_f32_e32 v83, v83, v136
	v_mul_f32_e32 v88, v88, v136
	v_mul_f32_e32 v89, v89, v136
	v_mul_f32_e32 v90, v90, v136
	v_mul_f32_e32 v91, v91, v136
	v_mul_f32_e32 v84, v84, v136
	v_mul_f32_e32 v85, v85, v136
	v_mul_f32_e32 v86, v86, v136
	v_mul_f32_e32 v87, v87, v136
	v_add_u32_e32 v158, 98304, v131
	v_cvt_pk_bf16_f32 v92, v92, v93
	v_cvt_pk_bf16_f32 v93, v94, v95
	v_cvt_pk_bf16_f32 v80, v80, v81
	v_cvt_pk_bf16_f32 v81, v82, v83
	v_cvt_pk_bf16_f32 v88, v88, v89
	v_cvt_pk_bf16_f32 v89, v90, v91
	v_cvt_pk_bf16_f32 v84, v84, v85
	v_cvt_pk_bf16_f32 v85, v86, v87
	global_store_dwordx2 v158, v[92:93], s[24:25]
	global_store_dwordx2 v158, v[80:81], s[24:25] offset:32
	global_store_dwordx2 v158, v[88:89], s[24:25] offset:64
	global_store_dwordx2 v158, v[84:85], s[24:25] offset:96
	v_mul_f32_e32 v76, v76, v137
	v_mul_f32_e32 v77, v77, v137
	v_mul_f32_e32 v78, v78, v137
	v_mul_f32_e32 v79, v79, v137
	v_mul_f32_e32 v64, v64, v137
	v_mul_f32_e32 v65, v65, v137
	v_mul_f32_e32 v66, v66, v137
	v_mul_f32_e32 v67, v67, v137
	v_mul_f32_e32 v72, v72, v137
	v_mul_f32_e32 v73, v73, v137
	v_mul_f32_e32 v74, v74, v137
	v_mul_f32_e32 v75, v75, v137
	v_mul_f32_e32 v68, v68, v137
	v_mul_f32_e32 v69, v69, v137
	v_mul_f32_e32 v70, v70, v137
	v_mul_f32_e32 v71, v71, v137
	v_add_u32_e32 v158, 147456, v131
	v_cvt_pk_bf16_f32 v76, v76, v77
	v_cvt_pk_bf16_f32 v77, v78, v79
	v_cvt_pk_bf16_f32 v64, v64, v65
	v_cvt_pk_bf16_f32 v65, v66, v67
	v_cvt_pk_bf16_f32 v72, v72, v73
	v_cvt_pk_bf16_f32 v73, v74, v75
	v_cvt_pk_bf16_f32 v68, v68, v69
	v_cvt_pk_bf16_f32 v69, v70, v71
	global_store_dwordx2 v158, v[76:77], s[24:25]
	global_store_dwordx2 v158, v[64:65], s[24:25] offset:32
	global_store_dwordx2 v158, v[72:73], s[24:25] offset:64
	global_store_dwordx2 v158, v[68:69], s[24:25] offset:96
	v_mul_f32_e32 v60, v60, v138
	v_mul_f32_e32 v61, v61, v138
	v_mul_f32_e32 v62, v62, v138
	v_mul_f32_e32 v63, v63, v138
	v_mul_f32_e32 v48, v48, v138
	v_mul_f32_e32 v49, v49, v138
	v_mul_f32_e32 v50, v50, v138
	v_mul_f32_e32 v51, v51, v138
	v_mul_f32_e32 v56, v56, v138
	v_mul_f32_e32 v57, v57, v138
	v_mul_f32_e32 v58, v58, v138
	v_mul_f32_e32 v59, v59, v138
	v_mul_f32_e32 v52, v52, v138
	v_mul_f32_e32 v53, v53, v138
	v_mul_f32_e32 v54, v54, v138
	v_mul_f32_e32 v55, v55, v138
	v_add_u32_e32 v158, 196608, v131
	v_cvt_pk_bf16_f32 v60, v60, v61
	v_cvt_pk_bf16_f32 v61, v62, v63
	v_cvt_pk_bf16_f32 v48, v48, v49
	v_cvt_pk_bf16_f32 v49, v50, v51
	v_cvt_pk_bf16_f32 v56, v56, v57
	v_cvt_pk_bf16_f32 v57, v58, v59
	v_cvt_pk_bf16_f32 v52, v52, v53
	v_cvt_pk_bf16_f32 v53, v54, v55
	global_store_dwordx2 v158, v[60:61], s[24:25]
	global_store_dwordx2 v158, v[48:49], s[24:25] offset:32
	global_store_dwordx2 v158, v[56:57], s[24:25] offset:64
	global_store_dwordx2 v158, v[52:53], s[24:25] offset:96
	v_mul_f32_e32 v44, v44, v139
	v_mul_f32_e32 v45, v45, v139
	v_mul_f32_e32 v46, v46, v139
	v_mul_f32_e32 v47, v47, v139
	v_mul_f32_e32 v32, v32, v139
	v_mul_f32_e32 v33, v33, v139
	v_mul_f32_e32 v34, v34, v139
	v_mul_f32_e32 v35, v35, v139
	v_mul_f32_e32 v40, v40, v139
	v_mul_f32_e32 v41, v41, v139
	v_mul_f32_e32 v42, v42, v139
	v_mul_f32_e32 v43, v43, v139
	v_mul_f32_e32 v36, v36, v139
	v_mul_f32_e32 v37, v37, v139
	v_mul_f32_e32 v38, v38, v139
	v_mul_f32_e32 v39, v39, v139
	v_add_u32_e32 v158, 245760, v131
	v_cvt_pk_bf16_f32 v44, v44, v45
	v_cvt_pk_bf16_f32 v45, v46, v47
	v_cvt_pk_bf16_f32 v32, v32, v33
	v_cvt_pk_bf16_f32 v33, v34, v35
	v_cvt_pk_bf16_f32 v40, v40, v41
	v_cvt_pk_bf16_f32 v41, v42, v43
	v_cvt_pk_bf16_f32 v36, v36, v37
	v_cvt_pk_bf16_f32 v37, v38, v39
	global_store_dwordx2 v158, v[44:45], s[24:25]
	global_store_dwordx2 v158, v[32:33], s[24:25] offset:32
	global_store_dwordx2 v158, v[40:41], s[24:25] offset:64
	global_store_dwordx2 v158, v[36:37], s[24:25] offset:96
	v_mul_f32_e32 v28, v28, v140
	v_mul_f32_e32 v29, v29, v140
	v_mul_f32_e32 v30, v30, v140
	v_mul_f32_e32 v31, v31, v140
	v_mul_f32_e32 v16, v16, v140
	v_mul_f32_e32 v17, v17, v140
	v_mul_f32_e32 v18, v18, v140
	v_mul_f32_e32 v19, v19, v140
	v_mul_f32_e32 v24, v24, v140
	v_mul_f32_e32 v25, v25, v140
	v_mul_f32_e32 v26, v26, v140
	v_mul_f32_e32 v27, v27, v140
	v_mul_f32_e32 v20, v20, v140
	v_mul_f32_e32 v21, v21, v140
	v_mul_f32_e32 v22, v22, v140
	v_mul_f32_e32 v23, v23, v140
	v_add_u32_e32 v158, 294912, v131
	v_cvt_pk_bf16_f32 v28, v28, v29
	v_cvt_pk_bf16_f32 v29, v30, v31
	v_cvt_pk_bf16_f32 v16, v16, v17
	v_cvt_pk_bf16_f32 v17, v18, v19
	v_cvt_pk_bf16_f32 v24, v24, v25
	v_cvt_pk_bf16_f32 v25, v26, v27
	v_cvt_pk_bf16_f32 v20, v20, v21
	v_cvt_pk_bf16_f32 v21, v22, v23
	global_store_dwordx2 v158, v[28:29], s[24:25]
	global_store_dwordx2 v158, v[16:17], s[24:25] offset:32
	global_store_dwordx2 v158, v[24:25], s[24:25] offset:64
	global_store_dwordx2 v158, v[20:21], s[24:25] offset:96
	v_mul_f32_e32 v12, v12, v141
	v_mul_f32_e32 v13, v13, v141
	v_mul_f32_e32 v14, v14, v141
	v_mul_f32_e32 v15, v15, v141
	v_mul_f32_e32 v0, v0, v141
	v_mul_f32_e32 v1, v1, v141
	v_mul_f32_e32 v2, v2, v141
	v_mul_f32_e32 v3, v3, v141
	v_mul_f32_e32 v8, v8, v141
	v_mul_f32_e32 v9, v9, v141
	v_mul_f32_e32 v10, v10, v141
	v_mul_f32_e32 v11, v11, v141
	v_mul_f32_e32 v4, v4, v141
	v_mul_f32_e32 v5, v5, v141
	v_mul_f32_e32 v6, v6, v141
	v_mul_f32_e32 v7, v7, v141
	v_add_u32_e32 v158, 344064, v131
	v_cvt_pk_bf16_f32 v12, v12, v13
	v_cvt_pk_bf16_f32 v13, v14, v15
	v_cvt_pk_bf16_f32 v0, v0, v1
	v_cvt_pk_bf16_f32 v1, v2, v3
	v_cvt_pk_bf16_f32 v8, v8, v9
	v_cvt_pk_bf16_f32 v9, v10, v11
	v_cvt_pk_bf16_f32 v4, v4, v5
	v_cvt_pk_bf16_f32 v5, v6, v7
	global_store_dwordx2 v158, v[12:13], s[24:25]
	global_store_dwordx2 v158, v[0:1], s[24:25] offset:32
	global_store_dwordx2 v158, v[8:9], s[24:25] offset:64
	global_store_dwordx2 v158, v[4:5], s[24:25] offset:96
.Lq_epi_done:
	s_mov_b64 s[0:1], 0
	s_barrier
.LBB0_906:
	s_and_b64 vcc, exec, s[0:1]
	s_cbranch_vccz .LBB0_803
	v_and_b32_e32 v2, 64, v192
	v_add_u32_e32 v2, 64, v2
	v_xor_b32_e32 v3, 32, v192
	v_cmp_lt_i32_e32 vcc, v3, v2
	v_mov_b32_e32 v128, v167
	s_ashr_i32 s8, s20, 3
	v_cndmask_b32_e32 v3, v192, v3, vcc
	v_lshlrev_b32_e32 v33, 2, v3
	v_xor_b32_e32 v3, 16, v192
	v_cmp_lt_i32_e32 vcc, v3, v2
	s_lshl_b32 s9, s8, 8
	v_and_b32_e32 v0, 63, v128
	v_cndmask_b32_e32 v3, v192, v3, vcc
	v_lshlrev_b32_e32 v34, 2, v3
	v_xor_b32_e32 v3, 8, v192
	v_cmp_lt_i32_e32 vcc, v3, v2
	v_ashrrev_i32_e32 v1, 6, v128
	v_readlane_b32 s1, v254, 47
	v_cndmask_b32_e32 v3, v192, v3, vcc
	v_lshlrev_b32_e32 v35, 2, v3
	v_xor_b32_e32 v3, 4, v192
	v_cmp_lt_i32_e32 vcc, v3, v2
	v_lshlrev_b32_e32 v164, 3, v0
	v_lshl_add_u32 v32, v1, 5, s9
	v_cndmask_b32_e32 v3, v192, v3, vcc
	v_lshlrev_b32_e32 v36, 2, v3
	v_xor_b32_e32 v3, 2, v192
	v_cmp_lt_i32_e32 vcc, v3, v2
	s_mov_b32 s0, 0
	v_cmp_eq_u32_e64 s[10:11], 0, v0
	v_cndmask_b32_e32 v3, v192, v3, vcc
	v_lshlrev_b32_e32 v37, 2, v3
	v_xor_b32_e32 v3, 1, v192
	v_cmp_lt_i32_e32 vcc, v3, v2
	v_lshl_add_u32 v39, v1, 7, s1
	v_lshl_add_u64 v[0:1], s[22:23], 0, v[164:165]
	v_cndmask_b32_e32 v2, v192, v3, vcc
	v_lshlrev_b32_e32 v38, 2, v2
	s_mov_b64 s[2:3], -1
	v_readfirstlane_b32 s0, v167
	v_and_b32_e32 v116, 63, v167
	v_and_b32_e32 v118, 15, v167
	s_lshr_b32 s0, s0, 6
	s_lshl_b32 s1, s0, 5
	s_add_u32 s2, s9, s1
	s_mul_i32 s2, s2, 0x1700
	s_add_u32 s2, s2, 0x400
	s_add_u32 s24, s22, s2
	s_addc_u32 s25, s23, 0
	v_lshlrev_b32_e32 v116, 3, v116
	v_and_b32_e32 v117, 48, v167
	s_lshl_b32 s1, s0, 7
	v_add_u32_e32 v117, s1, v117
	v_add_u32_e32 v117, 0x20000, v117
	global_load_dwordx2 v[16:17], v116, s[24:25]
	s_add_u32 s24, s24, 0x1700
	s_addc_u32 s25, s25, 0
	global_load_dwordx2 v[18:19], v116, s[24:25]
	s_add_u32 s24, s24, 0x1700
	s_addc_u32 s25, s25, 0
	global_load_dwordx2 v[20:21], v116, s[24:25]
	s_add_u32 s24, s24, 0x1700
	s_addc_u32 s25, s25, 0
	global_load_dwordx2 v[22:23], v116, s[24:25]
	s_add_u32 s24, s24, 0x1700
	s_addc_u32 s25, s25, 0
	global_load_dwordx2 v[24:25], v116, s[24:25]
	s_add_u32 s24, s24, 0x1700
	s_addc_u32 s25, s25, 0
	global_load_dwordx2 v[26:27], v116, s[24:25]
	s_add_u32 s24, s24, 0x1700
	s_addc_u32 s25, s25, 0
	global_load_dwordx2 v[28:29], v116, s[24:25]
	s_add_u32 s24, s24, 0x1700
	s_addc_u32 s25, s25, 0
	global_load_dwordx2 v[30:31], v116, s[24:25]
	s_add_u32 s24, s24, 0x1700
	s_addc_u32 s25, s25, 0
	global_load_dwordx2 v[32:33], v116, s[24:25]
	s_add_u32 s24, s24, 0x1700
	s_addc_u32 s25, s25, 0
	global_load_dwordx2 v[34:35], v116, s[24:25]
	s_add_u32 s24, s24, 0x1700
	s_addc_u32 s25, s25, 0
	global_load_dwordx2 v[36:37], v116, s[24:25]
	s_add_u32 s24, s24, 0x1700
	s_addc_u32 s25, s25, 0
	global_load_dwordx2 v[38:39], v116, s[24:25]
	s_add_u32 s24, s24, 0x1700
	s_addc_u32 s25, s25, 0
	global_load_dwordx2 v[40:41], v116, s[24:25]
	s_add_u32 s24, s24, 0x1700
	s_addc_u32 s25, s25, 0
	global_load_dwordx2 v[42:43], v116, s[24:25]
	s_add_u32 s24, s24, 0x1700
	s_addc_u32 s25, s25, 0
	global_load_dwordx2 v[44:45], v116, s[24:25]
	s_add_u32 s24, s24, 0x1700
	s_addc_u32 s25, s25, 0
	global_load_dwordx2 v[46:47], v116, s[24:25]
	s_add_u32 s24, s24, 0x1700
	s_addc_u32 s25, s25, 0
	s_waitcnt vmcnt(15)
	v_lshlrev_b32_e32 v112, 16, v16
	v_and_b32_e32 v16, 0xffff0000, v16
	v_mul_f32_e32 v16, v16, v16
	v_lshlrev_b32_e32 v113, 16, v17
	v_fmac_f32_e32 v16, v112, v112
	v_and_b32_e32 v17, 0xffff0000, v17
	v_fmac_f32_e32 v16, v113, v113
	v_fmac_f32_e32 v16, v17, v17
	s_waitcnt vmcnt(14)
	v_lshlrev_b32_e32 v112, 16, v18
	v_and_b32_e32 v18, 0xffff0000, v18
	v_mul_f32_e32 v18, v18, v18
	v_lshlrev_b32_e32 v113, 16, v19
	v_fmac_f32_e32 v18, v112, v112
	v_and_b32_e32 v19, 0xffff0000, v19
	v_fmac_f32_e32 v18, v113, v113
	v_fmac_f32_e32 v18, v19, v19
	s_waitcnt vmcnt(13)
	v_lshlrev_b32_e32 v112, 16, v20
	v_and_b32_e32 v20, 0xffff0000, v20
	v_mul_f32_e32 v20, v20, v20
	v_lshlrev_b32_e32 v113, 16, v21
	v_fmac_f32_e32 v20, v112, v112
	v_and_b32_e32 v21, 0xffff0000, v21
	v_fmac_f32_e32 v20, v113, v113
	v_fmac_f32_e32 v20, v21, v21
	s_waitcnt vmcnt(12)
	v_lshlrev_b32_e32 v112, 16, v22
	v_and_b32_e32 v22, 0xffff0000, v22
	v_mul_f32_e32 v22, v22, v22
	v_lshlrev_b32_e32 v113, 16, v23
	v_fmac_f32_e32 v22, v112, v112
	v_and_b32_e32 v23, 0xffff0000, v23
	v_fmac_f32_e32 v22, v113, v113
	v_fmac_f32_e32 v22, v23, v23
	s_waitcnt vmcnt(11)
	v_lshlrev_b32_e32 v112, 16, v24
	v_and_b32_e32 v24, 0xffff0000, v24
	v_mul_f32_e32 v24, v24, v24
	v_lshlrev_b32_e32 v113, 16, v25
	v_fmac_f32_e32 v24, v112, v112
	v_and_b32_e32 v25, 0xffff0000, v25
	v_fmac_f32_e32 v24, v113, v113
	v_fmac_f32_e32 v24, v25, v25
	s_waitcnt vmcnt(10)
	v_lshlrev_b32_e32 v112, 16, v26
	v_and_b32_e32 v26, 0xffff0000, v26
	v_mul_f32_e32 v26, v26, v26
	v_lshlrev_b32_e32 v113, 16, v27
	v_fmac_f32_e32 v26, v112, v112
	v_and_b32_e32 v27, 0xffff0000, v27
	v_fmac_f32_e32 v26, v113, v113
	v_fmac_f32_e32 v26, v27, v27
	s_waitcnt vmcnt(9)
	v_lshlrev_b32_e32 v112, 16, v28
	v_and_b32_e32 v28, 0xffff0000, v28
	v_mul_f32_e32 v28, v28, v28
	v_lshlrev_b32_e32 v113, 16, v29
	v_fmac_f32_e32 v28, v112, v112
	v_and_b32_e32 v29, 0xffff0000, v29
	v_fmac_f32_e32 v28, v113, v113
	v_fmac_f32_e32 v28, v29, v29
	s_waitcnt vmcnt(8)
	v_lshlrev_b32_e32 v112, 16, v30
	v_and_b32_e32 v30, 0xffff0000, v30
	v_mul_f32_e32 v30, v30, v30
	v_lshlrev_b32_e32 v113, 16, v31
	v_fmac_f32_e32 v30, v112, v112
	v_and_b32_e32 v31, 0xffff0000, v31
	v_fmac_f32_e32 v30, v113, v113
	v_fmac_f32_e32 v30, v31, v31
	s_waitcnt vmcnt(7)
	v_lshlrev_b32_e32 v112, 16, v32
	v_and_b32_e32 v32, 0xffff0000, v32
	v_mul_f32_e32 v32, v32, v32
	v_lshlrev_b32_e32 v113, 16, v33
	v_fmac_f32_e32 v32, v112, v112
	v_and_b32_e32 v33, 0xffff0000, v33
	v_fmac_f32_e32 v32, v113, v113
	v_fmac_f32_e32 v32, v33, v33
	s_waitcnt vmcnt(6)
	v_lshlrev_b32_e32 v112, 16, v34
	v_and_b32_e32 v34, 0xffff0000, v34
	v_mul_f32_e32 v34, v34, v34
	v_lshlrev_b32_e32 v113, 16, v35
	v_fmac_f32_e32 v34, v112, v112
	v_and_b32_e32 v35, 0xffff0000, v35
	v_fmac_f32_e32 v34, v113, v113
	v_fmac_f32_e32 v34, v35, v35
	s_waitcnt vmcnt(5)
	v_lshlrev_b32_e32 v112, 16, v36
	v_and_b32_e32 v36, 0xffff0000, v36
	v_mul_f32_e32 v36, v36, v36
	v_lshlrev_b32_e32 v113, 16, v37
	v_fmac_f32_e32 v36, v112, v112
	v_and_b32_e32 v37, 0xffff0000, v37
	v_fmac_f32_e32 v36, v113, v113
	v_fmac_f32_e32 v36, v37, v37
	s_waitcnt vmcnt(4)
	v_lshlrev_b32_e32 v112, 16, v38
	v_and_b32_e32 v38, 0xffff0000, v38
	v_mul_f32_e32 v38, v38, v38
	v_lshlrev_b32_e32 v113, 16, v39
	v_fmac_f32_e32 v38, v112, v112
	v_and_b32_e32 v39, 0xffff0000, v39
	v_fmac_f32_e32 v38, v113, v113
	v_fmac_f32_e32 v38, v39, v39
	s_waitcnt vmcnt(3)
	v_lshlrev_b32_e32 v112, 16, v40
	v_and_b32_e32 v40, 0xffff0000, v40
	v_mul_f32_e32 v40, v40, v40
	v_lshlrev_b32_e32 v113, 16, v41
	v_fmac_f32_e32 v40, v112, v112
	v_and_b32_e32 v41, 0xffff0000, v41
	v_fmac_f32_e32 v40, v113, v113
	v_fmac_f32_e32 v40, v41, v41
	s_waitcnt vmcnt(2)
	v_lshlrev_b32_e32 v112, 16, v42
	v_and_b32_e32 v42, 0xffff0000, v42
	v_mul_f32_e32 v42, v42, v42
	v_lshlrev_b32_e32 v113, 16, v43
	v_fmac_f32_e32 v42, v112, v112
	v_and_b32_e32 v43, 0xffff0000, v43
	v_fmac_f32_e32 v42, v113, v113
	v_fmac_f32_e32 v42, v43, v43
	s_waitcnt vmcnt(1)
	v_lshlrev_b32_e32 v112, 16, v44
	v_and_b32_e32 v44, 0xffff0000, v44
	v_mul_f32_e32 v44, v44, v44
	v_lshlrev_b32_e32 v113, 16, v45
	v_fmac_f32_e32 v44, v112, v112
	v_and_b32_e32 v45, 0xffff0000, v45
	v_fmac_f32_e32 v44, v113, v113
	v_fmac_f32_e32 v44, v45, v45
	s_waitcnt vmcnt(0)
	v_lshlrev_b32_e32 v112, 16, v46
	v_and_b32_e32 v46, 0xffff0000, v46
	v_mul_f32_e32 v46, v46, v46
	v_lshlrev_b32_e32 v113, 16, v47
	v_fmac_f32_e32 v46, v112, v112
	v_and_b32_e32 v47, 0xffff0000, v47
	v_fmac_f32_e32 v46, v113, v113
	v_fmac_f32_e32 v46, v47, v47
	s_nop 1
	v_permlane32_swap_b32_e32 v16, v32
	v_permlane32_swap_b32_e32 v18, v34
	v_permlane32_swap_b32_e32 v20, v36
	v_permlane32_swap_b32_e32 v22, v38
	v_permlane32_swap_b32_e32 v24, v40
	v_permlane32_swap_b32_e32 v26, v42
	v_permlane32_swap_b32_e32 v28, v44
	v_permlane32_swap_b32_e32 v30, v46
	s_nop 0
	v_add_f32_e32 v16, v16, v32
	v_add_f32_e32 v18, v18, v34
	v_add_f32_e32 v20, v20, v36
	v_add_f32_e32 v22, v22, v38
	v_add_f32_e32 v24, v24, v40
	v_add_f32_e32 v26, v26, v42
	v_add_f32_e32 v28, v28, v44
	v_add_f32_e32 v30, v30, v46
	s_nop 1
	v_permlane16_swap_b32_e32 v16, v24
	v_permlane16_swap_b32_e32 v18, v26
	v_permlane16_swap_b32_e32 v20, v28
	v_permlane16_swap_b32_e32 v22, v30
	s_nop 0
	v_add_f32_e32 v16, v16, v24
	v_add_f32_e32 v18, v18, v26
	v_add_f32_e32 v20, v20, v28
	v_add_f32_e32 v22, v22, v30
	s_nop 1
	v_add_f32_dpp v16, v16, v16 row_ror:8 row_mask:0xf bank_mask:0xf
	v_add_f32_dpp v18, v18, v18 row_ror:8 row_mask:0xf bank_mask:0xf
	v_add_f32_dpp v20, v20, v20 row_ror:8 row_mask:0xf bank_mask:0xf
	v_add_f32_dpp v22, v22, v22 row_ror:8 row_mask:0xf bank_mask:0xf
	s_nop 1
	v_add_f32_dpp v16, v16, v16 row_ror:4 row_mask:0xf bank_mask:0xf
	v_add_f32_dpp v18, v18, v18 row_ror:4 row_mask:0xf bank_mask:0xf
	v_add_f32_dpp v20, v20, v20 row_ror:4 row_mask:0xf bank_mask:0xf
	v_add_f32_dpp v22, v22, v22 row_ror:4 row_mask:0xf bank_mask:0xf
	s_nop 1
	v_add_f32_dpp v16, v16, v16 row_ror:2 row_mask:0xf bank_mask:0xf
	v_add_f32_dpp v18, v18, v18 row_ror:2 row_mask:0xf bank_mask:0xf
	v_add_f32_dpp v20, v20, v20 row_ror:2 row_mask:0xf bank_mask:0xf
	v_add_f32_dpp v22, v22, v22 row_ror:2 row_mask:0xf bank_mask:0xf
	s_nop 1
	v_add_f32_dpp v16, v16, v16 row_ror:1 row_mask:0xf bank_mask:0xf
	v_add_f32_dpp v18, v18, v18 row_ror:1 row_mask:0xf bank_mask:0xf
	v_add_f32_dpp v20, v20, v20 row_ror:1 row_mask:0xf bank_mask:0xf
	v_add_f32_dpp v22, v22, v22 row_ror:1 row_mask:0xf bank_mask:0xf
	v_fmamk_f32 v16, v16, 0x3b800000, v166
	v_fmamk_f32 v18, v18, 0x3b800000, v166
	v_fmamk_f32 v20, v20, 0x3b800000, v166
	v_fmamk_f32 v22, v22, 0x3b800000, v166
	v_mul_f32_e32 v112, 0x4b800000, v16
	v_cmp_gt_f32_e32 vcc, s58, v16
	s_nop 1
	v_cndmask_b32_e32 v16, v16, v112, vcc
	v_rsq_f32_e32 v16, v16
	s_nop 0
	v_mul_f32_e32 v112, 0x45800000, v16
	v_cndmask_b32_e32 v16, v16, v112, vcc
	v_mul_f32_e32 v112, 0x4b800000, v18
	v_cmp_gt_f32_e32 vcc, s58, v18
	s_nop 1
	v_cndmask_b32_e32 v18, v18, v112, vcc
	v_rsq_f32_e32 v18, v18
	s_nop 0
	v_mul_f32_e32 v112, 0x45800000, v18
	v_cndmask_b32_e32 v18, v18, v112, vcc
	v_mul_f32_e32 v112, 0x4b800000, v20
	v_cmp_gt_f32_e32 vcc, s58, v20
	s_nop 1
	v_cndmask_b32_e32 v20, v20, v112, vcc
	v_rsq_f32_e32 v20, v20
	s_nop 0
	v_mul_f32_e32 v112, 0x45800000, v20
	v_cndmask_b32_e32 v20, v20, v112, vcc
	v_mul_f32_e32 v112, 0x4b800000, v22
	v_cmp_gt_f32_e32 vcc, s58, v22
	s_nop 1
	v_cndmask_b32_e32 v22, v22, v112, vcc
	v_rsq_f32_e32 v22, v22
	s_nop 0
	v_mul_f32_e32 v112, 0x45800000, v22
	v_cndmask_b32_e32 v22, v22, v112, vcc
	v_mov_b32_e32 v112, v16
	v_mov_b32_e32 v113, v18
	v_mov_b32_e32 v114, v20
	v_mov_b32_e32 v115, v22
	v_cmp_eq_u32_e32 vcc, 0, v118
	s_and_saveexec_b64 s[0:1], vcc
	ds_write_b128 v117, v[112:115]
	s_or_b64 exec, exec, s[0:1]
	global_load_dwordx2 v[16:17], v116, s[24:25]
	s_add_u32 s24, s24, 0x1700
	s_addc_u32 s25, s25, 0
	global_load_dwordx2 v[18:19], v116, s[24:25]
	s_add_u32 s24, s24, 0x1700
	s_addc_u32 s25, s25, 0
	global_load_dwordx2 v[20:21], v116, s[24:25]
	s_add_u32 s24, s24, 0x1700
	s_addc_u32 s25, s25, 0
	global_load_dwordx2 v[22:23], v116, s[24:25]
	s_add_u32 s24, s24, 0x1700
	s_addc_u32 s25, s25, 0
	global_load_dwordx2 v[24:25], v116, s[24:25]
	s_add_u32 s24, s24, 0x1700
	s_addc_u32 s25, s25, 0
	global_load_dwordx2 v[26:27], v116, s[24:25]
	s_add_u32 s24, s24, 0x1700
	s_addc_u32 s25, s25, 0
	global_load_dwordx2 v[28:29], v116, s[24:25]
	s_add_u32 s24, s24, 0x1700
	s_addc_u32 s25, s25, 0
	global_load_dwordx2 v[30:31], v116, s[24:25]
	s_add_u32 s24, s24, 0x1700
	s_addc_u32 s25, s25, 0
	global_load_dwordx2 v[32:33], v116, s[24:25]
	s_add_u32 s24, s24, 0x1700
	s_addc_u32 s25, s25, 0
	global_load_dwordx2 v[34:35], v116, s[24:25]
	s_add_u32 s24, s24, 0x1700
	s_addc_u32 s25, s25, 0
	global_load_dwordx2 v[36:37], v116, s[24:25]
	s_add_u32 s24, s24, 0x1700
	s_addc_u32 s25, s25, 0
	global_load_dwordx2 v[38:39], v116, s[24:25]
	s_add_u32 s24, s24, 0x1700
	s_addc_u32 s25, s25, 0
	global_load_dwordx2 v[40:41], v116, s[24:25]
	s_add_u32 s24, s24, 0x1700
	s_addc_u32 s25, s25, 0
	global_load_dwordx2 v[42:43], v116, s[24:25]
	s_add_u32 s24, s24, 0x1700
	s_addc_u32 s25, s25, 0
	global_load_dwordx2 v[44:45], v116, s[24:25]
	s_add_u32 s24, s24, 0x1700
	s_addc_u32 s25, s25, 0
	global_load_dwordx2 v[46:47], v116, s[24:25]
	s_add_u32 s24, s24, 0x1700
	s_addc_u32 s25, s25, 0
	s_waitcnt vmcnt(15)
	v_lshlrev_b32_e32 v112, 16, v16
	v_and_b32_e32 v16, 0xffff0000, v16
	v_mul_f32_e32 v16, v16, v16
	v_lshlrev_b32_e32 v113, 16, v17
	v_fmac_f32_e32 v16, v112, v112
	v_and_b32_e32 v17, 0xffff0000, v17
	v_fmac_f32_e32 v16, v113, v113
	v_fmac_f32_e32 v16, v17, v17
	s_waitcnt vmcnt(14)
	v_lshlrev_b32_e32 v112, 16, v18
	v_and_b32_e32 v18, 0xffff0000, v18
	v_mul_f32_e32 v18, v18, v18
	v_lshlrev_b32_e32 v113, 16, v19
	v_fmac_f32_e32 v18, v112, v112
	v_and_b32_e32 v19, 0xffff0000, v19
	v_fmac_f32_e32 v18, v113, v113
	v_fmac_f32_e32 v18, v19, v19
	s_waitcnt vmcnt(13)
	v_lshlrev_b32_e32 v112, 16, v20
	v_and_b32_e32 v20, 0xffff0000, v20
	v_mul_f32_e32 v20, v20, v20
	v_lshlrev_b32_e32 v113, 16, v21
	v_fmac_f32_e32 v20, v112, v112
	v_and_b32_e32 v21, 0xffff0000, v21
	v_fmac_f32_e32 v20, v113, v113
	v_fmac_f32_e32 v20, v21, v21
	s_waitcnt vmcnt(12)
	v_lshlrev_b32_e32 v112, 16, v22
	v_and_b32_e32 v22, 0xffff0000, v22
	v_mul_f32_e32 v22, v22, v22
	v_lshlrev_b32_e32 v113, 16, v23
	v_fmac_f32_e32 v22, v112, v112
	v_and_b32_e32 v23, 0xffff0000, v23
	v_fmac_f32_e32 v22, v113, v113
	v_fmac_f32_e32 v22, v23, v23
	s_waitcnt vmcnt(11)
	v_lshlrev_b32_e32 v112, 16, v24
	v_and_b32_e32 v24, 0xffff0000, v24
	v_mul_f32_e32 v24, v24, v24
	v_lshlrev_b32_e32 v113, 16, v25
	v_fmac_f32_e32 v24, v112, v112
	v_and_b32_e32 v25, 0xffff0000, v25
	v_fmac_f32_e32 v24, v113, v113
	v_fmac_f32_e32 v24, v25, v25
	s_waitcnt vmcnt(10)
	v_lshlrev_b32_e32 v112, 16, v26
	v_and_b32_e32 v26, 0xffff0000, v26
	v_mul_f32_e32 v26, v26, v26
	v_lshlrev_b32_e32 v113, 16, v27
	v_fmac_f32_e32 v26, v112, v112
	v_and_b32_e32 v27, 0xffff0000, v27
	v_fmac_f32_e32 v26, v113, v113
	v_fmac_f32_e32 v26, v27, v27
	s_waitcnt vmcnt(9)
	v_lshlrev_b32_e32 v112, 16, v28
	v_and_b32_e32 v28, 0xffff0000, v28
	v_mul_f32_e32 v28, v28, v28
	v_lshlrev_b32_e32 v113, 16, v29
	v_fmac_f32_e32 v28, v112, v112
	v_and_b32_e32 v29, 0xffff0000, v29
	v_fmac_f32_e32 v28, v113, v113
	v_fmac_f32_e32 v28, v29, v29
	s_waitcnt vmcnt(8)
	v_lshlrev_b32_e32 v112, 16, v30
	v_and_b32_e32 v30, 0xffff0000, v30
	v_mul_f32_e32 v30, v30, v30
	v_lshlrev_b32_e32 v113, 16, v31
	v_fmac_f32_e32 v30, v112, v112
	v_and_b32_e32 v31, 0xffff0000, v31
	v_fmac_f32_e32 v30, v113, v113
	v_fmac_f32_e32 v30, v31, v31
	s_waitcnt vmcnt(7)
	v_lshlrev_b32_e32 v112, 16, v32
	v_and_b32_e32 v32, 0xffff0000, v32
	v_mul_f32_e32 v32, v32, v32
	v_lshlrev_b32_e32 v113, 16, v33
	v_fmac_f32_e32 v32, v112, v112
	v_and_b32_e32 v33, 0xffff0000, v33
	v_fmac_f32_e32 v32, v113, v113
	v_fmac_f32_e32 v32, v33, v33
	s_waitcnt vmcnt(6)
	v_lshlrev_b32_e32 v112, 16, v34
	v_and_b32_e32 v34, 0xffff0000, v34
	v_mul_f32_e32 v34, v34, v34
	v_lshlrev_b32_e32 v113, 16, v35
	v_fmac_f32_e32 v34, v112, v112
	v_and_b32_e32 v35, 0xffff0000, v35
	v_fmac_f32_e32 v34, v113, v113
	v_fmac_f32_e32 v34, v35, v35
	s_waitcnt vmcnt(5)
	v_lshlrev_b32_e32 v112, 16, v36
	v_and_b32_e32 v36, 0xffff0000, v36
	v_mul_f32_e32 v36, v36, v36
	v_lshlrev_b32_e32 v113, 16, v37
	v_fmac_f32_e32 v36, v112, v112
	v_and_b32_e32 v37, 0xffff0000, v37
	v_fmac_f32_e32 v36, v113, v113
	v_fmac_f32_e32 v36, v37, v37
	s_waitcnt vmcnt(4)
	v_lshlrev_b32_e32 v112, 16, v38
	v_and_b32_e32 v38, 0xffff0000, v38
	v_mul_f32_e32 v38, v38, v38
	v_lshlrev_b32_e32 v113, 16, v39
	v_fmac_f32_e32 v38, v112, v112
	v_and_b32_e32 v39, 0xffff0000, v39
	v_fmac_f32_e32 v38, v113, v113
	v_fmac_f32_e32 v38, v39, v39
	s_waitcnt vmcnt(3)
	v_lshlrev_b32_e32 v112, 16, v40
	v_and_b32_e32 v40, 0xffff0000, v40
	v_mul_f32_e32 v40, v40, v40
	v_lshlrev_b32_e32 v113, 16, v41
	v_fmac_f32_e32 v40, v112, v112
	v_and_b32_e32 v41, 0xffff0000, v41
	v_fmac_f32_e32 v40, v113, v113
	v_fmac_f32_e32 v40, v41, v41
	s_waitcnt vmcnt(2)
	v_lshlrev_b32_e32 v112, 16, v42
	v_and_b32_e32 v42, 0xffff0000, v42
	v_mul_f32_e32 v42, v42, v42
	v_lshlrev_b32_e32 v113, 16, v43
	v_fmac_f32_e32 v42, v112, v112
	v_and_b32_e32 v43, 0xffff0000, v43
	v_fmac_f32_e32 v42, v113, v113
	v_fmac_f32_e32 v42, v43, v43
	s_waitcnt vmcnt(1)
	v_lshlrev_b32_e32 v112, 16, v44
	v_and_b32_e32 v44, 0xffff0000, v44
	v_mul_f32_e32 v44, v44, v44
	v_lshlrev_b32_e32 v113, 16, v45
	v_fmac_f32_e32 v44, v112, v112
	v_and_b32_e32 v45, 0xffff0000, v45
	v_fmac_f32_e32 v44, v113, v113
	v_fmac_f32_e32 v44, v45, v45
	s_waitcnt vmcnt(0)
	v_lshlrev_b32_e32 v112, 16, v46
	v_and_b32_e32 v46, 0xffff0000, v46
	v_mul_f32_e32 v46, v46, v46
	v_lshlrev_b32_e32 v113, 16, v47
	v_fmac_f32_e32 v46, v112, v112
	v_and_b32_e32 v47, 0xffff0000, v47
	v_fmac_f32_e32 v46, v113, v113
	v_fmac_f32_e32 v46, v47, v47
	s_nop 1
	v_permlane32_swap_b32_e32 v16, v32
	v_permlane32_swap_b32_e32 v18, v34
	v_permlane32_swap_b32_e32 v20, v36
	v_permlane32_swap_b32_e32 v22, v38
	v_permlane32_swap_b32_e32 v24, v40
	v_permlane32_swap_b32_e32 v26, v42
	v_permlane32_swap_b32_e32 v28, v44
	v_permlane32_swap_b32_e32 v30, v46
	s_nop 0
	v_add_f32_e32 v16, v16, v32
	v_add_f32_e32 v18, v18, v34
	v_add_f32_e32 v20, v20, v36
	v_add_f32_e32 v22, v22, v38
	v_add_f32_e32 v24, v24, v40
	v_add_f32_e32 v26, v26, v42
	v_add_f32_e32 v28, v28, v44
	v_add_f32_e32 v30, v30, v46
	s_nop 1
	v_permlane16_swap_b32_e32 v16, v24
	v_permlane16_swap_b32_e32 v18, v26
	v_permlane16_swap_b32_e32 v20, v28
	v_permlane16_swap_b32_e32 v22, v30
	s_nop 0
	v_add_f32_e32 v16, v16, v24
	v_add_f32_e32 v18, v18, v26
	v_add_f32_e32 v20, v20, v28
	v_add_f32_e32 v22, v22, v30
	s_nop 1
	v_add_f32_dpp v16, v16, v16 row_ror:8 row_mask:0xf bank_mask:0xf
	v_add_f32_dpp v18, v18, v18 row_ror:8 row_mask:0xf bank_mask:0xf
	v_add_f32_dpp v20, v20, v20 row_ror:8 row_mask:0xf bank_mask:0xf
	v_add_f32_dpp v22, v22, v22 row_ror:8 row_mask:0xf bank_mask:0xf
	s_nop 1
	v_add_f32_dpp v16, v16, v16 row_ror:4 row_mask:0xf bank_mask:0xf
	v_add_f32_dpp v18, v18, v18 row_ror:4 row_mask:0xf bank_mask:0xf
	v_add_f32_dpp v20, v20, v20 row_ror:4 row_mask:0xf bank_mask:0xf
	v_add_f32_dpp v22, v22, v22 row_ror:4 row_mask:0xf bank_mask:0xf
	s_nop 1
	v_add_f32_dpp v16, v16, v16 row_ror:2 row_mask:0xf bank_mask:0xf
	v_add_f32_dpp v18, v18, v18 row_ror:2 row_mask:0xf bank_mask:0xf
	v_add_f32_dpp v20, v20, v20 row_ror:2 row_mask:0xf bank_mask:0xf
	v_add_f32_dpp v22, v22, v22 row_ror:2 row_mask:0xf bank_mask:0xf
	s_nop 1
	v_add_f32_dpp v16, v16, v16 row_ror:1 row_mask:0xf bank_mask:0xf
	v_add_f32_dpp v18, v18, v18 row_ror:1 row_mask:0xf bank_mask:0xf
	v_add_f32_dpp v20, v20, v20 row_ror:1 row_mask:0xf bank_mask:0xf
	v_add_f32_dpp v22, v22, v22 row_ror:1 row_mask:0xf bank_mask:0xf
	v_fmamk_f32 v16, v16, 0x3b800000, v166
	v_fmamk_f32 v18, v18, 0x3b800000, v166
	v_fmamk_f32 v20, v20, 0x3b800000, v166
	v_fmamk_f32 v22, v22, 0x3b800000, v166
	v_mul_f32_e32 v112, 0x4b800000, v16
	v_cmp_gt_f32_e32 vcc, s58, v16
	s_nop 1
	v_cndmask_b32_e32 v16, v16, v112, vcc
	v_rsq_f32_e32 v16, v16
	s_nop 0
	v_mul_f32_e32 v112, 0x45800000, v16
	v_cndmask_b32_e32 v16, v16, v112, vcc
	v_mul_f32_e32 v112, 0x4b800000, v18
	v_cmp_gt_f32_e32 vcc, s58, v18
	s_nop 1
	v_cndmask_b32_e32 v18, v18, v112, vcc
	v_rsq_f32_e32 v18, v18
	s_nop 0
	v_mul_f32_e32 v112, 0x45800000, v18
	v_cndmask_b32_e32 v18, v18, v112, vcc
	v_mul_f32_e32 v112, 0x4b800000, v20
	v_cmp_gt_f32_e32 vcc, s58, v20
	s_nop 1
	v_cndmask_b32_e32 v20, v20, v112, vcc
	v_rsq_f32_e32 v20, v20
	s_nop 0
	v_mul_f32_e32 v112, 0x45800000, v20
	v_cndmask_b32_e32 v20, v20, v112, vcc
	v_mul_f32_e32 v112, 0x4b800000, v22
	v_cmp_gt_f32_e32 vcc, s58, v22
	s_nop 1
	v_cndmask_b32_e32 v22, v22, v112, vcc
	v_rsq_f32_e32 v22, v22
	s_nop 0
	v_mul_f32_e32 v112, 0x45800000, v22
	v_cndmask_b32_e32 v22, v22, v112, vcc
	v_mov_b32_e32 v112, v16
	v_mov_b32_e32 v113, v18
	v_mov_b32_e32 v114, v20
	v_mov_b32_e32 v115, v22
	v_cmp_eq_u32_e32 vcc, 0, v118
	s_and_saveexec_b64 s[0:1], vcc
	ds_write_b128 v117, v[112:115] offset:64
	s_or_b64 exec, exec, s[0:1]
